# group-1 waves run their epilogue before the barrier closing their last MMA segment (barrier moved behind the epilogue for that group) so the two groups' epilogues overlap; all GEMMs but P9
# speedup vs baseline: 1.0125x; 1.0125x over previous
.LBB0_566:
	s_ashr_i32 s9, s8, 31
	v_cmp_lt_i64_e32 vcc, s[10:11], v[144:145]
	s_lshl_b64 s[10:11], s[8:9], 19
	s_add_u32 s10, s40, s10
	s_addc_u32 s11, s41, s11
	s_and_b64 s[12:13], vcc, exec
	s_cselect_b32 s9, s11, s17
	s_cselect_b32 s75, s10, s16
	s_ashr_i32 s7, s6, 31
	s_lshl_b64 s[12:13], s[6:7], 19
	s_add_u32 s12, s48, s12
	s_addc_u32 s13, s49, s13
	s_and_b64 s[18:19], vcc, exec
	s_cselect_b32 s7, s13, s35
	s_cselect_b32 s76, s12, s34
	s_add_u32 s16, s16, 0x40080
	s_addc_u32 s17, s17, 0
	s_add_u32 s77, s34, 0x100
	s_addc_u32 s78, s35, 0
	s_mov_b32 s79, -2
	ds_read_b128 v[154:157], v151
	ds_read_b128 v[158:161], v151 offset:1024
	ds_read_b128 v[162:165], v151 offset:2048
	ds_read_b128 v[166:169], v151 offset:3072
	s_add_u32 s18, s16, 0xfffc0080
	s_addc_u32 s19, s17, -1
	s_cmp_eq_u32 s79, 12
	s_cselect_b32 s19, s9, s19
	s_cselect_b32 s18, s75, s18
	s_cselect_b32 s35, s7, s78
	s_cselect_b32 s34, s76, s77
	v_lshl_add_u64 v[172:173], s[16:17], 0, v[140:141]
	s_add_i32 m0, s53, 0xc000
	ds_read_b128 v[176:179], v152
	ds_read_b128 v[180:183], v152 offset:1024
	ds_read_b128 v[184:187], v152 offset:2048
	ds_read_b128 v[188:191], v152 offset:3072
	ds_read_b128 v[192:195], v152 offset:4096
	ds_read_b128 v[196:199], v152 offset:5120
	ds_read_b128 v[200:203], v152 offset:6144
	ds_read_b128 v[204:207], v152 offset:7168
	global_load_lds_dwordx4 v[172:173], off
	v_lshl_add_u64 v[172:173], s[16:17], 0, v[142:143]
	s_add_i32 m0, s53, 0xe000
	s_nop 0
	global_load_lds_dwordx4 v[172:173], off
	ds_read_b128 v[208:211], v153
	ds_read_b128 v[212:215], v153 offset:1024
	ds_read_b128 v[216:219], v153 offset:2048
	ds_read_b128 v[220:223], v153 offset:3072
	s_waitcnt lgkmcnt(0)
	s_setprio 1
	s_barrier
	v_mfma_f32_16x16x32_bf16 v[126:129], v[154:157], v[176:179], 0
	v_mfma_f32_16x16x32_bf16 v[122:125], v[162:165], v[176:179], 0
	v_mfma_f32_16x16x32_bf16 v[110:113], v[154:157], v[184:187], 0
	v_mfma_f32_16x16x32_bf16 v[106:109], v[162:165], v[184:187], 0
	v_mfma_f32_16x16x32_bf16 v[94:97], v[154:157], v[192:195], 0
	v_mfma_f32_16x16x32_bf16 v[90:93], v[162:165], v[192:195], 0
	v_mfma_f32_16x16x32_bf16 v[78:81], v[154:157], v[200:203], 0
	v_mfma_f32_16x16x32_bf16 v[74:77], v[162:165], v[200:203], 0
	v_mfma_f32_16x16x32_bf16 v[126:129], v[158:161], v[180:183], v[126:129]
	v_mfma_f32_16x16x32_bf16 v[122:125], v[166:169], v[180:183], v[122:125]
	v_mfma_f32_16x16x32_bf16 v[110:113], v[158:161], v[188:191], v[110:113]
	v_mfma_f32_16x16x32_bf16 v[106:109], v[166:169], v[188:191], v[106:109]
	v_mfma_f32_16x16x32_bf16 v[94:97], v[158:161], v[196:199], v[94:97]
	v_mfma_f32_16x16x32_bf16 v[90:93], v[166:169], v[196:199], v[90:93]
	v_mfma_f32_16x16x32_bf16 v[78:81], v[158:161], v[204:207], v[78:81]
	v_mfma_f32_16x16x32_bf16 v[74:77], v[166:169], v[204:207], v[74:77]
	v_mfma_f32_16x16x32_bf16 v[118:121], v[208:211], v[176:179], 0
	v_mfma_f32_16x16x32_bf16 v[114:117], v[216:219], v[176:179], 0
	v_mfma_f32_16x16x32_bf16 v[102:105], v[208:211], v[184:187], 0
	v_mfma_f32_16x16x32_bf16 v[98:101], v[216:219], v[184:187], 0
	v_mfma_f32_16x16x32_bf16 v[86:89], v[208:211], v[192:195], 0
	v_mfma_f32_16x16x32_bf16 v[82:85], v[216:219], v[192:195], 0
	v_mfma_f32_16x16x32_bf16 v[70:73], v[208:211], v[200:203], 0
	v_mfma_f32_16x16x32_bf16 v[66:69], v[216:219], v[200:203], 0
	v_mfma_f32_16x16x32_bf16 v[118:121], v[212:215], v[180:183], v[118:121]
	v_mfma_f32_16x16x32_bf16 v[114:117], v[220:223], v[180:183], v[114:117]
	v_mfma_f32_16x16x32_bf16 v[102:105], v[212:215], v[188:191], v[102:105]
	v_mfma_f32_16x16x32_bf16 v[98:101], v[220:223], v[188:191], v[98:101]
	v_mfma_f32_16x16x32_bf16 v[86:89], v[212:215], v[196:199], v[86:89]
	v_mfma_f32_16x16x32_bf16 v[82:85], v[220:223], v[196:199], v[82:85]
	v_mfma_f32_16x16x32_bf16 v[70:73], v[212:215], v[204:207], v[70:73]
	v_mfma_f32_16x16x32_bf16 v[66:69], v[220:223], v[204:207], v[66:69]
	s_barrier
	s_setprio 0
	s_add_i32 s20, s72, s52
	v_lshl_add_u64 v[172:173], s[34:35], 0, v[134:135]
	s_mov_b32 m0, s20
	s_nop 0
	global_load_lds_dwordx4 v[172:173], off
	v_lshl_add_u64 v[224:225], s[34:35], 0, v[130:131]
	s_add_i32 m0, s20, 0x2000
	s_nop 0
	global_load_lds_dwordx4 v[224:225], off
	s_mov_b32 m0, s53
	v_lshl_add_u64 v[226:227], s[18:19], 0, v[136:137]
	ds_read_b128 v[176:179], v152 offset:16384
	ds_read_b128 v[180:183], v152 offset:17408
	ds_read_b128 v[184:187], v152 offset:18432
	ds_read_b128 v[188:191], v152 offset:19456
	ds_read_b128 v[192:195], v152 offset:20480
	ds_read_b128 v[196:199], v152 offset:21504
	ds_read_b128 v[200:203], v152 offset:22528
	ds_read_b128 v[204:207], v152 offset:23552
	global_load_lds_dwordx4 v[226:227], off
	v_lshl_add_u64 v[228:229], s[18:19], 0, v[132:133]
	s_mov_b32 m0, s54
	s_nop 0
	global_load_lds_dwordx4 v[228:229], off
	s_waitcnt vmcnt(6)
	s_waitcnt lgkmcnt(0)
	s_setprio 1
	s_barrier
	v_mfma_f32_16x16x32_bf16 v[62:65], v[154:157], v[176:179], 0
	v_mfma_f32_16x16x32_bf16 v[58:61], v[162:165], v[176:179], 0
	v_mfma_f32_16x16x32_bf16 v[46:49], v[154:157], v[184:187], 0
	v_mfma_f32_16x16x32_bf16 v[42:45], v[162:165], v[184:187], 0
	v_mfma_f32_16x16x32_bf16 v[30:33], v[154:157], v[192:195], 0
	v_mfma_f32_16x16x32_bf16 v[26:29], v[162:165], v[192:195], 0
	v_mfma_f32_16x16x32_bf16 v[14:17], v[154:157], v[200:203], 0
	v_mfma_f32_16x16x32_bf16 v[10:13], v[162:165], v[200:203], 0
	v_mfma_f32_16x16x32_bf16 v[62:65], v[158:161], v[180:183], v[62:65]
	v_mfma_f32_16x16x32_bf16 v[58:61], v[166:169], v[180:183], v[58:61]
	v_mfma_f32_16x16x32_bf16 v[46:49], v[158:161], v[188:191], v[46:49]
	v_mfma_f32_16x16x32_bf16 v[42:45], v[166:169], v[188:191], v[42:45]
	v_mfma_f32_16x16x32_bf16 v[30:33], v[158:161], v[196:199], v[30:33]
	v_mfma_f32_16x16x32_bf16 v[26:29], v[166:169], v[196:199], v[26:29]
	v_mfma_f32_16x16x32_bf16 v[14:17], v[158:161], v[204:207], v[14:17]
	v_mfma_f32_16x16x32_bf16 v[10:13], v[166:169], v[204:207], v[10:13]
	v_mfma_f32_16x16x32_bf16 v[54:57], v[208:211], v[176:179], 0
	v_mfma_f32_16x16x32_bf16 v[50:53], v[216:219], v[176:179], 0
	v_mfma_f32_16x16x32_bf16 v[38:41], v[208:211], v[184:187], 0
	v_mfma_f32_16x16x32_bf16 v[34:37], v[216:219], v[184:187], 0
	v_mfma_f32_16x16x32_bf16 v[22:25], v[208:211], v[192:195], 0
	v_mfma_f32_16x16x32_bf16 v[18:21], v[216:219], v[192:195], 0
	v_mfma_f32_16x16x32_bf16 v[6:9], v[208:211], v[200:203], 0
	v_mfma_f32_16x16x32_bf16 v[2:5], v[216:219], v[200:203], 0
	v_mfma_f32_16x16x32_bf16 v[54:57], v[212:215], v[180:183], v[54:57]
	v_mfma_f32_16x16x32_bf16 v[50:53], v[220:223], v[180:183], v[50:53]
	v_mfma_f32_16x16x32_bf16 v[38:41], v[212:215], v[188:191], v[38:41]
	v_mfma_f32_16x16x32_bf16 v[34:37], v[220:223], v[188:191], v[34:37]
	v_mfma_f32_16x16x32_bf16 v[22:25], v[212:215], v[196:199], v[22:25]
	v_mfma_f32_16x16x32_bf16 v[18:21], v[220:223], v[196:199], v[18:21]
	v_mfma_f32_16x16x32_bf16 v[6:9], v[212:215], v[204:207], v[6:9]
	v_mfma_f32_16x16x32_bf16 v[2:5], v[220:223], v[204:207], v[2:5]
	s_barrier
	s_setprio 0
	s_add_u32 s20, s34, 0x40000
	s_addc_u32 s21, s35, 0
	s_add_i32 s60, s73, s52
	v_lshl_add_u64 v[246:247], s[20:21], 0, v[134:135]
	s_mov_b32 m0, s60
	s_nop 0
	global_load_lds_dwordx4 v[246:247], off
	v_lshl_add_u64 v[246:247], s[20:21], 0, v[130:131]
	s_add_i32 m0, s60, 0x2000
	s_nop 0
	global_load_lds_dwordx4 v[246:247], off
	s_add_i32 s20, 0, 0x18000
	v_add_u32_e32 v166, s20, v150
	ds_read_b128 v[154:157], v166
	ds_read_b128 v[158:161], v166 offset:1024
	ds_read_b128 v[162:165], v166 offset:2048
	ds_read_b128 v[166:169], v166 offset:3072
	s_add_u32 s18, s18, 0x40000
	s_addc_u32 s19, s19, 0
	s_mov_b32 m0, s55
	v_lshl_add_u64 v[208:209], s[18:19], 0, v[136:137]
	ds_read_b128 v[176:179], v152 offset:32768
	ds_read_b128 v[180:183], v152 offset:33792
	ds_read_b128 v[184:187], v152 offset:34816
	ds_read_b128 v[188:191], v152 offset:35840
	ds_read_b128 v[192:195], v152 offset:36864
	ds_read_b128 v[196:199], v152 offset:37888
	ds_read_b128 v[200:203], v152 offset:38912
	ds_read_b128 v[204:207], v152 offset:39936
	global_load_lds_dwordx4 v[208:209], off
	v_lshl_add_u64 v[208:209], s[18:19], 0, v[132:133]
	s_mov_b32 m0, s56
	s_nop 0
	global_load_lds_dwordx4 v[208:209], off
	s_add_i32 s21, 0, 0x1c000
	v_add_u32_e32 v171, s21, v150
	ds_read_b128 v[208:211], v171
	ds_read_b128 v[212:215], v171 offset:1024
	ds_read_b128 v[216:219], v171 offset:2048
	ds_read_b128 v[220:223], v171 offset:3072
	s_waitcnt vmcnt(8)
	s_waitcnt lgkmcnt(0)
	s_setprio 1
	s_barrier
	v_mfma_f32_16x16x32_bf16 v[126:129], v[154:157], v[176:179], v[126:129]
	v_mfma_f32_16x16x32_bf16 v[122:125], v[162:165], v[176:179], v[122:125]
	v_mfma_f32_16x16x32_bf16 v[110:113], v[154:157], v[184:187], v[110:113]
	v_mfma_f32_16x16x32_bf16 v[106:109], v[162:165], v[184:187], v[106:109]
	v_mfma_f32_16x16x32_bf16 v[94:97], v[154:157], v[192:195], v[94:97]
	v_mfma_f32_16x16x32_bf16 v[90:93], v[162:165], v[192:195], v[90:93]
	v_mfma_f32_16x16x32_bf16 v[78:81], v[154:157], v[200:203], v[78:81]
	v_mfma_f32_16x16x32_bf16 v[74:77], v[162:165], v[200:203], v[74:77]
	v_mfma_f32_16x16x32_bf16 v[126:129], v[158:161], v[180:183], v[126:129]
	v_mfma_f32_16x16x32_bf16 v[122:125], v[166:169], v[180:183], v[122:125]
	v_mfma_f32_16x16x32_bf16 v[110:113], v[158:161], v[188:191], v[110:113]
	v_mfma_f32_16x16x32_bf16 v[106:109], v[166:169], v[188:191], v[106:109]
	v_mfma_f32_16x16x32_bf16 v[94:97], v[158:161], v[196:199], v[94:97]
	v_mfma_f32_16x16x32_bf16 v[90:93], v[166:169], v[196:199], v[90:93]
	v_mfma_f32_16x16x32_bf16 v[78:81], v[158:161], v[204:207], v[78:81]
	v_mfma_f32_16x16x32_bf16 v[74:77], v[166:169], v[204:207], v[74:77]
	v_mfma_f32_16x16x32_bf16 v[118:121], v[208:211], v[176:179], v[118:121]
	v_mfma_f32_16x16x32_bf16 v[114:117], v[216:219], v[176:179], v[114:117]
	v_mfma_f32_16x16x32_bf16 v[102:105], v[208:211], v[184:187], v[102:105]
	v_mfma_f32_16x16x32_bf16 v[98:101], v[216:219], v[184:187], v[98:101]
	v_mfma_f32_16x16x32_bf16 v[86:89], v[208:211], v[192:195], v[86:89]
	v_mfma_f32_16x16x32_bf16 v[82:85], v[216:219], v[192:195], v[82:85]
	v_mfma_f32_16x16x32_bf16 v[70:73], v[208:211], v[200:203], v[70:73]
	v_mfma_f32_16x16x32_bf16 v[66:69], v[216:219], v[200:203], v[66:69]
	v_mfma_f32_16x16x32_bf16 v[118:121], v[212:215], v[180:183], v[118:121]
	v_mfma_f32_16x16x32_bf16 v[114:117], v[220:223], v[180:183], v[114:117]
	v_mfma_f32_16x16x32_bf16 v[102:105], v[212:215], v[188:191], v[102:105]
	v_mfma_f32_16x16x32_bf16 v[98:101], v[220:223], v[188:191], v[98:101]
	v_mfma_f32_16x16x32_bf16 v[86:89], v[212:215], v[196:199], v[86:89]
	v_mfma_f32_16x16x32_bf16 v[82:85], v[220:223], v[196:199], v[82:85]
	v_mfma_f32_16x16x32_bf16 v[70:73], v[212:215], v[204:207], v[70:73]
	v_mfma_f32_16x16x32_bf16 v[66:69], v[220:223], v[204:207], v[66:69]
	s_barrier
	s_setprio 0
	s_add_i32 s18, s20, s52
	v_lshl_add_u64 v[172:173], v[172:173], 0, s[4:5]
	s_mov_b32 m0, s18
	s_nop 0
	global_load_lds_dwordx4 v[172:173], off
	v_lshl_add_u64 v[172:173], v[224:225], 0, s[4:5]
	s_add_i32 m0, s18, 0x2000
	s_nop 0
	global_load_lds_dwordx4 v[172:173], off
	s_mov_b32 m0, s68
	v_lshl_add_u64 v[172:173], v[226:227], 0, s[4:5]
	ds_read_b128 v[176:179], v152 offset:49152
	ds_read_b128 v[180:183], v152 offset:50176
	ds_read_b128 v[184:187], v152 offset:51200
	ds_read_b128 v[188:191], v152 offset:52224
	ds_read_b128 v[192:195], v152 offset:53248
	ds_read_b128 v[196:199], v152 offset:54272
	ds_read_b128 v[200:203], v152 offset:55296
	ds_read_b128 v[204:207], v152 offset:56320
	global_load_lds_dwordx4 v[172:173], off
	v_lshl_add_u64 v[172:173], v[228:229], 0, s[4:5]
	s_mov_b32 m0, s69
	s_nop 0
	global_load_lds_dwordx4 v[172:173], off
	s_add_u32 s18, s34, 0x40080
	s_addc_u32 s19, s35, 0
	s_add_i32 s20, s21, s52
	v_lshl_add_u64 v[248:249], s[18:19], 0, v[134:135]
	s_mov_b32 m0, s20
	s_nop 0
	global_load_lds_dwordx4 v[248:249], off
	v_lshl_add_u64 v[248:249], s[18:19], 0, v[130:131]
	s_add_i32 m0, s20, 0x2000
	s_nop 0
	global_load_lds_dwordx4 v[248:249], off
	s_waitcnt vmcnt(6)
	s_waitcnt lgkmcnt(0)
	s_setprio 1
	s_barrier
	v_mfma_f32_16x16x32_bf16 v[62:65], v[154:157], v[176:179], v[62:65]
	v_mfma_f32_16x16x32_bf16 v[58:61], v[162:165], v[176:179], v[58:61]
	v_mfma_f32_16x16x32_bf16 v[46:49], v[154:157], v[184:187], v[46:49]
	v_mfma_f32_16x16x32_bf16 v[42:45], v[162:165], v[184:187], v[42:45]
	v_mfma_f32_16x16x32_bf16 v[30:33], v[154:157], v[192:195], v[30:33]
	v_mfma_f32_16x16x32_bf16 v[26:29], v[162:165], v[192:195], v[26:29]
	v_mfma_f32_16x16x32_bf16 v[14:17], v[154:157], v[200:203], v[14:17]
	v_mfma_f32_16x16x32_bf16 v[10:13], v[162:165], v[200:203], v[10:13]
	v_mfma_f32_16x16x32_bf16 v[62:65], v[158:161], v[180:183], v[62:65]
	v_mfma_f32_16x16x32_bf16 v[58:61], v[166:169], v[180:183], v[58:61]
	v_mfma_f32_16x16x32_bf16 v[46:49], v[158:161], v[188:191], v[46:49]
	v_mfma_f32_16x16x32_bf16 v[42:45], v[166:169], v[188:191], v[42:45]
	v_mfma_f32_16x16x32_bf16 v[30:33], v[158:161], v[196:199], v[30:33]
	v_mfma_f32_16x16x32_bf16 v[26:29], v[166:169], v[196:199], v[26:29]
	v_mfma_f32_16x16x32_bf16 v[14:17], v[158:161], v[204:207], v[14:17]
	v_mfma_f32_16x16x32_bf16 v[10:13], v[166:169], v[204:207], v[10:13]
	v_mfma_f32_16x16x32_bf16 v[54:57], v[208:211], v[176:179], v[54:57]
	v_mfma_f32_16x16x32_bf16 v[50:53], v[216:219], v[176:179], v[50:53]
	v_mfma_f32_16x16x32_bf16 v[38:41], v[208:211], v[184:187], v[38:41]
	v_mfma_f32_16x16x32_bf16 v[34:37], v[216:219], v[184:187], v[34:37]
	v_mfma_f32_16x16x32_bf16 v[22:25], v[208:211], v[192:195], v[22:25]
	v_mfma_f32_16x16x32_bf16 v[18:21], v[216:219], v[192:195], v[18:21]
	v_mfma_f32_16x16x32_bf16 v[6:9], v[208:211], v[200:203], v[6:9]
	v_mfma_f32_16x16x32_bf16 v[2:5], v[216:219], v[200:203], v[2:5]
	v_mfma_f32_16x16x32_bf16 v[54:57], v[212:215], v[180:183], v[54:57]
	v_mfma_f32_16x16x32_bf16 v[50:53], v[220:223], v[180:183], v[50:53]
	v_mfma_f32_16x16x32_bf16 v[38:41], v[212:215], v[188:191], v[38:41]
	v_mfma_f32_16x16x32_bf16 v[34:37], v[220:223], v[188:191], v[34:37]
	v_mfma_f32_16x16x32_bf16 v[22:25], v[212:215], v[196:199], v[22:25]
	v_mfma_f32_16x16x32_bf16 v[18:21], v[220:223], v[196:199], v[18:21]
	v_mfma_f32_16x16x32_bf16 v[6:9], v[212:215], v[204:207], v[6:9]
	v_mfma_f32_16x16x32_bf16 v[2:5], v[220:223], v[204:207], v[2:5]
	s_add_i32 s79, s79, 2
	s_add_u32 s16, s16, 0x100
	s_addc_u32 s17, s17, 0
	s_add_u32 s77, s77, 0x100
	s_addc_u32 s78, s78, 0
	s_cmp_gt_u32 s79, 13
.Ldfr_p2_r:
	s_barrier
	s_setprio 0
.LBB0_567:
	ds_read_b128 v[154:157], v151
	ds_read_b128 v[158:161], v151 offset:1024
	ds_read_b128 v[162:165], v151 offset:2048
	ds_read_b128 v[166:169], v151 offset:3072
	s_add_u32 s18, s16, 0xfffc0080
	s_addc_u32 s19, s17, -1
	s_cmp_eq_u32 s79, 12
	s_cselect_b32 s19, s9, s19
	s_cselect_b32 s18, s75, s18
	s_cselect_b32 s35, s7, s78
	s_cselect_b32 s34, s76, s77
	v_lshl_add_u64 v[172:173], s[16:17], 0, v[140:141]
	s_add_i32 m0, s53, 0xc000
	ds_read_b128 v[176:179], v152
	ds_read_b128 v[180:183], v152 offset:1024
	ds_read_b128 v[184:187], v152 offset:2048
	ds_read_b128 v[188:191], v152 offset:3072
	ds_read_b128 v[192:195], v152 offset:4096
	ds_read_b128 v[196:199], v152 offset:5120
	ds_read_b128 v[200:203], v152 offset:6144
	ds_read_b128 v[204:207], v152 offset:7168
	global_load_lds_dwordx4 v[172:173], off
	v_lshl_add_u64 v[172:173], s[16:17], 0, v[142:143]
	s_add_i32 m0, s53, 0xe000
	s_nop 0
	global_load_lds_dwordx4 v[172:173], off
	ds_read_b128 v[208:211], v153
	ds_read_b128 v[212:215], v153 offset:1024
	ds_read_b128 v[216:219], v153 offset:2048
	ds_read_b128 v[220:223], v153 offset:3072
	s_waitcnt lgkmcnt(0)
	s_setprio 1
	s_barrier
	v_mfma_f32_16x16x32_bf16 v[126:129], v[154:157], v[176:179], v[126:129]
	v_mfma_f32_16x16x32_bf16 v[122:125], v[162:165], v[176:179], v[122:125]
	v_mfma_f32_16x16x32_bf16 v[110:113], v[154:157], v[184:187], v[110:113]
	v_mfma_f32_16x16x32_bf16 v[106:109], v[162:165], v[184:187], v[106:109]
	v_mfma_f32_16x16x32_bf16 v[94:97], v[154:157], v[192:195], v[94:97]
	v_mfma_f32_16x16x32_bf16 v[90:93], v[162:165], v[192:195], v[90:93]
	v_mfma_f32_16x16x32_bf16 v[78:81], v[154:157], v[200:203], v[78:81]
	v_mfma_f32_16x16x32_bf16 v[74:77], v[162:165], v[200:203], v[74:77]
	v_mfma_f32_16x16x32_bf16 v[126:129], v[158:161], v[180:183], v[126:129]
	v_mfma_f32_16x16x32_bf16 v[122:125], v[166:169], v[180:183], v[122:125]
	v_mfma_f32_16x16x32_bf16 v[110:113], v[158:161], v[188:191], v[110:113]
	v_mfma_f32_16x16x32_bf16 v[106:109], v[166:169], v[188:191], v[106:109]
	v_mfma_f32_16x16x32_bf16 v[94:97], v[158:161], v[196:199], v[94:97]
	v_mfma_f32_16x16x32_bf16 v[90:93], v[166:169], v[196:199], v[90:93]
	v_mfma_f32_16x16x32_bf16 v[78:81], v[158:161], v[204:207], v[78:81]
	v_mfma_f32_16x16x32_bf16 v[74:77], v[166:169], v[204:207], v[74:77]
	v_mfma_f32_16x16x32_bf16 v[118:121], v[208:211], v[176:179], v[118:121]
	v_mfma_f32_16x16x32_bf16 v[114:117], v[216:219], v[176:179], v[114:117]
	v_mfma_f32_16x16x32_bf16 v[102:105], v[208:211], v[184:187], v[102:105]
	v_mfma_f32_16x16x32_bf16 v[98:101], v[216:219], v[184:187], v[98:101]
	v_mfma_f32_16x16x32_bf16 v[86:89], v[208:211], v[192:195], v[86:89]
	v_mfma_f32_16x16x32_bf16 v[82:85], v[216:219], v[192:195], v[82:85]
	v_mfma_f32_16x16x32_bf16 v[70:73], v[208:211], v[200:203], v[70:73]
	v_mfma_f32_16x16x32_bf16 v[66:69], v[216:219], v[200:203], v[66:69]
	v_mfma_f32_16x16x32_bf16 v[118:121], v[212:215], v[180:183], v[118:121]
	v_mfma_f32_16x16x32_bf16 v[114:117], v[220:223], v[180:183], v[114:117]
	v_mfma_f32_16x16x32_bf16 v[102:105], v[212:215], v[188:191], v[102:105]
	v_mfma_f32_16x16x32_bf16 v[98:101], v[220:223], v[188:191], v[98:101]
	v_mfma_f32_16x16x32_bf16 v[86:89], v[212:215], v[196:199], v[86:89]
	v_mfma_f32_16x16x32_bf16 v[82:85], v[220:223], v[196:199], v[82:85]
	v_mfma_f32_16x16x32_bf16 v[70:73], v[212:215], v[204:207], v[70:73]
	v_mfma_f32_16x16x32_bf16 v[66:69], v[220:223], v[204:207], v[66:69]
	s_barrier
	s_setprio 0
	s_add_i32 s20, s72, s52
	v_lshl_add_u64 v[172:173], s[34:35], 0, v[134:135]
	s_mov_b32 m0, s20
	s_nop 0
	global_load_lds_dwordx4 v[172:173], off
	v_lshl_add_u64 v[224:225], s[34:35], 0, v[130:131]
	s_add_i32 m0, s20, 0x2000
	s_nop 0
	global_load_lds_dwordx4 v[224:225], off
	s_mov_b32 m0, s53
	v_lshl_add_u64 v[226:227], s[18:19], 0, v[136:137]
	ds_read_b128 v[176:179], v152 offset:16384
	ds_read_b128 v[180:183], v152 offset:17408
	ds_read_b128 v[184:187], v152 offset:18432
	ds_read_b128 v[188:191], v152 offset:19456
	ds_read_b128 v[192:195], v152 offset:20480
	ds_read_b128 v[196:199], v152 offset:21504
	ds_read_b128 v[200:203], v152 offset:22528
	ds_read_b128 v[204:207], v152 offset:23552
	global_load_lds_dwordx4 v[226:227], off
	v_lshl_add_u64 v[228:229], s[18:19], 0, v[132:133]
	s_mov_b32 m0, s54
	s_nop 0
	global_load_lds_dwordx4 v[228:229], off
	s_waitcnt vmcnt(6)
	s_waitcnt lgkmcnt(0)
	s_setprio 1
	s_barrier
	v_mfma_f32_16x16x32_bf16 v[62:65], v[154:157], v[176:179], v[62:65]
	v_mfma_f32_16x16x32_bf16 v[58:61], v[162:165], v[176:179], v[58:61]
	v_mfma_f32_16x16x32_bf16 v[46:49], v[154:157], v[184:187], v[46:49]
	v_mfma_f32_16x16x32_bf16 v[42:45], v[162:165], v[184:187], v[42:45]
	v_mfma_f32_16x16x32_bf16 v[30:33], v[154:157], v[192:195], v[30:33]
	v_mfma_f32_16x16x32_bf16 v[26:29], v[162:165], v[192:195], v[26:29]
	v_mfma_f32_16x16x32_bf16 v[14:17], v[154:157], v[200:203], v[14:17]
	v_mfma_f32_16x16x32_bf16 v[10:13], v[162:165], v[200:203], v[10:13]
	v_mfma_f32_16x16x32_bf16 v[62:65], v[158:161], v[180:183], v[62:65]
	v_mfma_f32_16x16x32_bf16 v[58:61], v[166:169], v[180:183], v[58:61]
	v_mfma_f32_16x16x32_bf16 v[46:49], v[158:161], v[188:191], v[46:49]
	v_mfma_f32_16x16x32_bf16 v[42:45], v[166:169], v[188:191], v[42:45]
	v_mfma_f32_16x16x32_bf16 v[30:33], v[158:161], v[196:199], v[30:33]
	v_mfma_f32_16x16x32_bf16 v[26:29], v[166:169], v[196:199], v[26:29]
	v_mfma_f32_16x16x32_bf16 v[14:17], v[158:161], v[204:207], v[14:17]
	v_mfma_f32_16x16x32_bf16 v[10:13], v[166:169], v[204:207], v[10:13]
	v_mfma_f32_16x16x32_bf16 v[54:57], v[208:211], v[176:179], v[54:57]
	v_mfma_f32_16x16x32_bf16 v[50:53], v[216:219], v[176:179], v[50:53]
	v_mfma_f32_16x16x32_bf16 v[38:41], v[208:211], v[184:187], v[38:41]
	v_mfma_f32_16x16x32_bf16 v[34:37], v[216:219], v[184:187], v[34:37]
	v_mfma_f32_16x16x32_bf16 v[22:25], v[208:211], v[192:195], v[22:25]
	v_mfma_f32_16x16x32_bf16 v[18:21], v[216:219], v[192:195], v[18:21]
	v_mfma_f32_16x16x32_bf16 v[6:9], v[208:211], v[200:203], v[6:9]
	v_mfma_f32_16x16x32_bf16 v[2:5], v[216:219], v[200:203], v[2:5]
	v_mfma_f32_16x16x32_bf16 v[54:57], v[212:215], v[180:183], v[54:57]
	v_mfma_f32_16x16x32_bf16 v[50:53], v[220:223], v[180:183], v[50:53]
	v_mfma_f32_16x16x32_bf16 v[38:41], v[212:215], v[188:191], v[38:41]
	v_mfma_f32_16x16x32_bf16 v[34:37], v[220:223], v[188:191], v[34:37]
	v_mfma_f32_16x16x32_bf16 v[22:25], v[212:215], v[196:199], v[22:25]
	v_mfma_f32_16x16x32_bf16 v[18:21], v[220:223], v[196:199], v[18:21]
	v_mfma_f32_16x16x32_bf16 v[6:9], v[212:215], v[204:207], v[6:9]
	v_mfma_f32_16x16x32_bf16 v[2:5], v[220:223], v[204:207], v[2:5]
	s_barrier
	s_setprio 0
	s_add_u32 s20, s34, 0x40000
	s_addc_u32 s21, s35, 0
	s_add_i32 s60, s73, s52
	v_lshl_add_u64 v[246:247], s[20:21], 0, v[134:135]
	s_mov_b32 m0, s60
	s_nop 0
	global_load_lds_dwordx4 v[246:247], off
	v_lshl_add_u64 v[246:247], s[20:21], 0, v[130:131]
	s_add_i32 m0, s60, 0x2000
	s_nop 0
	global_load_lds_dwordx4 v[246:247], off
	s_add_i32 s20, 0, 0x18000
	v_add_u32_e32 v166, s20, v150
	ds_read_b128 v[154:157], v166
	ds_read_b128 v[158:161], v166 offset:1024
	ds_read_b128 v[162:165], v166 offset:2048
	ds_read_b128 v[166:169], v166 offset:3072
	s_add_u32 s18, s18, 0x40000
	s_addc_u32 s19, s19, 0
	s_mov_b32 m0, s55
	v_lshl_add_u64 v[208:209], s[18:19], 0, v[136:137]
	ds_read_b128 v[176:179], v152 offset:32768
	ds_read_b128 v[180:183], v152 offset:33792
	ds_read_b128 v[184:187], v152 offset:34816
	ds_read_b128 v[188:191], v152 offset:35840
	ds_read_b128 v[192:195], v152 offset:36864
	ds_read_b128 v[196:199], v152 offset:37888
	ds_read_b128 v[200:203], v152 offset:38912
	ds_read_b128 v[204:207], v152 offset:39936
	global_load_lds_dwordx4 v[208:209], off
	v_lshl_add_u64 v[208:209], s[18:19], 0, v[132:133]
	s_mov_b32 m0, s56
	s_nop 0
	global_load_lds_dwordx4 v[208:209], off
	s_add_i32 s21, 0, 0x1c000
	v_add_u32_e32 v171, s21, v150
	ds_read_b128 v[208:211], v171
	ds_read_b128 v[212:215], v171 offset:1024
	ds_read_b128 v[216:219], v171 offset:2048
	ds_read_b128 v[220:223], v171 offset:3072
	s_waitcnt vmcnt(8)
	s_waitcnt lgkmcnt(0)
	s_setprio 1
	s_barrier
	v_mfma_f32_16x16x32_bf16 v[126:129], v[154:157], v[176:179], v[126:129]
	v_mfma_f32_16x16x32_bf16 v[122:125], v[162:165], v[176:179], v[122:125]
	v_mfma_f32_16x16x32_bf16 v[110:113], v[154:157], v[184:187], v[110:113]
	v_mfma_f32_16x16x32_bf16 v[106:109], v[162:165], v[184:187], v[106:109]
	v_mfma_f32_16x16x32_bf16 v[94:97], v[154:157], v[192:195], v[94:97]
	v_mfma_f32_16x16x32_bf16 v[90:93], v[162:165], v[192:195], v[90:93]
	v_mfma_f32_16x16x32_bf16 v[78:81], v[154:157], v[200:203], v[78:81]
	v_mfma_f32_16x16x32_bf16 v[74:77], v[162:165], v[200:203], v[74:77]
	v_mfma_f32_16x16x32_bf16 v[126:129], v[158:161], v[180:183], v[126:129]
	v_mfma_f32_16x16x32_bf16 v[122:125], v[166:169], v[180:183], v[122:125]
	v_mfma_f32_16x16x32_bf16 v[110:113], v[158:161], v[188:191], v[110:113]
	v_mfma_f32_16x16x32_bf16 v[106:109], v[166:169], v[188:191], v[106:109]
	v_mfma_f32_16x16x32_bf16 v[94:97], v[158:161], v[196:199], v[94:97]
	v_mfma_f32_16x16x32_bf16 v[90:93], v[166:169], v[196:199], v[90:93]
	v_mfma_f32_16x16x32_bf16 v[78:81], v[158:161], v[204:207], v[78:81]
	v_mfma_f32_16x16x32_bf16 v[74:77], v[166:169], v[204:207], v[74:77]
	v_mfma_f32_16x16x32_bf16 v[118:121], v[208:211], v[176:179], v[118:121]
	v_mfma_f32_16x16x32_bf16 v[114:117], v[216:219], v[176:179], v[114:117]
	v_mfma_f32_16x16x32_bf16 v[102:105], v[208:211], v[184:187], v[102:105]
	v_mfma_f32_16x16x32_bf16 v[98:101], v[216:219], v[184:187], v[98:101]
	v_mfma_f32_16x16x32_bf16 v[86:89], v[208:211], v[192:195], v[86:89]
	v_mfma_f32_16x16x32_bf16 v[82:85], v[216:219], v[192:195], v[82:85]
	v_mfma_f32_16x16x32_bf16 v[70:73], v[208:211], v[200:203], v[70:73]
	v_mfma_f32_16x16x32_bf16 v[66:69], v[216:219], v[200:203], v[66:69]
	v_mfma_f32_16x16x32_bf16 v[118:121], v[212:215], v[180:183], v[118:121]
	v_mfma_f32_16x16x32_bf16 v[114:117], v[220:223], v[180:183], v[114:117]
	v_mfma_f32_16x16x32_bf16 v[102:105], v[212:215], v[188:191], v[102:105]
	v_mfma_f32_16x16x32_bf16 v[98:101], v[220:223], v[188:191], v[98:101]
	v_mfma_f32_16x16x32_bf16 v[86:89], v[212:215], v[196:199], v[86:89]
	v_mfma_f32_16x16x32_bf16 v[82:85], v[220:223], v[196:199], v[82:85]
	v_mfma_f32_16x16x32_bf16 v[70:73], v[212:215], v[204:207], v[70:73]
	v_mfma_f32_16x16x32_bf16 v[66:69], v[220:223], v[204:207], v[66:69]
	s_barrier
	s_setprio 0
	s_add_i32 s18, s20, s52
	v_lshl_add_u64 v[172:173], v[172:173], 0, s[4:5]
	s_mov_b32 m0, s18
	s_nop 0
	global_load_lds_dwordx4 v[172:173], off
	v_lshl_add_u64 v[172:173], v[224:225], 0, s[4:5]
	s_add_i32 m0, s18, 0x2000
	s_nop 0
	global_load_lds_dwordx4 v[172:173], off
	s_mov_b32 m0, s68
	v_lshl_add_u64 v[172:173], v[226:227], 0, s[4:5]
	ds_read_b128 v[176:179], v152 offset:49152
	ds_read_b128 v[180:183], v152 offset:50176
	ds_read_b128 v[184:187], v152 offset:51200
	ds_read_b128 v[188:191], v152 offset:52224
	ds_read_b128 v[192:195], v152 offset:53248
	ds_read_b128 v[196:199], v152 offset:54272
	ds_read_b128 v[200:203], v152 offset:55296
	ds_read_b128 v[204:207], v152 offset:56320
	global_load_lds_dwordx4 v[172:173], off
	v_lshl_add_u64 v[172:173], v[228:229], 0, s[4:5]
	s_mov_b32 m0, s69
	s_nop 0
	global_load_lds_dwordx4 v[172:173], off
	s_add_u32 s18, s34, 0x40080
	s_addc_u32 s19, s35, 0
	s_add_i32 s20, s21, s52
	v_lshl_add_u64 v[248:249], s[18:19], 0, v[134:135]
	s_mov_b32 m0, s20
	s_nop 0
	global_load_lds_dwordx4 v[248:249], off
	v_lshl_add_u64 v[248:249], s[18:19], 0, v[130:131]
	s_add_i32 m0, s20, 0x2000
	s_nop 0
	global_load_lds_dwordx4 v[248:249], off
	s_waitcnt vmcnt(6)
	s_waitcnt lgkmcnt(0)
	s_setprio 1
	s_barrier
	v_mfma_f32_16x16x32_bf16 v[62:65], v[154:157], v[176:179], v[62:65]
	v_mfma_f32_16x16x32_bf16 v[58:61], v[162:165], v[176:179], v[58:61]
	v_mfma_f32_16x16x32_bf16 v[46:49], v[154:157], v[184:187], v[46:49]
	v_mfma_f32_16x16x32_bf16 v[42:45], v[162:165], v[184:187], v[42:45]
	v_mfma_f32_16x16x32_bf16 v[30:33], v[154:157], v[192:195], v[30:33]
	v_mfma_f32_16x16x32_bf16 v[26:29], v[162:165], v[192:195], v[26:29]
	v_mfma_f32_16x16x32_bf16 v[14:17], v[154:157], v[200:203], v[14:17]
	v_mfma_f32_16x16x32_bf16 v[10:13], v[162:165], v[200:203], v[10:13]
	v_mfma_f32_16x16x32_bf16 v[62:65], v[158:161], v[180:183], v[62:65]
	v_mfma_f32_16x16x32_bf16 v[58:61], v[166:169], v[180:183], v[58:61]
	v_mfma_f32_16x16x32_bf16 v[46:49], v[158:161], v[188:191], v[46:49]
	v_mfma_f32_16x16x32_bf16 v[42:45], v[166:169], v[188:191], v[42:45]
	v_mfma_f32_16x16x32_bf16 v[30:33], v[158:161], v[196:199], v[30:33]
	v_mfma_f32_16x16x32_bf16 v[26:29], v[166:169], v[196:199], v[26:29]
	v_mfma_f32_16x16x32_bf16 v[14:17], v[158:161], v[204:207], v[14:17]
	v_mfma_f32_16x16x32_bf16 v[10:13], v[166:169], v[204:207], v[10:13]
	v_mfma_f32_16x16x32_bf16 v[54:57], v[208:211], v[176:179], v[54:57]
	v_mfma_f32_16x16x32_bf16 v[50:53], v[216:219], v[176:179], v[50:53]
	v_mfma_f32_16x16x32_bf16 v[38:41], v[208:211], v[184:187], v[38:41]
	v_mfma_f32_16x16x32_bf16 v[34:37], v[216:219], v[184:187], v[34:37]
	v_mfma_f32_16x16x32_bf16 v[22:25], v[208:211], v[192:195], v[22:25]
	v_mfma_f32_16x16x32_bf16 v[18:21], v[216:219], v[192:195], v[18:21]
	v_mfma_f32_16x16x32_bf16 v[6:9], v[208:211], v[200:203], v[6:9]
	v_mfma_f32_16x16x32_bf16 v[2:5], v[216:219], v[200:203], v[2:5]
	v_mfma_f32_16x16x32_bf16 v[54:57], v[212:215], v[180:183], v[54:57]
	v_mfma_f32_16x16x32_bf16 v[50:53], v[220:223], v[180:183], v[50:53]
	v_mfma_f32_16x16x32_bf16 v[38:41], v[212:215], v[188:191], v[38:41]
	v_mfma_f32_16x16x32_bf16 v[34:37], v[220:223], v[188:191], v[34:37]
	v_mfma_f32_16x16x32_bf16 v[22:25], v[212:215], v[196:199], v[22:25]
	v_mfma_f32_16x16x32_bf16 v[18:21], v[220:223], v[196:199], v[18:21]
	v_mfma_f32_16x16x32_bf16 v[6:9], v[212:215], v[204:207], v[6:9]
	v_mfma_f32_16x16x32_bf16 v[2:5], v[220:223], v[204:207], v[2:5]
	s_add_i32 s79, s79, 2
	s_add_u32 s16, s16, 0x100
	s_addc_u32 s17, s17, 0
	s_add_u32 s77, s77, 0x100
	s_addc_u32 s78, s78, 0
	s_cmp_gt_u32 s79, 13
	s_cbranch_scc0 .Ldfr_p2_r
	s_cmpk_gt_u32 s33, 0xff
	s_cbranch_scc1 .Ldfr_p2_b
	s_barrier
.Ldfr_p2_b:
	s_setprio 0
	v_mul_f32_e32 v154, 0xbfb8aa3b, v126
	v_mul_f32_e32 v155, 0xbfb8aa3b, v127
	v_exp_f32_e32 v154, v154
	v_exp_f32_e32 v155, v155
	s_and_b64 vcc, exec, s[2:3]
	s_mov_b64 s[34:35], s[12:13]
	v_add_f32_e32 v154, 1.0, v154
	v_add_f32_e32 v155, 1.0, v155
	v_rcp_f32_e32 v156, v154
	v_rcp_f32_e32 v157, v155
	v_mul_f32_e32 v155, 0xbfb8aa3b, v128
	v_exp_f32_e32 v155, v155
	v_lshl_add_u32 v154, s14, 8, v149
	v_pk_mul_f32 v[126:127], v[126:127], v[156:157]
	v_mul_f32_e32 v156, 0xbfb8aa3b, v129
	v_exp_f32_e32 v156, v156
	v_pk_mul_f32 v[118:119], v[126:127], v[118:119]
	v_add_f32_e32 v126, 1.0, v155
	v_mul_f32_e32 v155, 0xbfb8aa3b, v122
	v_add_f32_e32 v127, 1.0, v156
	v_rcp_f32_e32 v126, v126
	v_rcp_f32_e32 v127, v127
	v_exp_f32_e32 v155, v155
	v_mul_f32_e32 v156, 0xbfb8aa3b, v123
	v_exp_f32_e32 v156, v156
	v_pk_mul_f32 v[126:127], v[128:129], v[126:127]
	v_add_f32_e32 v128, 1.0, v155
	v_mul_f32_e32 v155, 0xbfb8aa3b, v124
	v_add_f32_e32 v129, 1.0, v156
	v_exp_f32_e32 v155, v155
	v_mul_f32_e32 v156, 0xbfb8aa3b, v125
	v_exp_f32_e32 v157, v156
	v_rcp_f32_e32 v128, v128
	v_add_f32_e32 v155, 1.0, v155
	v_rcp_f32_e32 v129, v129
	v_rcp_f32_e32 v156, v155
	v_add_f32_e32 v155, 1.0, v157
	v_rcp_f32_e32 v157, v155
	v_pk_mul_f32 v[122:123], v[122:123], v[128:129]
	s_lshl_b32 s14, s15, 7
	v_pk_mul_f32 v[122:123], v[122:123], v[114:115]
	v_pk_mul_f32 v[114:115], v[124:125], v[156:157]
	s_ashr_i32 s15, s14, 31
	v_pk_mul_f32 v[124:125], v[114:115], v[116:117]
	v_mov_b64_e32 v[114:115], s[0:1]
	v_mad_i64_i32 v[116:117], s[16:17], v154, s74, v[114:115]
	s_lshl_b64 s[14:15], s[14:15], 1
	v_lshl_add_u64 v[116:117], v[116:117], 0, s[14:15]
	v_pk_mul_f32 v[120:121], v[126:127], v[120:121]
	v_lshl_add_u64 v[126:127], v[116:117], 0, v[138:139]
	v_cvt_pk_bf16_f32 v116, v118, v119
	v_mul_f32_e32 v118, 0xbfb8aa3b, v110
	v_exp_f32_e32 v119, v118
	v_mul_f32_e32 v118, 0xbfb8aa3b, v111
	v_cvt_pk_bf16_f32 v117, v120, v121
	v_exp_f32_e32 v121, v118
	v_add_f32_e32 v119, 1.0, v119
	v_rcp_f32_e32 v120, v119
	v_cvt_pk_bf16_f32 v118, v122, v123
	v_add_f32_e32 v119, 1.0, v121
	v_rcp_f32_e32 v121, v119
	v_cvt_pk_bf16_f32 v119, v124, v125
	global_store_dwordx4 v[126:127], v[116:119], off nt
	v_pk_mul_f32 v[110:111], v[110:111], v[120:121]
	s_nop 0
	v_mul_f32_e32 v116, 0xbfb8aa3b, v112
	v_mul_f32_e32 v117, 0xbfb8aa3b, v113
	v_exp_f32_e32 v116, v116
	v_exp_f32_e32 v117, v117
	v_pk_mul_f32 v[102:103], v[110:111], v[102:103]
	v_or_b32_e32 v118, 16, v154
	v_add_f32_e32 v110, 1.0, v116
	v_add_f32_e32 v111, 1.0, v117
	v_mul_f32_e32 v116, 0xbfb8aa3b, v106
	v_mul_f32_e32 v117, 0xbfb8aa3b, v107
	v_rcp_f32_e32 v110, v110
	v_rcp_f32_e32 v111, v111
	v_exp_f32_e32 v116, v116
	v_exp_f32_e32 v117, v117
	v_pk_mul_f32 v[110:111], v[112:113], v[110:111]
	v_add_f32_e32 v112, 1.0, v116
	v_add_f32_e32 v113, 1.0, v117
	v_mul_f32_e32 v116, 0xbfb8aa3b, v108
	v_mul_f32_e32 v117, 0xbfb8aa3b, v109
	v_exp_f32_e32 v116, v116
	v_exp_f32_e32 v117, v117
	v_rcp_f32_e32 v112, v112
	v_rcp_f32_e32 v113, v113
	v_add_f32_e32 v116, 1.0, v116
	v_add_f32_e32 v117, 1.0, v117
	v_rcp_f32_e32 v116, v116
	v_rcp_f32_e32 v117, v117
	v_pk_mul_f32 v[106:107], v[106:107], v[112:113]
	v_pk_mul_f32 v[104:105], v[110:111], v[104:105]
	v_pk_mul_f32 v[106:107], v[106:107], v[98:99]
	v_pk_mul_f32 v[98:99], v[108:109], v[116:117]
	s_nop 0
	v_pk_mul_f32 v[108:109], v[98:99], v[100:101]
	v_mad_i64_i32 v[98:99], s[16:17], v118, s74, v[114:115]
	v_mul_f32_e32 v100, 0xbfb8aa3b, v94
	v_lshl_add_u64 v[98:99], v[98:99], 0, s[14:15]
	v_exp_f32_e32 v101, v100
	v_mul_f32_e32 v100, 0xbfb8aa3b, v95
	v_lshl_add_u64 v[110:111], v[98:99], 0, v[138:139]
	v_cvt_pk_bf16_f32 v98, v102, v103
	v_exp_f32_e32 v103, v100
	v_add_f32_e32 v101, 1.0, v101
	v_rcp_f32_e32 v102, v101
	v_cvt_pk_bf16_f32 v99, v104, v105
	v_add_f32_e32 v101, 1.0, v103
	v_cvt_pk_bf16_f32 v100, v106, v107
	v_rcp_f32_e32 v103, v101
	v_cvt_pk_bf16_f32 v101, v108, v109
	global_store_dwordx4 v[110:111], v[98:101], off nt
	v_pk_mul_f32 v[94:95], v[94:95], v[102:103]
	s_nop 0
	v_mul_f32_e32 v98, 0xbfb8aa3b, v96
	v_mul_f32_e32 v99, 0xbfb8aa3b, v97
	v_exp_f32_e32 v98, v98
	v_exp_f32_e32 v99, v99
	v_pk_mul_f32 v[86:87], v[94:95], v[86:87]
	v_or_b32_e32 v100, 32, v154
	v_add_f32_e32 v94, 1.0, v98
	v_add_f32_e32 v95, 1.0, v99
	v_mul_f32_e32 v98, 0xbfb8aa3b, v90
	v_mul_f32_e32 v99, 0xbfb8aa3b, v91
	v_rcp_f32_e32 v94, v94
	v_rcp_f32_e32 v95, v95
	v_exp_f32_e32 v98, v98
	v_exp_f32_e32 v99, v99
	v_pk_mul_f32 v[94:95], v[96:97], v[94:95]
	v_add_f32_e32 v96, 1.0, v98
	v_add_f32_e32 v97, 1.0, v99
	v_mul_f32_e32 v98, 0xbfb8aa3b, v92
	v_mul_f32_e32 v99, 0xbfb8aa3b, v93
	v_exp_f32_e32 v98, v98
	v_exp_f32_e32 v99, v99
	v_rcp_f32_e32 v96, v96
	v_rcp_f32_e32 v97, v97
	v_add_f32_e32 v98, 1.0, v98
	v_add_f32_e32 v99, 1.0, v99
	v_rcp_f32_e32 v98, v98
	v_rcp_f32_e32 v99, v99
	v_pk_mul_f32 v[90:91], v[90:91], v[96:97]
	v_pk_mul_f32 v[88:89], v[94:95], v[88:89]
	v_pk_mul_f32 v[90:91], v[90:91], v[82:83]
	v_pk_mul_f32 v[82:83], v[92:93], v[98:99]
	s_nop 0
	v_pk_mul_f32 v[92:93], v[82:83], v[84:85]
	v_mad_i64_i32 v[82:83], s[16:17], v100, s74, v[114:115]
	v_mul_f32_e32 v84, 0xbfb8aa3b, v78
	v_lshl_add_u64 v[82:83], v[82:83], 0, s[14:15]
	v_exp_f32_e32 v85, v84
	v_mul_f32_e32 v84, 0xbfb8aa3b, v79
	v_lshl_add_u64 v[94:95], v[82:83], 0, v[138:139]
	v_cvt_pk_bf16_f32 v82, v86, v87
	v_exp_f32_e32 v87, v84
	v_add_f32_e32 v85, 1.0, v85
	v_rcp_f32_e32 v86, v85
	v_cvt_pk_bf16_f32 v83, v88, v89
	v_add_f32_e32 v85, 1.0, v87
	v_cvt_pk_bf16_f32 v84, v90, v91
	v_rcp_f32_e32 v87, v85
	v_cvt_pk_bf16_f32 v85, v92, v93
	global_store_dwordx4 v[94:95], v[82:85], off nt
	v_pk_mul_f32 v[78:79], v[78:79], v[86:87]
	s_nop 0
	v_mul_f32_e32 v82, 0xbfb8aa3b, v80
	v_mul_f32_e32 v83, 0xbfb8aa3b, v81
	v_exp_f32_e32 v82, v82
	v_exp_f32_e32 v83, v83
	v_pk_mul_f32 v[70:71], v[78:79], v[70:71]
	v_or_b32_e32 v84, 48, v154
	v_add_f32_e32 v78, 1.0, v82
	v_add_f32_e32 v79, 1.0, v83
	v_mul_f32_e32 v82, 0xbfb8aa3b, v74
	v_mul_f32_e32 v83, 0xbfb8aa3b, v75
	v_rcp_f32_e32 v78, v78
	v_rcp_f32_e32 v79, v79
	v_exp_f32_e32 v82, v82
	v_exp_f32_e32 v83, v83
	v_pk_mul_f32 v[78:79], v[80:81], v[78:79]
	v_add_f32_e32 v80, 1.0, v82
	v_add_f32_e32 v81, 1.0, v83
	v_mul_f32_e32 v82, 0xbfb8aa3b, v76
	v_mul_f32_e32 v83, 0xbfb8aa3b, v77
	v_exp_f32_e32 v82, v82
	v_exp_f32_e32 v83, v83
	v_rcp_f32_e32 v80, v80
	v_rcp_f32_e32 v81, v81
	v_add_f32_e32 v82, 1.0, v82
	v_add_f32_e32 v83, 1.0, v83
	v_rcp_f32_e32 v82, v82
	v_rcp_f32_e32 v83, v83
	v_pk_mul_f32 v[74:75], v[74:75], v[80:81]
	v_pk_mul_f32 v[72:73], v[78:79], v[72:73]
	v_pk_mul_f32 v[74:75], v[74:75], v[66:67]
	v_pk_mul_f32 v[66:67], v[76:77], v[82:83]
	s_nop 0
	v_pk_mul_f32 v[76:77], v[66:67], v[68:69]
	v_mad_i64_i32 v[66:67], s[16:17], v84, s74, v[114:115]
	v_mul_f32_e32 v68, 0xbfb8aa3b, v62
	v_lshl_add_u64 v[66:67], v[66:67], 0, s[14:15]
	v_exp_f32_e32 v69, v68
	v_mul_f32_e32 v68, 0xbfb8aa3b, v63
	v_lshl_add_u64 v[78:79], v[66:67], 0, v[138:139]
	v_cvt_pk_bf16_f32 v66, v70, v71
	v_exp_f32_e32 v71, v68
	v_add_f32_e32 v69, 1.0, v69
	v_rcp_f32_e32 v70, v69
	v_cvt_pk_bf16_f32 v67, v72, v73
	v_add_f32_e32 v69, 1.0, v71
	v_cvt_pk_bf16_f32 v68, v74, v75
	v_rcp_f32_e32 v71, v69
	v_cvt_pk_bf16_f32 v69, v76, v77
	global_store_dwordx4 v[78:79], v[66:69], off nt
	v_pk_mul_f32 v[62:63], v[62:63], v[70:71]
	s_nop 0
	v_mul_f32_e32 v66, 0xbfb8aa3b, v64
	v_mul_f32_e32 v67, 0xbfb8aa3b, v65
	v_exp_f32_e32 v66, v66
	v_exp_f32_e32 v67, v67
	v_pk_mul_f32 v[54:55], v[62:63], v[54:55]
	v_add_u32_e32 v68, 0x80, v154
	v_add_f32_e32 v62, 1.0, v66
	v_add_f32_e32 v63, 1.0, v67
	v_mul_f32_e32 v66, 0xbfb8aa3b, v58
	v_mul_f32_e32 v67, 0xbfb8aa3b, v59
	v_rcp_f32_e32 v62, v62
	v_rcp_f32_e32 v63, v63
	v_exp_f32_e32 v66, v66
	v_exp_f32_e32 v67, v67
	v_pk_mul_f32 v[62:63], v[64:65], v[62:63]
	v_add_f32_e32 v64, 1.0, v66
	v_add_f32_e32 v65, 1.0, v67
	v_mul_f32_e32 v66, 0xbfb8aa3b, v60
	v_mul_f32_e32 v67, 0xbfb8aa3b, v61
	v_exp_f32_e32 v66, v66
	v_exp_f32_e32 v67, v67
	v_rcp_f32_e32 v64, v64
	v_rcp_f32_e32 v65, v65
	v_add_f32_e32 v66, 1.0, v66
	v_add_f32_e32 v67, 1.0, v67
	v_rcp_f32_e32 v66, v66
	v_rcp_f32_e32 v67, v67
	v_pk_mul_f32 v[58:59], v[58:59], v[64:65]
	v_pk_mul_f32 v[56:57], v[62:63], v[56:57]
	v_pk_mul_f32 v[58:59], v[58:59], v[50:51]
	v_pk_mul_f32 v[50:51], v[60:61], v[66:67]
	s_nop 0
	v_pk_mul_f32 v[60:61], v[50:51], v[52:53]
	v_mad_i64_i32 v[50:51], s[16:17], v68, s74, v[114:115]
	v_mul_f32_e32 v52, 0xbfb8aa3b, v46
	v_lshl_add_u64 v[50:51], v[50:51], 0, s[14:15]
	v_exp_f32_e32 v53, v52
	v_mul_f32_e32 v52, 0xbfb8aa3b, v47
	v_lshl_add_u64 v[62:63], v[50:51], 0, v[138:139]
	v_cvt_pk_bf16_f32 v50, v54, v55
	v_exp_f32_e32 v55, v52
	v_add_f32_e32 v53, 1.0, v53
	v_rcp_f32_e32 v54, v53
	v_cvt_pk_bf16_f32 v51, v56, v57
	v_add_f32_e32 v53, 1.0, v55
	v_cvt_pk_bf16_f32 v52, v58, v59
	v_rcp_f32_e32 v55, v53
	v_cvt_pk_bf16_f32 v53, v60, v61
	global_store_dwordx4 v[62:63], v[50:53], off nt
	v_pk_mul_f32 v[46:47], v[46:47], v[54:55]
	s_nop 0
	v_mul_f32_e32 v50, 0xbfb8aa3b, v48
	v_mul_f32_e32 v51, 0xbfb8aa3b, v49
	v_exp_f32_e32 v50, v50
	v_exp_f32_e32 v51, v51
	v_pk_mul_f32 v[38:39], v[46:47], v[38:39]
	v_add_u32_e32 v52, 0x90, v154
	v_add_f32_e32 v46, 1.0, v50
	v_add_f32_e32 v47, 1.0, v51
	v_mul_f32_e32 v50, 0xbfb8aa3b, v42
	v_mul_f32_e32 v51, 0xbfb8aa3b, v43
	v_rcp_f32_e32 v46, v46
	v_rcp_f32_e32 v47, v47
	v_exp_f32_e32 v50, v50
	v_exp_f32_e32 v51, v51
	v_pk_mul_f32 v[46:47], v[48:49], v[46:47]
	v_add_f32_e32 v48, 1.0, v50
	v_add_f32_e32 v49, 1.0, v51
	v_mul_f32_e32 v50, 0xbfb8aa3b, v44
	v_mul_f32_e32 v51, 0xbfb8aa3b, v45
	v_exp_f32_e32 v50, v50
	v_exp_f32_e32 v51, v51
	v_rcp_f32_e32 v48, v48
	v_rcp_f32_e32 v49, v49
	v_add_f32_e32 v50, 1.0, v50
	v_add_f32_e32 v51, 1.0, v51
	v_rcp_f32_e32 v50, v50
	v_rcp_f32_e32 v51, v51
	v_pk_mul_f32 v[42:43], v[42:43], v[48:49]
	v_pk_mul_f32 v[40:41], v[46:47], v[40:41]
	v_pk_mul_f32 v[42:43], v[42:43], v[34:35]
	v_pk_mul_f32 v[34:35], v[44:45], v[50:51]
	s_nop 0
	v_pk_mul_f32 v[44:45], v[34:35], v[36:37]
	v_mad_i64_i32 v[34:35], s[16:17], v52, s74, v[114:115]
	v_mul_f32_e32 v36, 0xbfb8aa3b, v30
	v_lshl_add_u64 v[34:35], v[34:35], 0, s[14:15]
	v_exp_f32_e32 v37, v36
	v_mul_f32_e32 v36, 0xbfb8aa3b, v31
	v_lshl_add_u64 v[46:47], v[34:35], 0, v[138:139]
	v_cvt_pk_bf16_f32 v34, v38, v39
	v_exp_f32_e32 v39, v36
	v_add_f32_e32 v37, 1.0, v37
	v_rcp_f32_e32 v38, v37
	v_cvt_pk_bf16_f32 v35, v40, v41
	v_add_f32_e32 v37, 1.0, v39
	v_cvt_pk_bf16_f32 v36, v42, v43
	v_rcp_f32_e32 v39, v37
	v_cvt_pk_bf16_f32 v37, v44, v45
	global_store_dwordx4 v[46:47], v[34:37], off nt
	v_pk_mul_f32 v[30:31], v[30:31], v[38:39]
	s_nop 0
	v_mul_f32_e32 v34, 0xbfb8aa3b, v32
	v_mul_f32_e32 v35, 0xbfb8aa3b, v33
	v_exp_f32_e32 v34, v34
	v_exp_f32_e32 v35, v35
	v_pk_mul_f32 v[22:23], v[30:31], v[22:23]
	v_add_u32_e32 v36, 0xa0, v154
	v_add_f32_e32 v30, 1.0, v34
	v_add_f32_e32 v31, 1.0, v35
	v_mul_f32_e32 v34, 0xbfb8aa3b, v26
	v_mul_f32_e32 v35, 0xbfb8aa3b, v27
	v_rcp_f32_e32 v30, v30
	v_rcp_f32_e32 v31, v31
	v_exp_f32_e32 v34, v34
	v_exp_f32_e32 v35, v35
	v_pk_mul_f32 v[30:31], v[32:33], v[30:31]
	v_add_f32_e32 v32, 1.0, v34
	v_add_f32_e32 v33, 1.0, v35
	v_mul_f32_e32 v34, 0xbfb8aa3b, v28
	v_mul_f32_e32 v35, 0xbfb8aa3b, v29
	v_exp_f32_e32 v34, v34
	v_exp_f32_e32 v35, v35
	v_rcp_f32_e32 v32, v32
	v_rcp_f32_e32 v33, v33
	v_add_f32_e32 v34, 1.0, v34
	v_add_f32_e32 v35, 1.0, v35
	v_rcp_f32_e32 v34, v34
	v_rcp_f32_e32 v35, v35
	v_pk_mul_f32 v[26:27], v[26:27], v[32:33]
	v_pk_mul_f32 v[24:25], v[30:31], v[24:25]
	v_pk_mul_f32 v[26:27], v[26:27], v[18:19]
	v_pk_mul_f32 v[18:19], v[28:29], v[34:35]
	s_nop 0
	v_pk_mul_f32 v[28:29], v[18:19], v[20:21]
	v_mad_i64_i32 v[18:19], s[16:17], v36, s74, v[114:115]
	v_mul_f32_e32 v20, 0xbfb8aa3b, v14
	v_lshl_add_u64 v[18:19], v[18:19], 0, s[14:15]
	v_exp_f32_e32 v21, v20
	v_mul_f32_e32 v20, 0xbfb8aa3b, v15
	v_lshl_add_u64 v[30:31], v[18:19], 0, v[138:139]
	v_cvt_pk_bf16_f32 v18, v22, v23
	v_exp_f32_e32 v23, v20
	v_add_f32_e32 v21, 1.0, v21
	v_rcp_f32_e32 v22, v21
	v_cvt_pk_bf16_f32 v19, v24, v25
	v_add_f32_e32 v21, 1.0, v23
	v_cvt_pk_bf16_f32 v20, v26, v27
	v_rcp_f32_e32 v23, v21
	v_cvt_pk_bf16_f32 v21, v28, v29
	global_store_dwordx4 v[30:31], v[18:21], off nt
	v_pk_mul_f32 v[14:15], v[14:15], v[22:23]
	s_nop 0
	v_mul_f32_e32 v18, 0xbfb8aa3b, v16
	v_mul_f32_e32 v19, 0xbfb8aa3b, v17
	v_exp_f32_e32 v18, v18
	v_exp_f32_e32 v19, v19
	v_pk_mul_f32 v[6:7], v[14:15], v[6:7]
	v_add_u32_e32 v20, 0xb0, v154
	v_add_f32_e32 v14, 1.0, v18
	v_add_f32_e32 v15, 1.0, v19
	v_mul_f32_e32 v18, 0xbfb8aa3b, v10
	v_mul_f32_e32 v19, 0xbfb8aa3b, v11
	v_rcp_f32_e32 v14, v14
	v_rcp_f32_e32 v15, v15
	v_exp_f32_e32 v18, v18
	v_exp_f32_e32 v19, v19
	v_pk_mul_f32 v[14:15], v[16:17], v[14:15]
	v_add_f32_e32 v16, 1.0, v18
	v_add_f32_e32 v17, 1.0, v19
	v_mul_f32_e32 v18, 0xbfb8aa3b, v12
	v_mul_f32_e32 v19, 0xbfb8aa3b, v13
	v_exp_f32_e32 v18, v18
	v_exp_f32_e32 v19, v19
	v_rcp_f32_e32 v16, v16
	v_rcp_f32_e32 v17, v17
	v_add_f32_e32 v18, 1.0, v18
	v_add_f32_e32 v19, 1.0, v19
	v_rcp_f32_e32 v18, v18
	v_rcp_f32_e32 v19, v19
	v_pk_mul_f32 v[10:11], v[10:11], v[16:17]
	v_pk_mul_f32 v[8:9], v[14:15], v[8:9]
	v_pk_mul_f32 v[10:11], v[10:11], v[2:3]
	v_pk_mul_f32 v[2:3], v[12:13], v[18:19]
	s_nop 0
	v_pk_mul_f32 v[12:13], v[2:3], v[4:5]
	v_mad_i64_i32 v[2:3], s[16:17], v20, s74, v[114:115]
	v_lshl_add_u64 v[2:3], v[2:3], 0, s[14:15]
	v_lshl_add_u64 v[14:15], v[2:3], 0, v[138:139]
	v_cvt_pk_bf16_f32 v2, v6, v7
	v_cvt_pk_bf16_f32 v3, v8, v9
	v_cvt_pk_bf16_f32 v4, v10, v11
	v_cvt_pk_bf16_f32 v5, v12, v13
	s_mov_b32 s15, s6
	s_mov_b32 s14, s8
	s_mov_b64 s[16:17], s[10:11]
	global_store_dwordx4 v[14:15], v[2:5], off nt
	s_cmpk_gt_u32 s33, 0xff
	s_cbranch_scc0 .Ldfr_p2_c
	s_barrier
.Ldfr_p2_c:
	s_cbranch_vccz .LBB0_564
	s_waitcnt vmcnt(0)
	s_cmpk_gt_u32 s33, 0xff
	s_cbranch_scc1 .LBB0_571
	s_barrier

.LBB0_810:
	s_or_b64 exec, exec, s[0:1]
	s_cmpk_gt_u32 s53, 0xff
	s_cbranch_scc0 .Ldfr_p3_c
	s_barrier
.Ldfr_p3_c:
	s_and_b64 vcc, exec, s[4:5]
	s_mov_b32 s34, s87
	s_mov_b32 s48, s89
	s_mov_b64 s[8:9], s[40:41]
	s_mov_b64 s[10:11], s[38:39]
	s_cbranch_vccnz .LBB0_855

.LBB0_821:
	s_add_u32 s0, s10, 0xb0080
	s_addc_u32 s1, s11, 0
	s_add_u32 s10, s8, 0x100
	s_addc_u32 s11, s9, 0
	s_mov_b32 s49, -2
	s_waitcnt lgkmcnt(0)
	ds_read_b128 v[130:133], v241
	ds_read_b128 v[134:137], v241 offset:1024
	ds_read_b128 v[138:141], v241 offset:2048
	ds_read_b128 v[142:145], v241 offset:3072
	s_add_u32 s6, s0, 0xfff50080
	s_addc_u32 s7, s1, -1
	s_cmp_eq_u32 s49, 40
	s_cselect_b32 s9, s39, s7
	s_cselect_b32 s8, s38, s6
	s_cselect_b32 s7, s41, s11
	s_cselect_b32 s6, s40, s10
	v_lshl_add_u64 v[202:203], s[0:1], 0, v[186:187]
	s_add_i32 m0, s57, 0xc000
	ds_read_b128 v[146:149], v242
	ds_read_b128 v[150:153], v242 offset:1024
	ds_read_b128 v[154:157], v242 offset:2048
	ds_read_b128 v[158:161], v242 offset:3072
	ds_read_b128 v[162:165], v242 offset:4096
	ds_read_b128 v[166:169], v242 offset:5120
	ds_read_b128 v[194:197], v242 offset:6144
	ds_read_b128 v[198:201], v242 offset:7168
	global_load_lds_dwordx4 v[202:203], off
	v_lshl_add_u64 v[202:203], s[0:1], 0, v[188:189]
	s_add_i32 m0, s57, 0xe000
	s_nop 0
	global_load_lds_dwordx4 v[202:203], off
	s_waitcnt lgkmcnt(8)
	s_setprio 1
	s_barrier
	s_waitcnt lgkmcnt(0)
	v_mfma_f32_16x16x32_bf16 v[126:129], v[130:133], v[146:149], 0
	v_mfma_f32_16x16x32_bf16 v[122:125], v[138:141], v[146:149], 0
	v_mfma_f32_16x16x32_bf16 v[110:113], v[130:133], v[154:157], 0
	v_mfma_f32_16x16x32_bf16 v[106:109], v[138:141], v[154:157], 0
	v_mfma_f32_16x16x32_bf16 v[94:97], v[130:133], v[162:165], 0
	v_mfma_f32_16x16x32_bf16 v[90:93], v[138:141], v[162:165], 0
	v_mfma_f32_16x16x32_bf16 v[78:81], v[130:133], v[194:197], 0
	v_mfma_f32_16x16x32_bf16 v[74:77], v[138:141], v[194:197], 0
	v_mfma_f32_16x16x32_bf16 v[126:129], v[134:137], v[150:153], v[126:129]
	v_mfma_f32_16x16x32_bf16 v[122:125], v[142:145], v[150:153], v[122:125]
	v_mfma_f32_16x16x32_bf16 v[110:113], v[134:137], v[158:161], v[110:113]
	v_mfma_f32_16x16x32_bf16 v[106:109], v[142:145], v[158:161], v[106:109]
	v_mfma_f32_16x16x32_bf16 v[94:97], v[134:137], v[166:169], v[94:97]
	v_mfma_f32_16x16x32_bf16 v[90:93], v[142:145], v[166:169], v[90:93]
	v_mfma_f32_16x16x32_bf16 v[78:81], v[134:137], v[198:201], v[78:81]
	v_mfma_f32_16x16x32_bf16 v[74:77], v[142:145], v[198:201], v[74:77]
	s_barrier
	s_setprio 0
	s_add_i32 s20, s77, s56
	v_lshl_add_u64 v[218:219], s[6:7], 0, v[176:177]
	s_mov_b32 m0, s20
	ds_read_b128 v[202:205], v243
	ds_read_b128 v[206:209], v243 offset:1024
	ds_read_b128 v[210:213], v243 offset:2048
	ds_read_b128 v[214:217], v243 offset:3072
	global_load_lds_dwordx4 v[218:219], off
	v_lshl_add_u64 v[220:221], s[6:7], 0, v[180:181]
	s_add_i32 m0, s20, 0x2000
	s_nop 0
	global_load_lds_dwordx4 v[220:221], off
	s_setprio 1
	s_barrier
	s_waitcnt lgkmcnt(0)
	v_mfma_f32_16x16x32_bf16 v[118:121], v[202:205], v[146:149], 0
	v_mfma_f32_16x16x32_bf16 v[114:117], v[210:213], v[146:149], 0
	v_mfma_f32_16x16x32_bf16 v[102:105], v[202:205], v[154:157], 0
	v_mfma_f32_16x16x32_bf16 v[98:101], v[210:213], v[154:157], 0
	v_mfma_f32_16x16x32_bf16 v[86:89], v[202:205], v[162:165], 0
	v_mfma_f32_16x16x32_bf16 v[82:85], v[210:213], v[162:165], 0
	v_mfma_f32_16x16x32_bf16 v[70:73], v[202:205], v[194:197], 0
	v_mfma_f32_16x16x32_bf16 v[66:69], v[210:213], v[194:197], 0
	v_mfma_f32_16x16x32_bf16 v[118:121], v[206:209], v[150:153], v[118:121]
	v_mfma_f32_16x16x32_bf16 v[114:117], v[214:217], v[150:153], v[114:117]
	v_mfma_f32_16x16x32_bf16 v[102:105], v[206:209], v[158:161], v[102:105]
	v_mfma_f32_16x16x32_bf16 v[98:101], v[214:217], v[158:161], v[98:101]
	v_mfma_f32_16x16x32_bf16 v[86:89], v[206:209], v[166:169], v[86:89]
	v_mfma_f32_16x16x32_bf16 v[82:85], v[214:217], v[166:169], v[82:85]
	v_mfma_f32_16x16x32_bf16 v[70:73], v[206:209], v[198:201], v[70:73]
	v_mfma_f32_16x16x32_bf16 v[66:69], v[214:217], v[198:201], v[66:69]
	s_barrier
	s_setprio 0
	s_mov_b32 m0, s57
	v_lshl_add_u64 v[222:223], s[8:9], 0, v[172:173]
	ds_read_b128 v[146:149], v242 offset:16384
	ds_read_b128 v[150:153], v242 offset:17408
	ds_read_b128 v[154:157], v242 offset:18432
	ds_read_b128 v[158:161], v242 offset:19456
	ds_read_b128 v[162:165], v242 offset:20480
	ds_read_b128 v[166:169], v242 offset:21504
	ds_read_b128 v[194:197], v242 offset:22528
	ds_read_b128 v[198:201], v242 offset:23552
	global_load_lds_dwordx4 v[222:223], off
	v_lshl_add_u64 v[224:225], s[8:9], 0, v[178:179]
	s_mov_b32 m0, s68
	s_nop 0
	global_load_lds_dwordx4 v[224:225], off
	s_setprio 1
	s_barrier
	s_waitcnt lgkmcnt(0)
	v_mfma_f32_16x16x32_bf16 v[62:65], v[130:133], v[146:149], 0
	v_mfma_f32_16x16x32_bf16 v[58:61], v[138:141], v[146:149], 0
	v_mfma_f32_16x16x32_bf16 v[46:49], v[130:133], v[154:157], 0
	v_mfma_f32_16x16x32_bf16 v[42:45], v[138:141], v[154:157], 0
	v_mfma_f32_16x16x32_bf16 v[30:33], v[130:133], v[162:165], 0
	v_mfma_f32_16x16x32_bf16 v[26:29], v[138:141], v[162:165], 0
	v_mfma_f32_16x16x32_bf16 v[14:17], v[130:133], v[194:197], 0
	v_mfma_f32_16x16x32_bf16 v[10:13], v[138:141], v[194:197], 0
	v_mfma_f32_16x16x32_bf16 v[62:65], v[134:137], v[150:153], v[62:65]
	v_mfma_f32_16x16x32_bf16 v[58:61], v[142:145], v[150:153], v[58:61]
	v_mfma_f32_16x16x32_bf16 v[46:49], v[134:137], v[158:161], v[46:49]
	v_mfma_f32_16x16x32_bf16 v[42:45], v[142:145], v[158:161], v[42:45]
	v_mfma_f32_16x16x32_bf16 v[30:33], v[134:137], v[166:169], v[30:33]
	v_mfma_f32_16x16x32_bf16 v[26:29], v[142:145], v[166:169], v[26:29]
	v_mfma_f32_16x16x32_bf16 v[14:17], v[134:137], v[198:201], v[14:17]
	v_mfma_f32_16x16x32_bf16 v[10:13], v[142:145], v[198:201], v[10:13]
	s_barrier
	s_setprio 0
	s_add_u32 s20, s6, 0xb0000
	s_addc_u32 s21, s7, 0
	s_add_i32 s50, s78, s56
	v_lshl_add_u64 v[130:131], s[20:21], 0, v[176:177]
	s_mov_b32 m0, s50
	s_nop 0
	global_load_lds_dwordx4 v[130:131], off
	v_lshl_add_u64 v[130:131], s[20:21], 0, v[180:181]
	s_add_i32 m0, s50, 0x2000
	s_nop 0
	global_load_lds_dwordx4 v[130:131], off
	s_waitcnt vmcnt(6)
	s_setprio 1
	s_barrier
	v_mfma_f32_16x16x32_bf16 v[54:57], v[202:205], v[146:149], 0
	v_mfma_f32_16x16x32_bf16 v[50:53], v[210:213], v[146:149], 0
	v_mfma_f32_16x16x32_bf16 v[38:41], v[202:205], v[154:157], 0
	v_mfma_f32_16x16x32_bf16 v[34:37], v[210:213], v[154:157], 0
	v_mfma_f32_16x16x32_bf16 v[22:25], v[202:205], v[162:165], 0
	v_mfma_f32_16x16x32_bf16 v[18:21], v[210:213], v[162:165], 0
	v_mfma_f32_16x16x32_bf16 v[6:9], v[202:205], v[194:197], 0
	v_mfma_f32_16x16x32_bf16 v[2:5], v[210:213], v[194:197], 0
	v_mfma_f32_16x16x32_bf16 v[54:57], v[206:209], v[150:153], v[54:57]
	v_mfma_f32_16x16x32_bf16 v[50:53], v[214:217], v[150:153], v[50:53]
	v_mfma_f32_16x16x32_bf16 v[38:41], v[206:209], v[158:161], v[38:41]
	v_mfma_f32_16x16x32_bf16 v[34:37], v[214:217], v[158:161], v[34:37]
	v_mfma_f32_16x16x32_bf16 v[22:25], v[206:209], v[166:169], v[22:25]
	v_mfma_f32_16x16x32_bf16 v[18:21], v[214:217], v[166:169], v[18:21]
	v_mfma_f32_16x16x32_bf16 v[6:9], v[206:209], v[198:201], v[6:9]
	v_mfma_f32_16x16x32_bf16 v[2:5], v[214:217], v[198:201], v[2:5]
	s_barrier
	s_setprio 0
	s_add_i32 s20, 0, 0x18000
	v_add_u32_e32 v142, s20, v240
	ds_read_b128 v[130:133], v142
	ds_read_b128 v[134:137], v142 offset:1024
	ds_read_b128 v[138:141], v142 offset:2048
	ds_read_b128 v[142:145], v142 offset:3072
	s_add_u32 s8, s8, 0xb0000
	s_addc_u32 s9, s9, 0
	s_mov_b32 m0, s69
	v_lshl_add_u64 v[202:203], s[8:9], 0, v[172:173]
	ds_read_b128 v[146:149], v242 offset:32768
	ds_read_b128 v[150:153], v242 offset:33792
	ds_read_b128 v[154:157], v242 offset:34816
	ds_read_b128 v[158:161], v242 offset:35840
	ds_read_b128 v[162:165], v242 offset:36864
	ds_read_b128 v[166:169], v242 offset:37888
	ds_read_b128 v[194:197], v242 offset:38912
	ds_read_b128 v[198:201], v242 offset:39936
	global_load_lds_dwordx4 v[202:203], off
	v_lshl_add_u64 v[202:203], s[8:9], 0, v[178:179]
	s_mov_b32 m0, s70
	s_nop 0
	global_load_lds_dwordx4 v[202:203], off
	s_waitcnt lgkmcnt(8)
	s_setprio 1
	s_barrier
	s_waitcnt lgkmcnt(0)
	v_mfma_f32_16x16x32_bf16 v[126:129], v[130:133], v[146:149], v[126:129]
	v_mfma_f32_16x16x32_bf16 v[122:125], v[138:141], v[146:149], v[122:125]
	v_mfma_f32_16x16x32_bf16 v[110:113], v[130:133], v[154:157], v[110:113]
	v_mfma_f32_16x16x32_bf16 v[106:109], v[138:141], v[154:157], v[106:109]
	v_mfma_f32_16x16x32_bf16 v[94:97], v[130:133], v[162:165], v[94:97]
	v_mfma_f32_16x16x32_bf16 v[90:93], v[138:141], v[162:165], v[90:93]
	v_mfma_f32_16x16x32_bf16 v[78:81], v[130:133], v[194:197], v[78:81]
	v_mfma_f32_16x16x32_bf16 v[74:77], v[138:141], v[194:197], v[74:77]
	v_mfma_f32_16x16x32_bf16 v[126:129], v[134:137], v[150:153], v[126:129]
	v_mfma_f32_16x16x32_bf16 v[122:125], v[142:145], v[150:153], v[122:125]
	v_mfma_f32_16x16x32_bf16 v[110:113], v[134:137], v[158:161], v[110:113]
	v_mfma_f32_16x16x32_bf16 v[106:109], v[142:145], v[158:161], v[106:109]
	v_mfma_f32_16x16x32_bf16 v[94:97], v[134:137], v[166:169], v[94:97]
	v_mfma_f32_16x16x32_bf16 v[90:93], v[142:145], v[166:169], v[90:93]
	v_mfma_f32_16x16x32_bf16 v[78:81], v[134:137], v[198:201], v[78:81]
	v_mfma_f32_16x16x32_bf16 v[74:77], v[142:145], v[198:201], v[74:77]
	s_barrier
	s_setprio 0
	s_add_i32 s8, 0, 0x1c000
	s_add_i32 s9, s20, s56
	v_add_u32_e32 v184, s8, v240
	v_lshl_add_u64 v[218:219], v[218:219], 0, s[16:17]
	s_mov_b32 m0, s9
	ds_read_b128 v[202:205], v184
	ds_read_b128 v[206:209], v184 offset:1024
	ds_read_b128 v[210:213], v184 offset:2048
	ds_read_b128 v[214:217], v184 offset:3072
	global_load_lds_dwordx4 v[218:219], off
	v_lshl_add_u64 v[218:219], v[220:221], 0, s[16:17]
	s_add_i32 m0, s9, 0x2000
	s_nop 0
	global_load_lds_dwordx4 v[218:219], off
	s_setprio 1
	s_barrier
	s_waitcnt lgkmcnt(0)
	v_mfma_f32_16x16x32_bf16 v[118:121], v[202:205], v[146:149], v[118:121]
	v_mfma_f32_16x16x32_bf16 v[114:117], v[210:213], v[146:149], v[114:117]
	v_mfma_f32_16x16x32_bf16 v[102:105], v[202:205], v[154:157], v[102:105]
	v_mfma_f32_16x16x32_bf16 v[98:101], v[210:213], v[154:157], v[98:101]
	v_mfma_f32_16x16x32_bf16 v[86:89], v[202:205], v[162:165], v[86:89]
	v_mfma_f32_16x16x32_bf16 v[82:85], v[210:213], v[162:165], v[82:85]
	v_mfma_f32_16x16x32_bf16 v[70:73], v[202:205], v[194:197], v[70:73]
	v_mfma_f32_16x16x32_bf16 v[66:69], v[210:213], v[194:197], v[66:69]
	v_mfma_f32_16x16x32_bf16 v[118:121], v[206:209], v[150:153], v[118:121]
	v_mfma_f32_16x16x32_bf16 v[114:117], v[214:217], v[150:153], v[114:117]
	v_mfma_f32_16x16x32_bf16 v[102:105], v[206:209], v[158:161], v[102:105]
	v_mfma_f32_16x16x32_bf16 v[98:101], v[214:217], v[158:161], v[98:101]
	v_mfma_f32_16x16x32_bf16 v[86:89], v[206:209], v[166:169], v[86:89]
	v_mfma_f32_16x16x32_bf16 v[82:85], v[214:217], v[166:169], v[82:85]
	v_mfma_f32_16x16x32_bf16 v[70:73], v[206:209], v[198:201], v[70:73]
	v_mfma_f32_16x16x32_bf16 v[66:69], v[214:217], v[198:201], v[66:69]
	s_barrier
	s_setprio 0
	s_mov_b32 m0, s74
	v_lshl_add_u64 v[218:219], v[222:223], 0, s[16:17]
	ds_read_b128 v[146:149], v242 offset:49152
	ds_read_b128 v[150:153], v242 offset:50176
	ds_read_b128 v[154:157], v242 offset:51200
	ds_read_b128 v[158:161], v242 offset:52224
	ds_read_b128 v[162:165], v242 offset:53248
	ds_read_b128 v[166:169], v242 offset:54272
	ds_read_b128 v[194:197], v242 offset:55296
	ds_read_b128 v[198:201], v242 offset:56320
	global_load_lds_dwordx4 v[218:219], off
	v_lshl_add_u64 v[218:219], v[224:225], 0, s[16:17]
	s_mov_b32 m0, s75
	s_nop 0
	global_load_lds_dwordx4 v[218:219], off
	s_setprio 1
	s_barrier
	s_waitcnt lgkmcnt(0)
	v_mfma_f32_16x16x32_bf16 v[62:65], v[130:133], v[146:149], v[62:65]
	v_mfma_f32_16x16x32_bf16 v[58:61], v[138:141], v[146:149], v[58:61]
	v_mfma_f32_16x16x32_bf16 v[46:49], v[130:133], v[154:157], v[46:49]
	v_mfma_f32_16x16x32_bf16 v[42:45], v[138:141], v[154:157], v[42:45]
	v_mfma_f32_16x16x32_bf16 v[30:33], v[130:133], v[162:165], v[30:33]
	v_mfma_f32_16x16x32_bf16 v[26:29], v[138:141], v[162:165], v[26:29]
	v_mfma_f32_16x16x32_bf16 v[14:17], v[130:133], v[194:197], v[14:17]
	v_mfma_f32_16x16x32_bf16 v[10:13], v[138:141], v[194:197], v[10:13]
	v_mfma_f32_16x16x32_bf16 v[62:65], v[134:137], v[150:153], v[62:65]
	v_mfma_f32_16x16x32_bf16 v[58:61], v[142:145], v[150:153], v[58:61]
	v_mfma_f32_16x16x32_bf16 v[46:49], v[134:137], v[158:161], v[46:49]
	v_mfma_f32_16x16x32_bf16 v[42:45], v[142:145], v[158:161], v[42:45]
	v_mfma_f32_16x16x32_bf16 v[30:33], v[134:137], v[166:169], v[30:33]
	v_mfma_f32_16x16x32_bf16 v[26:29], v[142:145], v[166:169], v[26:29]
	v_mfma_f32_16x16x32_bf16 v[14:17], v[134:137], v[198:201], v[14:17]
	v_mfma_f32_16x16x32_bf16 v[10:13], v[142:145], v[198:201], v[10:13]
	s_barrier
	s_setprio 0
	s_add_u32 s6, s6, 0xb0080
	s_addc_u32 s7, s7, 0
	s_add_i32 s8, s8, s56
	v_lshl_add_u64 v[130:131], s[6:7], 0, v[176:177]
	s_mov_b32 m0, s8
	s_nop 0
	global_load_lds_dwordx4 v[130:131], off
	v_lshl_add_u64 v[130:131], s[6:7], 0, v[180:181]
	s_add_i32 m0, s8, 0x2000
	s_nop 0
	global_load_lds_dwordx4 v[130:131], off
	s_waitcnt vmcnt(6)
	s_setprio 1
	s_barrier
	v_mfma_f32_16x16x32_bf16 v[54:57], v[202:205], v[146:149], v[54:57]
	v_mfma_f32_16x16x32_bf16 v[50:53], v[210:213], v[146:149], v[50:53]
	v_mfma_f32_16x16x32_bf16 v[38:41], v[202:205], v[154:157], v[38:41]
	v_mfma_f32_16x16x32_bf16 v[34:37], v[210:213], v[154:157], v[34:37]
	v_mfma_f32_16x16x32_bf16 v[22:25], v[202:205], v[162:165], v[22:25]
	v_mfma_f32_16x16x32_bf16 v[18:21], v[210:213], v[162:165], v[18:21]
	v_mfma_f32_16x16x32_bf16 v[6:9], v[202:205], v[194:197], v[6:9]
	v_mfma_f32_16x16x32_bf16 v[2:5], v[210:213], v[194:197], v[2:5]
	v_mfma_f32_16x16x32_bf16 v[54:57], v[206:209], v[150:153], v[54:57]
	v_mfma_f32_16x16x32_bf16 v[50:53], v[214:217], v[150:153], v[50:53]
	v_mfma_f32_16x16x32_bf16 v[38:41], v[206:209], v[158:161], v[38:41]
	v_mfma_f32_16x16x32_bf16 v[34:37], v[214:217], v[158:161], v[34:37]
	v_mfma_f32_16x16x32_bf16 v[22:25], v[206:209], v[166:169], v[22:25]
	v_mfma_f32_16x16x32_bf16 v[18:21], v[214:217], v[166:169], v[18:21]
	v_mfma_f32_16x16x32_bf16 v[6:9], v[206:209], v[198:201], v[6:9]
	v_mfma_f32_16x16x32_bf16 v[2:5], v[214:217], v[198:201], v[2:5]
	s_add_i32 s49, s49, 2
	s_add_u32 s0, s0, 0x100
	s_addc_u32 s1, s1, 0
	s_add_u32 s10, s10, 0x100
	s_addc_u32 s11, s11, 0
	s_cmp_gt_u32 s49, 41

.LBB0_822:
	ds_read_b128 v[130:133], v241
	ds_read_b128 v[134:137], v241 offset:1024
	ds_read_b128 v[138:141], v241 offset:2048
	ds_read_b128 v[142:145], v241 offset:3072
	s_add_u32 s6, s0, 0xfff50080
	s_addc_u32 s7, s1, -1
	s_cmp_eq_u32 s49, 40
	s_cselect_b32 s9, s39, s7
	s_cselect_b32 s8, s38, s6
	s_cselect_b32 s7, s41, s11
	s_cselect_b32 s6, s40, s10
	v_lshl_add_u64 v[202:203], s[0:1], 0, v[186:187]
	s_add_i32 m0, s57, 0xc000
	ds_read_b128 v[146:149], v242
	ds_read_b128 v[150:153], v242 offset:1024
	ds_read_b128 v[154:157], v242 offset:2048
	ds_read_b128 v[158:161], v242 offset:3072
	ds_read_b128 v[162:165], v242 offset:4096
	ds_read_b128 v[166:169], v242 offset:5120
	ds_read_b128 v[194:197], v242 offset:6144
	ds_read_b128 v[198:201], v242 offset:7168
	global_load_lds_dwordx4 v[202:203], off
	v_lshl_add_u64 v[202:203], s[0:1], 0, v[188:189]
	s_add_i32 m0, s57, 0xe000
	s_nop 0
	global_load_lds_dwordx4 v[202:203], off
	s_waitcnt lgkmcnt(8)
	s_setprio 1
	s_barrier
	s_waitcnt lgkmcnt(0)
	v_mfma_f32_16x16x32_bf16 v[126:129], v[130:133], v[146:149], v[126:129]
	v_mfma_f32_16x16x32_bf16 v[122:125], v[138:141], v[146:149], v[122:125]
	v_mfma_f32_16x16x32_bf16 v[110:113], v[130:133], v[154:157], v[110:113]
	v_mfma_f32_16x16x32_bf16 v[106:109], v[138:141], v[154:157], v[106:109]
	v_mfma_f32_16x16x32_bf16 v[94:97], v[130:133], v[162:165], v[94:97]
	v_mfma_f32_16x16x32_bf16 v[90:93], v[138:141], v[162:165], v[90:93]
	v_mfma_f32_16x16x32_bf16 v[78:81], v[130:133], v[194:197], v[78:81]
	v_mfma_f32_16x16x32_bf16 v[74:77], v[138:141], v[194:197], v[74:77]
	v_mfma_f32_16x16x32_bf16 v[126:129], v[134:137], v[150:153], v[126:129]
	v_mfma_f32_16x16x32_bf16 v[122:125], v[142:145], v[150:153], v[122:125]
	v_mfma_f32_16x16x32_bf16 v[110:113], v[134:137], v[158:161], v[110:113]
	v_mfma_f32_16x16x32_bf16 v[106:109], v[142:145], v[158:161], v[106:109]
	v_mfma_f32_16x16x32_bf16 v[94:97], v[134:137], v[166:169], v[94:97]
	v_mfma_f32_16x16x32_bf16 v[90:93], v[142:145], v[166:169], v[90:93]
	v_mfma_f32_16x16x32_bf16 v[78:81], v[134:137], v[198:201], v[78:81]
	v_mfma_f32_16x16x32_bf16 v[74:77], v[142:145], v[198:201], v[74:77]
	s_barrier
	s_setprio 0
	s_add_i32 s20, s77, s56
	v_lshl_add_u64 v[218:219], s[6:7], 0, v[176:177]
	s_mov_b32 m0, s20
	ds_read_b128 v[202:205], v243
	ds_read_b128 v[206:209], v243 offset:1024
	ds_read_b128 v[210:213], v243 offset:2048
	ds_read_b128 v[214:217], v243 offset:3072
	global_load_lds_dwordx4 v[218:219], off
	v_lshl_add_u64 v[220:221], s[6:7], 0, v[180:181]
	s_add_i32 m0, s20, 0x2000
	s_nop 0
	global_load_lds_dwordx4 v[220:221], off
	s_setprio 1
	s_barrier
	s_waitcnt lgkmcnt(0)
	v_mfma_f32_16x16x32_bf16 v[118:121], v[202:205], v[146:149], v[118:121]
	v_mfma_f32_16x16x32_bf16 v[114:117], v[210:213], v[146:149], v[114:117]
	v_mfma_f32_16x16x32_bf16 v[102:105], v[202:205], v[154:157], v[102:105]
	v_mfma_f32_16x16x32_bf16 v[98:101], v[210:213], v[154:157], v[98:101]
	v_mfma_f32_16x16x32_bf16 v[86:89], v[202:205], v[162:165], v[86:89]
	v_mfma_f32_16x16x32_bf16 v[82:85], v[210:213], v[162:165], v[82:85]
	v_mfma_f32_16x16x32_bf16 v[70:73], v[202:205], v[194:197], v[70:73]
	v_mfma_f32_16x16x32_bf16 v[66:69], v[210:213], v[194:197], v[66:69]
	v_mfma_f32_16x16x32_bf16 v[118:121], v[206:209], v[150:153], v[118:121]
	v_mfma_f32_16x16x32_bf16 v[114:117], v[214:217], v[150:153], v[114:117]
	v_mfma_f32_16x16x32_bf16 v[102:105], v[206:209], v[158:161], v[102:105]
	v_mfma_f32_16x16x32_bf16 v[98:101], v[214:217], v[158:161], v[98:101]
	v_mfma_f32_16x16x32_bf16 v[86:89], v[206:209], v[166:169], v[86:89]
	v_mfma_f32_16x16x32_bf16 v[82:85], v[214:217], v[166:169], v[82:85]
	v_mfma_f32_16x16x32_bf16 v[70:73], v[206:209], v[198:201], v[70:73]
	v_mfma_f32_16x16x32_bf16 v[66:69], v[214:217], v[198:201], v[66:69]
	s_barrier
	s_setprio 0
	s_mov_b32 m0, s57
	v_lshl_add_u64 v[222:223], s[8:9], 0, v[172:173]
	ds_read_b128 v[146:149], v242 offset:16384
	ds_read_b128 v[150:153], v242 offset:17408
	ds_read_b128 v[154:157], v242 offset:18432
	ds_read_b128 v[158:161], v242 offset:19456
	ds_read_b128 v[162:165], v242 offset:20480
	ds_read_b128 v[166:169], v242 offset:21504
	ds_read_b128 v[194:197], v242 offset:22528
	ds_read_b128 v[198:201], v242 offset:23552
	global_load_lds_dwordx4 v[222:223], off
	v_lshl_add_u64 v[224:225], s[8:9], 0, v[178:179]
	s_mov_b32 m0, s68
	s_nop 0
	global_load_lds_dwordx4 v[224:225], off
	s_setprio 1
	s_barrier
	s_waitcnt lgkmcnt(0)
	v_mfma_f32_16x16x32_bf16 v[62:65], v[130:133], v[146:149], v[62:65]
	v_mfma_f32_16x16x32_bf16 v[58:61], v[138:141], v[146:149], v[58:61]
	v_mfma_f32_16x16x32_bf16 v[46:49], v[130:133], v[154:157], v[46:49]
	v_mfma_f32_16x16x32_bf16 v[42:45], v[138:141], v[154:157], v[42:45]
	v_mfma_f32_16x16x32_bf16 v[30:33], v[130:133], v[162:165], v[30:33]
	v_mfma_f32_16x16x32_bf16 v[26:29], v[138:141], v[162:165], v[26:29]
	v_mfma_f32_16x16x32_bf16 v[14:17], v[130:133], v[194:197], v[14:17]
	v_mfma_f32_16x16x32_bf16 v[10:13], v[138:141], v[194:197], v[10:13]
	v_mfma_f32_16x16x32_bf16 v[62:65], v[134:137], v[150:153], v[62:65]
	v_mfma_f32_16x16x32_bf16 v[58:61], v[142:145], v[150:153], v[58:61]
	v_mfma_f32_16x16x32_bf16 v[46:49], v[134:137], v[158:161], v[46:49]
	v_mfma_f32_16x16x32_bf16 v[42:45], v[142:145], v[158:161], v[42:45]
	v_mfma_f32_16x16x32_bf16 v[30:33], v[134:137], v[166:169], v[30:33]
	v_mfma_f32_16x16x32_bf16 v[26:29], v[142:145], v[166:169], v[26:29]
	v_mfma_f32_16x16x32_bf16 v[14:17], v[134:137], v[198:201], v[14:17]
	v_mfma_f32_16x16x32_bf16 v[10:13], v[142:145], v[198:201], v[10:13]
	s_barrier
	s_setprio 0
	s_add_u32 s20, s6, 0xb0000
	s_addc_u32 s21, s7, 0
	s_add_i32 s50, s78, s56
	v_lshl_add_u64 v[130:131], s[20:21], 0, v[176:177]
	s_mov_b32 m0, s50
	s_nop 0
	global_load_lds_dwordx4 v[130:131], off
	v_lshl_add_u64 v[130:131], s[20:21], 0, v[180:181]
	s_add_i32 m0, s50, 0x2000
	s_nop 0
	global_load_lds_dwordx4 v[130:131], off
	s_waitcnt vmcnt(6)
	s_setprio 1
	s_barrier
	v_mfma_f32_16x16x32_bf16 v[54:57], v[202:205], v[146:149], v[54:57]
	v_mfma_f32_16x16x32_bf16 v[50:53], v[210:213], v[146:149], v[50:53]
	v_mfma_f32_16x16x32_bf16 v[38:41], v[202:205], v[154:157], v[38:41]
	v_mfma_f32_16x16x32_bf16 v[34:37], v[210:213], v[154:157], v[34:37]
	v_mfma_f32_16x16x32_bf16 v[22:25], v[202:205], v[162:165], v[22:25]
	v_mfma_f32_16x16x32_bf16 v[18:21], v[210:213], v[162:165], v[18:21]
	v_mfma_f32_16x16x32_bf16 v[6:9], v[202:205], v[194:197], v[6:9]
	v_mfma_f32_16x16x32_bf16 v[2:5], v[210:213], v[194:197], v[2:5]
	v_mfma_f32_16x16x32_bf16 v[54:57], v[206:209], v[150:153], v[54:57]
	v_mfma_f32_16x16x32_bf16 v[50:53], v[214:217], v[150:153], v[50:53]
	v_mfma_f32_16x16x32_bf16 v[38:41], v[206:209], v[158:161], v[38:41]
	v_mfma_f32_16x16x32_bf16 v[34:37], v[214:217], v[158:161], v[34:37]
	v_mfma_f32_16x16x32_bf16 v[22:25], v[206:209], v[166:169], v[22:25]
	v_mfma_f32_16x16x32_bf16 v[18:21], v[214:217], v[166:169], v[18:21]
	v_mfma_f32_16x16x32_bf16 v[6:9], v[206:209], v[198:201], v[6:9]
	v_mfma_f32_16x16x32_bf16 v[2:5], v[214:217], v[198:201], v[2:5]
	s_barrier
	s_setprio 0
	s_add_i32 s20, 0, 0x18000
	v_add_u32_e32 v142, s20, v240
	ds_read_b128 v[130:133], v142
	ds_read_b128 v[134:137], v142 offset:1024
	ds_read_b128 v[138:141], v142 offset:2048
	ds_read_b128 v[142:145], v142 offset:3072
	s_add_u32 s8, s8, 0xb0000
	s_addc_u32 s9, s9, 0
	s_mov_b32 m0, s69
	v_lshl_add_u64 v[202:203], s[8:9], 0, v[172:173]
	ds_read_b128 v[146:149], v242 offset:32768
	ds_read_b128 v[150:153], v242 offset:33792
	ds_read_b128 v[154:157], v242 offset:34816
	ds_read_b128 v[158:161], v242 offset:35840
	ds_read_b128 v[162:165], v242 offset:36864
	ds_read_b128 v[166:169], v242 offset:37888
	ds_read_b128 v[194:197], v242 offset:38912
	ds_read_b128 v[198:201], v242 offset:39936
	global_load_lds_dwordx4 v[202:203], off
	v_lshl_add_u64 v[202:203], s[8:9], 0, v[178:179]
	s_mov_b32 m0, s70
	s_nop 0
	global_load_lds_dwordx4 v[202:203], off
	s_waitcnt lgkmcnt(8)
	s_setprio 1
	s_barrier
	s_waitcnt lgkmcnt(0)
	v_mfma_f32_16x16x32_bf16 v[126:129], v[130:133], v[146:149], v[126:129]
	v_mfma_f32_16x16x32_bf16 v[122:125], v[138:141], v[146:149], v[122:125]
	v_mfma_f32_16x16x32_bf16 v[110:113], v[130:133], v[154:157], v[110:113]
	v_mfma_f32_16x16x32_bf16 v[106:109], v[138:141], v[154:157], v[106:109]
	v_mfma_f32_16x16x32_bf16 v[94:97], v[130:133], v[162:165], v[94:97]
	v_mfma_f32_16x16x32_bf16 v[90:93], v[138:141], v[162:165], v[90:93]
	v_mfma_f32_16x16x32_bf16 v[78:81], v[130:133], v[194:197], v[78:81]
	v_mfma_f32_16x16x32_bf16 v[74:77], v[138:141], v[194:197], v[74:77]
	v_mfma_f32_16x16x32_bf16 v[126:129], v[134:137], v[150:153], v[126:129]
	v_mfma_f32_16x16x32_bf16 v[122:125], v[142:145], v[150:153], v[122:125]
	v_mfma_f32_16x16x32_bf16 v[110:113], v[134:137], v[158:161], v[110:113]
	v_mfma_f32_16x16x32_bf16 v[106:109], v[142:145], v[158:161], v[106:109]
	v_mfma_f32_16x16x32_bf16 v[94:97], v[134:137], v[166:169], v[94:97]
	v_mfma_f32_16x16x32_bf16 v[90:93], v[142:145], v[166:169], v[90:93]
	v_mfma_f32_16x16x32_bf16 v[78:81], v[134:137], v[198:201], v[78:81]
	v_mfma_f32_16x16x32_bf16 v[74:77], v[142:145], v[198:201], v[74:77]
	s_barrier
	s_setprio 0
	s_add_i32 s8, 0, 0x1c000
	s_add_i32 s9, s20, s56
	v_add_u32_e32 v184, s8, v240
	v_lshl_add_u64 v[218:219], v[218:219], 0, s[16:17]
	s_mov_b32 m0, s9
	ds_read_b128 v[202:205], v184
	ds_read_b128 v[206:209], v184 offset:1024
	ds_read_b128 v[210:213], v184 offset:2048
	ds_read_b128 v[214:217], v184 offset:3072
	global_load_lds_dwordx4 v[218:219], off
	v_lshl_add_u64 v[218:219], v[220:221], 0, s[16:17]
	s_add_i32 m0, s9, 0x2000
	s_nop 0
	global_load_lds_dwordx4 v[218:219], off
	s_setprio 1
	s_barrier
	s_waitcnt lgkmcnt(0)
	v_mfma_f32_16x16x32_bf16 v[118:121], v[202:205], v[146:149], v[118:121]
	v_mfma_f32_16x16x32_bf16 v[114:117], v[210:213], v[146:149], v[114:117]
	v_mfma_f32_16x16x32_bf16 v[102:105], v[202:205], v[154:157], v[102:105]
	v_mfma_f32_16x16x32_bf16 v[98:101], v[210:213], v[154:157], v[98:101]
	v_mfma_f32_16x16x32_bf16 v[86:89], v[202:205], v[162:165], v[86:89]
	v_mfma_f32_16x16x32_bf16 v[82:85], v[210:213], v[162:165], v[82:85]
	v_mfma_f32_16x16x32_bf16 v[70:73], v[202:205], v[194:197], v[70:73]
	v_mfma_f32_16x16x32_bf16 v[66:69], v[210:213], v[194:197], v[66:69]
	v_mfma_f32_16x16x32_bf16 v[118:121], v[206:209], v[150:153], v[118:121]
	v_mfma_f32_16x16x32_bf16 v[114:117], v[214:217], v[150:153], v[114:117]
	v_mfma_f32_16x16x32_bf16 v[102:105], v[206:209], v[158:161], v[102:105]
	v_mfma_f32_16x16x32_bf16 v[98:101], v[214:217], v[158:161], v[98:101]
	v_mfma_f32_16x16x32_bf16 v[86:89], v[206:209], v[166:169], v[86:89]
	v_mfma_f32_16x16x32_bf16 v[82:85], v[214:217], v[166:169], v[82:85]
	v_mfma_f32_16x16x32_bf16 v[70:73], v[206:209], v[198:201], v[70:73]
	v_mfma_f32_16x16x32_bf16 v[66:69], v[214:217], v[198:201], v[66:69]
	s_barrier
	s_setprio 0
	s_mov_b32 m0, s74
	v_lshl_add_u64 v[218:219], v[222:223], 0, s[16:17]
	ds_read_b128 v[146:149], v242 offset:49152
	ds_read_b128 v[150:153], v242 offset:50176
	ds_read_b128 v[154:157], v242 offset:51200
	ds_read_b128 v[158:161], v242 offset:52224
	ds_read_b128 v[162:165], v242 offset:53248
	ds_read_b128 v[166:169], v242 offset:54272
	ds_read_b128 v[194:197], v242 offset:55296
	ds_read_b128 v[198:201], v242 offset:56320
	global_load_lds_dwordx4 v[218:219], off
	v_lshl_add_u64 v[218:219], v[224:225], 0, s[16:17]
	s_mov_b32 m0, s75
	s_nop 0
	global_load_lds_dwordx4 v[218:219], off
	s_setprio 1
	s_barrier
	s_waitcnt lgkmcnt(0)
	v_mfma_f32_16x16x32_bf16 v[62:65], v[130:133], v[146:149], v[62:65]
	v_mfma_f32_16x16x32_bf16 v[58:61], v[138:141], v[146:149], v[58:61]
	v_mfma_f32_16x16x32_bf16 v[46:49], v[130:133], v[154:157], v[46:49]
	v_mfma_f32_16x16x32_bf16 v[42:45], v[138:141], v[154:157], v[42:45]
	v_mfma_f32_16x16x32_bf16 v[30:33], v[130:133], v[162:165], v[30:33]
	v_mfma_f32_16x16x32_bf16 v[26:29], v[138:141], v[162:165], v[26:29]
	v_mfma_f32_16x16x32_bf16 v[14:17], v[130:133], v[194:197], v[14:17]
	v_mfma_f32_16x16x32_bf16 v[10:13], v[138:141], v[194:197], v[10:13]
	v_mfma_f32_16x16x32_bf16 v[62:65], v[134:137], v[150:153], v[62:65]
	v_mfma_f32_16x16x32_bf16 v[58:61], v[142:145], v[150:153], v[58:61]
	v_mfma_f32_16x16x32_bf16 v[46:49], v[134:137], v[158:161], v[46:49]
	v_mfma_f32_16x16x32_bf16 v[42:45], v[142:145], v[158:161], v[42:45]
	v_mfma_f32_16x16x32_bf16 v[30:33], v[134:137], v[166:169], v[30:33]
	v_mfma_f32_16x16x32_bf16 v[26:29], v[142:145], v[166:169], v[26:29]
	v_mfma_f32_16x16x32_bf16 v[14:17], v[134:137], v[198:201], v[14:17]
	v_mfma_f32_16x16x32_bf16 v[10:13], v[142:145], v[198:201], v[10:13]
	s_barrier
	s_setprio 0
	s_add_u32 s6, s6, 0xb0080
	s_addc_u32 s7, s7, 0
	s_add_i32 s8, s8, s56
	v_lshl_add_u64 v[130:131], s[6:7], 0, v[176:177]
	s_mov_b32 m0, s8
	s_nop 0
	global_load_lds_dwordx4 v[130:131], off
	v_lshl_add_u64 v[130:131], s[6:7], 0, v[180:181]
	s_add_i32 m0, s8, 0x2000
	s_nop 0
	global_load_lds_dwordx4 v[130:131], off
	s_waitcnt vmcnt(6)
	s_setprio 1
	s_barrier
	v_mfma_f32_16x16x32_bf16 v[54:57], v[202:205], v[146:149], v[54:57]
	v_mfma_f32_16x16x32_bf16 v[50:53], v[210:213], v[146:149], v[50:53]
	v_mfma_f32_16x16x32_bf16 v[38:41], v[202:205], v[154:157], v[38:41]
	v_mfma_f32_16x16x32_bf16 v[34:37], v[210:213], v[154:157], v[34:37]
	v_mfma_f32_16x16x32_bf16 v[22:25], v[202:205], v[162:165], v[22:25]
	v_mfma_f32_16x16x32_bf16 v[18:21], v[210:213], v[162:165], v[18:21]
	v_mfma_f32_16x16x32_bf16 v[6:9], v[202:205], v[194:197], v[6:9]
	v_mfma_f32_16x16x32_bf16 v[2:5], v[210:213], v[194:197], v[2:5]
	v_mfma_f32_16x16x32_bf16 v[54:57], v[206:209], v[150:153], v[54:57]
	v_mfma_f32_16x16x32_bf16 v[50:53], v[214:217], v[150:153], v[50:53]
	v_mfma_f32_16x16x32_bf16 v[38:41], v[206:209], v[158:161], v[38:41]
	v_mfma_f32_16x16x32_bf16 v[34:37], v[214:217], v[158:161], v[34:37]
	v_mfma_f32_16x16x32_bf16 v[22:25], v[206:209], v[166:169], v[22:25]
	v_mfma_f32_16x16x32_bf16 v[18:21], v[214:217], v[166:169], v[18:21]
	v_mfma_f32_16x16x32_bf16 v[6:9], v[206:209], v[198:201], v[6:9]
	v_mfma_f32_16x16x32_bf16 v[2:5], v[214:217], v[198:201], v[2:5]
	s_add_i32 s49, s49, 2
	s_add_u32 s0, s0, 0x100
	s_addc_u32 s1, s1, 0
	s_add_u32 s10, s10, 0x100
	s_addc_u32 s11, s11, 0
	s_cmp_gt_u32 s49, 41
	s_cbranch_scc0 .Ldfr_p3_r
	s_cmpk_gt_u32 s53, 0xff
	s_cbranch_scc1 .Ldfr_p3_b
	s_barrier
.Ldfr_p3_b:
	s_setprio 0
	s_min_i32 s0, s48, 0x80
	s_ashr_i32 s0, s0, 3
	s_mul_hi_i32 s1, s0, 0x9000
	s_mul_i32 s0, s0, 0x9000
	s_add_u32 s6, s58, s0
	s_addc_u32 s7, s59, s1
	s_lshl_b32 s50, s34, 8
	s_ashr_i32 s51, s50, 31
	s_lshl_b64 s[0:1], s[50:51], 2
	s_add_u32 s0, s6, s0
	s_addc_u32 s1, s7, s1
	v_lshlrev_b32_e32 v184, 2, v182
	v_lshl_add_u64 v[130:131], s[0:1], 0, v[184:185]
	s_mov_b64 s[0:1], 0x2000
	v_lshl_add_u64 v[132:133], v[130:131], 0, s[0:1]
	s_movk_i32 s0, 0x2000
	v_add_co_u32_e32 v134, vcc, s0, v130
	s_mov_b64 s[0:1], 0x2200
	s_nop 0
	v_addc_co_u32_e32 v135, vcc, 0, v131, vcc
	global_load_dwordx4 v[194:197], v[134:135], off
	global_load_dwordx4 v[220:223], v[132:133], off offset:16
	v_lshl_add_u64 v[132:133], v[130:131], 0, s[0:1]
	s_mov_b64 s[0:1], 0x4000
	global_load_dwordx4 v[198:201], v[134:135], off offset:512
	global_load_dwordx4 v[224:227], v[132:133], off offset:16
	v_lshl_add_u64 v[132:133], v[130:131], 0, s[0:1]
	s_movk_i32 s0, 0x4000
	v_add_co_u32_e32 v134, vcc, s0, v130
	s_mov_b64 s[0:1], 0x4200
	v_lshl_add_u32 v212, s48, 8, v239
	v_addc_co_u32_e32 v135, vcc, 0, v131, vcc
	v_lshl_add_u64 v[130:131], v[130:131], 0, s[0:1]
	global_load_dwordx4 v[154:157], v[134:135], off
	global_load_dwordx4 v[162:165], v[132:133], off offset:16
	global_load_dwordx4 v[158:161], v[134:135], off offset:512
	global_load_dwordx4 v[166:169], v[130:131], off offset:16
	v_add_u32_e32 v130, 0xffff8000, v212
	v_ashrrev_i32_e32 v213, 31, v212
	v_cmp_gt_i32_e64 s[6:7], s76, v212
	v_mov_b32_e32 v134, s72
	v_mov_b32_e32 v135, s29
	v_cndmask_b32_e64 v131, 0, v213, s[6:7]
	v_cndmask_b32_e64 v130, v130, v212, s[6:7]
	v_mov_b32_e32 v136, s71
	v_mov_b32_e32 v137, s28
	v_cndmask_b32_e64 v133, v134, v135, s[6:7]
	v_cndmask_b32_e64 v132, v136, v137, s[6:7]
	v_lshlrev_b64 v[130:131], 11, v[130:131]
	v_lshl_add_u64 v[130:131], v[132:133], 0, v[130:131]
	s_lshl_b64 s[0:1], s[50:51], 1
	v_lshl_add_u64 v[130:131], v[130:131], 0, s[0:1]
	v_lshlrev_b32_e32 v184, 1, v182
	v_lshl_add_u64 v[130:131], v[130:131], 0, v[184:185]
	v_or_b32_e32 v218, 16, v212
	global_load_dwordx4 v[246:249], v[130:131], off
	global_load_dwordx4 v[250:253], v[130:131], off offset:256
	v_add_u32_e32 v130, 0xffff8010, v212
	v_ashrrev_i32_e32 v219, 31, v218
	v_cmp_gt_i32_e64 s[8:9], s76, v218
	v_or_b32_e32 v216, 32, v212
	v_ashrrev_i32_e32 v217, 31, v216
	v_cndmask_b32_e64 v131, 0, v219, s[8:9]
	v_cndmask_b32_e64 v130, v130, v218, s[8:9]
	v_cndmask_b32_e64 v133, v134, v135, s[8:9]
	v_cndmask_b32_e64 v132, v136, v137, s[8:9]
	v_lshlrev_b64 v[130:131], 11, v[130:131]
	v_lshl_add_u64 v[130:131], v[132:133], 0, v[130:131]
	v_lshl_add_u64 v[130:131], v[130:131], 0, s[0:1]
	v_lshl_add_u64 v[130:131], v[130:131], 0, v[184:185]
	global_load_dwordx4 v[150:153], v[130:131], off
	global_load_dwordx4 v[146:149], v[130:131], off offset:256
	v_add_u32_e32 v130, 0xffff8020, v212
	v_cmp_gt_i32_e64 s[10:11], s76, v216
	v_or_b32_e32 v214, 48, v212
	v_ashrrev_i32_e32 v215, 31, v214
	v_cndmask_b32_e64 v131, 0, v217, s[10:11]
	v_cndmask_b32_e64 v130, v130, v216, s[10:11]
	v_cndmask_b32_e64 v133, v134, v135, s[10:11]
	v_cndmask_b32_e64 v132, v136, v137, s[10:11]
	v_lshlrev_b64 v[130:131], 11, v[130:131]
	v_lshl_add_u64 v[130:131], v[132:133], 0, v[130:131]
	v_lshl_add_u64 v[130:131], v[130:131], 0, s[0:1]
	v_lshl_add_u64 v[130:131], v[130:131], 0, v[184:185]
	global_load_dwordx4 v[142:145], v[130:131], off
	global_load_dwordx4 v[138:141], v[130:131], off offset:256
	v_add_u32_e32 v130, 0xffff8030, v212
	v_cmp_gt_i32_e32 vcc, s76, v214
	s_waitcnt vmcnt(0)
	v_pk_mul_f32 v[210:211], v[194:195], 0.5 op_sel_hi:[1,0]
	v_cndmask_b32_e32 v131, 0, v215, vcc
	v_cndmask_b32_e32 v130, v130, v214, vcc
	v_cndmask_b32_e32 v133, v134, v135, vcc
	v_cndmask_b32_e32 v132, v136, v137, vcc
	v_lshlrev_b64 v[130:131], 11, v[130:131]
	v_lshl_add_u64 v[130:131], v[132:133], 0, v[130:131]
	v_lshl_add_u64 v[130:131], v[130:131], 0, s[0:1]
	v_lshl_add_u64 v[130:131], v[130:131], 0, v[184:185]
	global_load_dwordx4 v[134:137], v[130:131], off
	s_nop 0
	global_load_dwordx4 v[130:133], v[130:131], off offset:256
	v_pk_mul_f32 v[202:203], v[220:221], 0.5 op_sel_hi:[1,0]
	v_pk_mul_f32 v[208:209], v[198:199], 0.5 op_sel_hi:[1,0]
	v_pk_mul_f32 v[206:207], v[196:197], 0.5 op_sel_hi:[1,0]
	v_pk_mul_f32 v[204:205], v[200:201], 0.5 op_sel_hi:[1,0]
	v_pk_mul_f32 v[198:199], v[222:223], 0.5 op_sel_hi:[1,0]
	v_pk_mul_f32 v[200:201], v[224:225], 0.5 op_sel_hi:[1,0]
	v_pk_mul_f32 v[196:197], v[226:227], 0.5 op_sel_hi:[1,0]
	v_mov_b32_e32 v195, s51
	v_or_b32_e32 v194, s50, v182
	v_lshlrev_b32_e32 v220, 16, v246
	v_and_b32_e32 v221, 0xffff0000, v246
	v_pk_fma_f32 v[220:221], v[126:127], v[210:211], v[220:221]
	v_lshlrev_b32_e32 v126, 16, v250
	v_and_b32_e32 v127, 0xffff0000, v250
	v_pk_fma_f32 v[118:119], v[118:119], v[208:209], v[126:127]
	v_lshlrev_b32_e32 v126, 16, v247
	v_and_b32_e32 v127, 0xffff0000, v247
	v_pk_fma_f32 v[222:223], v[128:129], v[206:207], v[126:127]
	v_lshlrev_b32_e32 v126, 16, v251
	v_and_b32_e32 v127, 0xffff0000, v251
	v_pk_fma_f32 v[120:121], v[120:121], v[204:205], v[126:127]
	v_lshlrev_b32_e32 v126, 16, v248
	v_and_b32_e32 v127, 0xffff0000, v248
	v_pk_fma_f32 v[224:225], v[122:123], v[202:203], v[126:127]
	v_lshlrev_b32_e32 v122, 16, v252
	v_and_b32_e32 v123, 0xffff0000, v252
	v_pk_fma_f32 v[114:115], v[114:115], v[200:201], v[122:123]
	v_lshlrev_b32_e32 v122, 16, v249
	v_and_b32_e32 v123, 0xffff0000, v249
	v_pk_fma_f32 v[226:227], v[124:125], v[198:199], v[122:123]
	v_lshlrev_b32_e32 v122, 16, v253
	v_and_b32_e32 v123, 0xffff0000, v253
	v_pk_fma_f32 v[116:117], v[116:117], v[196:197], v[122:123]
	v_lshlrev_b64 v[122:123], 10, v[212:213]
	v_lshl_add_u64 v[228:229], v[122:123], 0, v[194:195]
	s_and_saveexec_b64 s[0:1], s[6:7]
	s_cbranch_execz .LBB0_825
	v_lshl_add_u64 v[126:127], v[228:229], 1, s[28:29]
	v_cvt_pk_bf16_f32 v122, v220, v221
	v_cvt_pk_bf16_f32 v123, v222, v223
	v_cvt_pk_bf16_f32 v124, v224, v225
	v_cvt_pk_bf16_f32 v125, v226, v227
	global_store_dwordx4 v[126:127], v[122:125], off nt
	s_nop 1
	v_cvt_pk_bf16_f32 v122, v118, v119
	v_cvt_pk_bf16_f32 v123, v120, v121
	v_cvt_pk_bf16_f32 v124, v114, v115
	v_cvt_pk_bf16_f32 v125, v116, v117
	global_store_dwordx4 v[126:127], v[122:125], off offset:256 nt

.LBB0_868:
	s_add_u32 s12, s12, 0xb0080
	s_addc_u32 s13, s13, 0
	s_add_u32 s78, s14, 0x100
	s_addc_u32 s79, s15, 0
	s_mov_b32 s87, -2
	ds_read_b128 v[146:149], v142
	ds_read_b128 v[150:153], v142 offset:1024
	ds_read_b128 v[154:157], v142 offset:2048
	ds_read_b128 v[158:161], v142 offset:3072
	s_add_u32 s14, s12, 0xfff50080
	s_addc_u32 s15, s13, -1
	s_cmp_eq_u32 s87, 18
	s_cselect_b32 s17, s1, s15
	s_cselect_b32 s16, s0, s14
	s_cselect_b32 s15, s7, s79
	s_cselect_b32 s14, s6, s78
	s_mov_b32 m0, s68
	v_lshl_add_u64 v[208:209], s[12:13], 0, v[132:133]
	ds_read_b128 v[162:165], v143
	ds_read_b128 v[166:169], v143 offset:1024
	ds_read_b128 v[184:187], v143 offset:2048
	ds_read_b128 v[188:191], v143 offset:3072
	ds_read_b128 v[192:195], v143 offset:4096
	ds_read_b128 v[196:199], v143 offset:5120
	ds_read_b128 v[200:203], v143 offset:6144
	ds_read_b128 v[204:207], v143 offset:7168
	global_load_lds_dwordx4 v[208:209], off
	v_lshl_add_u64 v[208:209], s[12:13], 0, v[134:135]
	s_mov_b32 m0, s69
	s_nop 0
	global_load_lds_dwordx4 v[208:209], off
	s_waitcnt lgkmcnt(8)
	s_setprio 1
	s_barrier
	s_waitcnt lgkmcnt(0)
	v_mfma_f32_16x16x32_bf16 v[126:129], v[146:149], v[162:165], 0
	v_mfma_f32_16x16x32_bf16 v[122:125], v[154:157], v[162:165], 0
	v_mfma_f32_16x16x32_bf16 v[118:121], v[146:149], v[184:187], 0
	v_mfma_f32_16x16x32_bf16 v[114:117], v[154:157], v[184:187], 0
	v_mfma_f32_16x16x32_bf16 v[102:105], v[146:149], v[192:195], 0
	v_mfma_f32_16x16x32_bf16 v[98:101], v[154:157], v[192:195], 0
	v_mfma_f32_16x16x32_bf16 v[86:89], v[146:149], v[200:203], 0
	v_mfma_f32_16x16x32_bf16 v[82:85], v[154:157], v[200:203], 0
	v_mfma_f32_16x16x32_bf16 v[126:129], v[150:153], v[166:169], v[126:129]
	v_mfma_f32_16x16x32_bf16 v[122:125], v[158:161], v[166:169], v[122:125]
	v_mfma_f32_16x16x32_bf16 v[118:121], v[150:153], v[188:191], v[118:121]
	v_mfma_f32_16x16x32_bf16 v[114:117], v[158:161], v[188:191], v[114:117]
	v_mfma_f32_16x16x32_bf16 v[102:105], v[150:153], v[196:199], v[102:105]
	v_mfma_f32_16x16x32_bf16 v[98:101], v[158:161], v[196:199], v[98:101]
	v_mfma_f32_16x16x32_bf16 v[86:89], v[150:153], v[204:207], v[86:89]
	v_mfma_f32_16x16x32_bf16 v[82:85], v[158:161], v[204:207], v[82:85]
	s_barrier
	s_setprio 0
	s_mov_b32 m0, s70
	v_lshl_add_u64 v[224:225], s[14:15], 0, v[176:177]
	ds_read_b128 v[208:211], v144
	ds_read_b128 v[212:215], v144 offset:1024
	ds_read_b128 v[216:219], v144 offset:2048
	ds_read_b128 v[220:223], v144 offset:3072
	global_load_lds_dwordx4 v[224:225], off
	v_lshl_add_u64 v[226:227], s[14:15], 0, v[180:181]
	s_mov_b32 m0, s71
	s_nop 0
	global_load_lds_dwordx4 v[226:227], off
	s_setprio 1
	s_barrier
	s_waitcnt lgkmcnt(0)
	v_mfma_f32_16x16x32_bf16 v[110:113], v[208:211], v[162:165], 0
	v_mfma_f32_16x16x32_bf16 v[106:109], v[216:219], v[162:165], 0
	v_mfma_f32_16x16x32_bf16 v[94:97], v[208:211], v[184:187], 0
	v_mfma_f32_16x16x32_bf16 v[90:93], v[216:219], v[184:187], 0
	v_mfma_f32_16x16x32_bf16 v[78:81], v[208:211], v[192:195], 0
	v_mfma_f32_16x16x32_bf16 v[74:77], v[216:219], v[192:195], 0
	v_mfma_f32_16x16x32_bf16 v[70:73], v[208:211], v[200:203], 0
	v_mfma_f32_16x16x32_bf16 v[66:69], v[216:219], v[200:203], 0
	v_mfma_f32_16x16x32_bf16 v[110:113], v[212:215], v[166:169], v[110:113]
	v_mfma_f32_16x16x32_bf16 v[106:109], v[220:223], v[166:169], v[106:109]
	v_mfma_f32_16x16x32_bf16 v[94:97], v[212:215], v[188:191], v[94:97]
	v_mfma_f32_16x16x32_bf16 v[90:93], v[220:223], v[188:191], v[90:93]
	v_mfma_f32_16x16x32_bf16 v[78:81], v[212:215], v[196:199], v[78:81]
	v_mfma_f32_16x16x32_bf16 v[74:77], v[220:223], v[196:199], v[74:77]
	v_mfma_f32_16x16x32_bf16 v[70:73], v[212:215], v[204:207], v[70:73]
	v_mfma_f32_16x16x32_bf16 v[66:69], v[220:223], v[204:207], v[66:69]
	s_barrier
	s_setprio 0
	s_mov_b32 m0, s40
	v_lshl_add_u64 v[228:229], s[16:17], 0, v[172:173]
	ds_read_b128 v[162:165], v143 offset:16384
	ds_read_b128 v[166:169], v143 offset:17408
	ds_read_b128 v[184:187], v143 offset:18432
	ds_read_b128 v[188:191], v143 offset:19456
	ds_read_b128 v[192:195], v143 offset:20480
	ds_read_b128 v[196:199], v143 offset:21504
	ds_read_b128 v[200:203], v143 offset:22528
	ds_read_b128 v[204:207], v143 offset:23552
	global_load_lds_dwordx4 v[228:229], off
	v_lshl_add_u64 v[234:235], s[16:17], 0, v[178:179]
	s_mov_b32 m0, s41
	s_nop 0
	global_load_lds_dwordx4 v[234:235], off
	s_setprio 1
	s_barrier
	s_waitcnt lgkmcnt(0)
	v_mfma_f32_16x16x32_bf16 v[62:65], v[146:149], v[162:165], 0
	v_mfma_f32_16x16x32_bf16 v[58:61], v[154:157], v[162:165], 0
	v_mfma_f32_16x16x32_bf16 v[54:57], v[146:149], v[184:187], 0
	v_mfma_f32_16x16x32_bf16 v[50:53], v[154:157], v[184:187], 0
	v_mfma_f32_16x16x32_bf16 v[38:41], v[146:149], v[192:195], 0
	v_mfma_f32_16x16x32_bf16 v[34:37], v[154:157], v[192:195], 0
	v_mfma_f32_16x16x32_bf16 v[22:25], v[146:149], v[200:203], 0
	v_mfma_f32_16x16x32_bf16 v[18:21], v[154:157], v[200:203], 0
	v_mfma_f32_16x16x32_bf16 v[62:65], v[150:153], v[166:169], v[62:65]
	v_mfma_f32_16x16x32_bf16 v[58:61], v[158:161], v[166:169], v[58:61]
	v_mfma_f32_16x16x32_bf16 v[54:57], v[150:153], v[188:191], v[54:57]
	v_mfma_f32_16x16x32_bf16 v[50:53], v[158:161], v[188:191], v[50:53]
	v_mfma_f32_16x16x32_bf16 v[38:41], v[150:153], v[196:199], v[38:41]
	v_mfma_f32_16x16x32_bf16 v[34:37], v[158:161], v[196:199], v[34:37]
	v_mfma_f32_16x16x32_bf16 v[22:25], v[150:153], v[204:207], v[22:25]
	v_mfma_f32_16x16x32_bf16 v[18:21], v[158:161], v[204:207], v[18:21]
	s_barrier
	s_setprio 0
	s_add_u32 s20, s14, 0xb0000
	s_addc_u32 s21, s15, 0
	s_add_i32 s60, s56, s35
	v_lshl_add_u64 v[146:147], s[20:21], 0, v[176:177]
	s_mov_b32 m0, s60
	s_nop 0
	global_load_lds_dwordx4 v[146:147], off
	v_lshl_add_u64 v[146:147], s[20:21], 0, v[180:181]
	s_add_i32 m0, s60, 0x2000
	s_nop 0
	global_load_lds_dwordx4 v[146:147], off
	s_waitcnt vmcnt(6)
	s_setprio 1
	s_barrier
	v_mfma_f32_16x16x32_bf16 v[46:49], v[208:211], v[162:165], 0
	v_mfma_f32_16x16x32_bf16 v[42:45], v[216:219], v[162:165], 0
	v_mfma_f32_16x16x32_bf16 v[30:33], v[208:211], v[184:187], 0
	v_mfma_f32_16x16x32_bf16 v[26:29], v[216:219], v[184:187], 0
	v_mfma_f32_16x16x32_bf16 v[14:17], v[208:211], v[192:195], 0
	v_mfma_f32_16x16x32_bf16 v[10:13], v[216:219], v[192:195], 0
	v_mfma_f32_16x16x32_bf16 v[6:9], v[208:211], v[200:203], 0
	v_mfma_f32_16x16x32_bf16 v[2:5], v[216:219], v[200:203], 0
	v_mfma_f32_16x16x32_bf16 v[46:49], v[212:215], v[166:169], v[46:49]
	v_mfma_f32_16x16x32_bf16 v[42:45], v[220:223], v[166:169], v[42:45]
	v_mfma_f32_16x16x32_bf16 v[30:33], v[212:215], v[188:191], v[30:33]
	v_mfma_f32_16x16x32_bf16 v[26:29], v[220:223], v[188:191], v[26:29]
	v_mfma_f32_16x16x32_bf16 v[14:17], v[212:215], v[196:199], v[14:17]
	v_mfma_f32_16x16x32_bf16 v[10:13], v[220:223], v[196:199], v[10:13]
	v_mfma_f32_16x16x32_bf16 v[6:9], v[212:215], v[204:207], v[6:9]
	v_mfma_f32_16x16x32_bf16 v[2:5], v[220:223], v[204:207], v[2:5]
	s_barrier
	s_setprio 0
	s_add_i32 s20, 0, 0x18000
	v_add_u32_e32 v145, s20, v141
	ds_read_b128 v[146:149], v145
	ds_read_b128 v[150:153], v145 offset:1024
	ds_read_b128 v[154:157], v145 offset:2048
	ds_read_b128 v[158:161], v145 offset:3072
	s_add_u32 s16, s16, 0xb0000
	s_addc_u32 s17, s17, 0
	s_mov_b32 m0, s48
	v_lshl_add_u64 v[208:209], s[16:17], 0, v[172:173]
	ds_read_b128 v[162:165], v143 offset:32768
	ds_read_b128 v[166:169], v143 offset:33792
	ds_read_b128 v[184:187], v143 offset:34816
	ds_read_b128 v[188:191], v143 offset:35840
	ds_read_b128 v[192:195], v143 offset:36864
	ds_read_b128 v[196:199], v143 offset:37888
	ds_read_b128 v[200:203], v143 offset:38912
	ds_read_b128 v[204:207], v143 offset:39936
	global_load_lds_dwordx4 v[208:209], off
	v_lshl_add_u64 v[208:209], s[16:17], 0, v[178:179]
	s_mov_b32 m0, s49
	s_nop 0
	global_load_lds_dwordx4 v[208:209], off
	s_waitcnt lgkmcnt(8)
	s_setprio 1
	s_barrier
	s_waitcnt lgkmcnt(0)
	v_mfma_f32_16x16x32_bf16 v[126:129], v[146:149], v[162:165], v[126:129]
	v_mfma_f32_16x16x32_bf16 v[122:125], v[154:157], v[162:165], v[122:125]
	v_mfma_f32_16x16x32_bf16 v[118:121], v[146:149], v[184:187], v[118:121]
	v_mfma_f32_16x16x32_bf16 v[114:117], v[154:157], v[184:187], v[114:117]
	v_mfma_f32_16x16x32_bf16 v[102:105], v[146:149], v[192:195], v[102:105]
	v_mfma_f32_16x16x32_bf16 v[98:101], v[154:157], v[192:195], v[98:101]
	v_mfma_f32_16x16x32_bf16 v[86:89], v[146:149], v[200:203], v[86:89]
	v_mfma_f32_16x16x32_bf16 v[82:85], v[154:157], v[200:203], v[82:85]
	v_mfma_f32_16x16x32_bf16 v[126:129], v[150:153], v[166:169], v[126:129]
	v_mfma_f32_16x16x32_bf16 v[122:125], v[158:161], v[166:169], v[122:125]
	v_mfma_f32_16x16x32_bf16 v[118:121], v[150:153], v[188:191], v[118:121]
	v_mfma_f32_16x16x32_bf16 v[114:117], v[158:161], v[188:191], v[114:117]
	v_mfma_f32_16x16x32_bf16 v[102:105], v[150:153], v[196:199], v[102:105]
	v_mfma_f32_16x16x32_bf16 v[98:101], v[158:161], v[196:199], v[98:101]
	v_mfma_f32_16x16x32_bf16 v[86:89], v[150:153], v[204:207], v[86:89]
	v_mfma_f32_16x16x32_bf16 v[82:85], v[158:161], v[204:207], v[82:85]
	s_barrier
	s_setprio 0
	s_add_i32 s16, 0, 0x1c000
	s_add_i32 s17, s20, s35
	v_add_u32_e32 v145, s16, v141
	v_lshl_add_u64 v[224:225], v[224:225], 0, s[8:9]
	s_mov_b32 m0, s17
	ds_read_b128 v[208:211], v145
	ds_read_b128 v[212:215], v145 offset:1024
	ds_read_b128 v[216:219], v145 offset:2048
	ds_read_b128 v[220:223], v145 offset:3072
	global_load_lds_dwordx4 v[224:225], off
	v_lshl_add_u64 v[224:225], v[226:227], 0, s[8:9]
	s_add_i32 m0, s17, 0x2000
	s_nop 0
	global_load_lds_dwordx4 v[224:225], off
	s_setprio 1
	s_barrier
	s_waitcnt lgkmcnt(0)
	v_mfma_f32_16x16x32_bf16 v[110:113], v[208:211], v[162:165], v[110:113]
	v_mfma_f32_16x16x32_bf16 v[106:109], v[216:219], v[162:165], v[106:109]
	v_mfma_f32_16x16x32_bf16 v[94:97], v[208:211], v[184:187], v[94:97]
	v_mfma_f32_16x16x32_bf16 v[90:93], v[216:219], v[184:187], v[90:93]
	v_mfma_f32_16x16x32_bf16 v[78:81], v[208:211], v[192:195], v[78:81]
	v_mfma_f32_16x16x32_bf16 v[74:77], v[216:219], v[192:195], v[74:77]
	v_mfma_f32_16x16x32_bf16 v[70:73], v[208:211], v[200:203], v[70:73]
	v_mfma_f32_16x16x32_bf16 v[66:69], v[216:219], v[200:203], v[66:69]
	v_mfma_f32_16x16x32_bf16 v[110:113], v[212:215], v[166:169], v[110:113]
	v_mfma_f32_16x16x32_bf16 v[106:109], v[220:223], v[166:169], v[106:109]
	v_mfma_f32_16x16x32_bf16 v[94:97], v[212:215], v[188:191], v[94:97]
	v_mfma_f32_16x16x32_bf16 v[90:93], v[220:223], v[188:191], v[90:93]
	v_mfma_f32_16x16x32_bf16 v[78:81], v[212:215], v[196:199], v[78:81]
	v_mfma_f32_16x16x32_bf16 v[74:77], v[220:223], v[196:199], v[74:77]
	v_mfma_f32_16x16x32_bf16 v[70:73], v[212:215], v[204:207], v[70:73]
	v_mfma_f32_16x16x32_bf16 v[66:69], v[220:223], v[204:207], v[66:69]
	s_barrier
	s_setprio 0
	s_mov_b32 m0, s54
	v_lshl_add_u64 v[224:225], v[228:229], 0, s[8:9]
	ds_read_b128 v[162:165], v143 offset:49152
	ds_read_b128 v[166:169], v143 offset:50176
	ds_read_b128 v[184:187], v143 offset:51200
	ds_read_b128 v[188:191], v143 offset:52224
	ds_read_b128 v[192:195], v143 offset:53248
	ds_read_b128 v[196:199], v143 offset:54272
	ds_read_b128 v[200:203], v143 offset:55296
	ds_read_b128 v[204:207], v143 offset:56320
	global_load_lds_dwordx4 v[224:225], off
	v_lshl_add_u64 v[224:225], v[234:235], 0, s[8:9]
	s_mov_b32 m0, s55
	s_nop 0
	global_load_lds_dwordx4 v[224:225], off
	s_setprio 1
	s_barrier
	s_waitcnt lgkmcnt(0)
	v_mfma_f32_16x16x32_bf16 v[62:65], v[146:149], v[162:165], v[62:65]
	v_mfma_f32_16x16x32_bf16 v[58:61], v[154:157], v[162:165], v[58:61]
	v_mfma_f32_16x16x32_bf16 v[54:57], v[146:149], v[184:187], v[54:57]
	v_mfma_f32_16x16x32_bf16 v[50:53], v[154:157], v[184:187], v[50:53]
	v_mfma_f32_16x16x32_bf16 v[38:41], v[146:149], v[192:195], v[38:41]
	v_mfma_f32_16x16x32_bf16 v[34:37], v[154:157], v[192:195], v[34:37]
	v_mfma_f32_16x16x32_bf16 v[22:25], v[146:149], v[200:203], v[22:25]
	v_mfma_f32_16x16x32_bf16 v[18:21], v[154:157], v[200:203], v[18:21]
	v_mfma_f32_16x16x32_bf16 v[62:65], v[150:153], v[166:169], v[62:65]
	v_mfma_f32_16x16x32_bf16 v[58:61], v[158:161], v[166:169], v[58:61]
	v_mfma_f32_16x16x32_bf16 v[54:57], v[150:153], v[188:191], v[54:57]
	v_mfma_f32_16x16x32_bf16 v[50:53], v[158:161], v[188:191], v[50:53]
	v_mfma_f32_16x16x32_bf16 v[38:41], v[150:153], v[196:199], v[38:41]
	v_mfma_f32_16x16x32_bf16 v[34:37], v[158:161], v[196:199], v[34:37]
	v_mfma_f32_16x16x32_bf16 v[22:25], v[150:153], v[204:207], v[22:25]
	v_mfma_f32_16x16x32_bf16 v[18:21], v[158:161], v[204:207], v[18:21]
	s_barrier
	s_setprio 0
	s_add_u32 s14, s14, 0xb0080
	s_addc_u32 s15, s15, 0
	s_add_i32 s16, s16, s35
	v_lshl_add_u64 v[146:147], s[14:15], 0, v[176:177]
	s_mov_b32 m0, s16
	s_nop 0
	global_load_lds_dwordx4 v[146:147], off
	v_lshl_add_u64 v[146:147], s[14:15], 0, v[180:181]
	s_add_i32 m0, s16, 0x2000
	s_nop 0
	global_load_lds_dwordx4 v[146:147], off
	s_waitcnt vmcnt(6)
	s_setprio 1
	s_barrier
	v_mfma_f32_16x16x32_bf16 v[46:49], v[208:211], v[162:165], v[46:49]
	v_mfma_f32_16x16x32_bf16 v[42:45], v[216:219], v[162:165], v[42:45]
	v_mfma_f32_16x16x32_bf16 v[30:33], v[208:211], v[184:187], v[30:33]
	v_mfma_f32_16x16x32_bf16 v[26:29], v[216:219], v[184:187], v[26:29]
	v_mfma_f32_16x16x32_bf16 v[14:17], v[208:211], v[192:195], v[14:17]
	v_mfma_f32_16x16x32_bf16 v[10:13], v[216:219], v[192:195], v[10:13]
	v_mfma_f32_16x16x32_bf16 v[6:9], v[208:211], v[200:203], v[6:9]
	v_mfma_f32_16x16x32_bf16 v[2:5], v[216:219], v[200:203], v[2:5]
	v_mfma_f32_16x16x32_bf16 v[46:49], v[212:215], v[166:169], v[46:49]
	v_mfma_f32_16x16x32_bf16 v[42:45], v[220:223], v[166:169], v[42:45]
	v_mfma_f32_16x16x32_bf16 v[30:33], v[212:215], v[188:191], v[30:33]
	v_mfma_f32_16x16x32_bf16 v[26:29], v[220:223], v[188:191], v[26:29]
	v_mfma_f32_16x16x32_bf16 v[14:17], v[212:215], v[196:199], v[14:17]
	v_mfma_f32_16x16x32_bf16 v[10:13], v[220:223], v[196:199], v[10:13]
	v_mfma_f32_16x16x32_bf16 v[6:9], v[212:215], v[204:207], v[6:9]
	v_mfma_f32_16x16x32_bf16 v[2:5], v[220:223], v[204:207], v[2:5]
	s_add_i32 s87, s87, 2
	s_add_u32 s12, s12, 0x100
	s_addc_u32 s13, s13, 0
	s_add_u32 s78, s78, 0x100
	s_addc_u32 s79, s79, 0
	s_cmp_gt_u32 s87, 19

.LBB0_869:
	ds_read_b128 v[146:149], v142
	ds_read_b128 v[150:153], v142 offset:1024
	ds_read_b128 v[154:157], v142 offset:2048
	ds_read_b128 v[158:161], v142 offset:3072
	s_add_u32 s14, s12, 0xfff50080
	s_addc_u32 s15, s13, -1
	s_cmp_eq_u32 s87, 18
	s_cselect_b32 s17, s1, s15
	s_cselect_b32 s16, s0, s14
	s_cselect_b32 s15, s7, s79
	s_cselect_b32 s14, s6, s78
	s_mov_b32 m0, s68
	v_lshl_add_u64 v[208:209], s[12:13], 0, v[132:133]
	ds_read_b128 v[162:165], v143
	ds_read_b128 v[166:169], v143 offset:1024
	ds_read_b128 v[184:187], v143 offset:2048
	ds_read_b128 v[188:191], v143 offset:3072
	ds_read_b128 v[192:195], v143 offset:4096
	ds_read_b128 v[196:199], v143 offset:5120
	ds_read_b128 v[200:203], v143 offset:6144
	ds_read_b128 v[204:207], v143 offset:7168
	global_load_lds_dwordx4 v[208:209], off
	v_lshl_add_u64 v[208:209], s[12:13], 0, v[134:135]
	s_mov_b32 m0, s69
	s_nop 0
	global_load_lds_dwordx4 v[208:209], off
	s_waitcnt lgkmcnt(8)
	s_setprio 1
	s_barrier
	s_waitcnt lgkmcnt(0)
	v_mfma_f32_16x16x32_bf16 v[126:129], v[146:149], v[162:165], v[126:129]
	v_mfma_f32_16x16x32_bf16 v[122:125], v[154:157], v[162:165], v[122:125]
	v_mfma_f32_16x16x32_bf16 v[118:121], v[146:149], v[184:187], v[118:121]
	v_mfma_f32_16x16x32_bf16 v[114:117], v[154:157], v[184:187], v[114:117]
	v_mfma_f32_16x16x32_bf16 v[102:105], v[146:149], v[192:195], v[102:105]
	v_mfma_f32_16x16x32_bf16 v[98:101], v[154:157], v[192:195], v[98:101]
	v_mfma_f32_16x16x32_bf16 v[86:89], v[146:149], v[200:203], v[86:89]
	v_mfma_f32_16x16x32_bf16 v[82:85], v[154:157], v[200:203], v[82:85]
	v_mfma_f32_16x16x32_bf16 v[126:129], v[150:153], v[166:169], v[126:129]
	v_mfma_f32_16x16x32_bf16 v[122:125], v[158:161], v[166:169], v[122:125]
	v_mfma_f32_16x16x32_bf16 v[118:121], v[150:153], v[188:191], v[118:121]
	v_mfma_f32_16x16x32_bf16 v[114:117], v[158:161], v[188:191], v[114:117]
	v_mfma_f32_16x16x32_bf16 v[102:105], v[150:153], v[196:199], v[102:105]
	v_mfma_f32_16x16x32_bf16 v[98:101], v[158:161], v[196:199], v[98:101]
	v_mfma_f32_16x16x32_bf16 v[86:89], v[150:153], v[204:207], v[86:89]
	v_mfma_f32_16x16x32_bf16 v[82:85], v[158:161], v[204:207], v[82:85]
	s_barrier
	s_setprio 0
	s_mov_b32 m0, s70
	v_lshl_add_u64 v[224:225], s[14:15], 0, v[176:177]
	ds_read_b128 v[208:211], v144
	ds_read_b128 v[212:215], v144 offset:1024
	ds_read_b128 v[216:219], v144 offset:2048
	ds_read_b128 v[220:223], v144 offset:3072
	global_load_lds_dwordx4 v[224:225], off
	v_lshl_add_u64 v[226:227], s[14:15], 0, v[180:181]
	s_mov_b32 m0, s71
	s_nop 0
	global_load_lds_dwordx4 v[226:227], off
	s_setprio 1
	s_barrier
	s_waitcnt lgkmcnt(0)
	v_mfma_f32_16x16x32_bf16 v[110:113], v[208:211], v[162:165], v[110:113]
	v_mfma_f32_16x16x32_bf16 v[106:109], v[216:219], v[162:165], v[106:109]
	v_mfma_f32_16x16x32_bf16 v[94:97], v[208:211], v[184:187], v[94:97]
	v_mfma_f32_16x16x32_bf16 v[90:93], v[216:219], v[184:187], v[90:93]
	v_mfma_f32_16x16x32_bf16 v[78:81], v[208:211], v[192:195], v[78:81]
	v_mfma_f32_16x16x32_bf16 v[74:77], v[216:219], v[192:195], v[74:77]
	v_mfma_f32_16x16x32_bf16 v[70:73], v[208:211], v[200:203], v[70:73]
	v_mfma_f32_16x16x32_bf16 v[66:69], v[216:219], v[200:203], v[66:69]
	v_mfma_f32_16x16x32_bf16 v[110:113], v[212:215], v[166:169], v[110:113]
	v_mfma_f32_16x16x32_bf16 v[106:109], v[220:223], v[166:169], v[106:109]
	v_mfma_f32_16x16x32_bf16 v[94:97], v[212:215], v[188:191], v[94:97]
	v_mfma_f32_16x16x32_bf16 v[90:93], v[220:223], v[188:191], v[90:93]
	v_mfma_f32_16x16x32_bf16 v[78:81], v[212:215], v[196:199], v[78:81]
	v_mfma_f32_16x16x32_bf16 v[74:77], v[220:223], v[196:199], v[74:77]
	v_mfma_f32_16x16x32_bf16 v[70:73], v[212:215], v[204:207], v[70:73]
	v_mfma_f32_16x16x32_bf16 v[66:69], v[220:223], v[204:207], v[66:69]
	s_barrier
	s_setprio 0
	s_mov_b32 m0, s40
	v_lshl_add_u64 v[228:229], s[16:17], 0, v[172:173]
	ds_read_b128 v[162:165], v143 offset:16384
	ds_read_b128 v[166:169], v143 offset:17408
	ds_read_b128 v[184:187], v143 offset:18432
	ds_read_b128 v[188:191], v143 offset:19456
	ds_read_b128 v[192:195], v143 offset:20480
	ds_read_b128 v[196:199], v143 offset:21504
	ds_read_b128 v[200:203], v143 offset:22528
	ds_read_b128 v[204:207], v143 offset:23552
	global_load_lds_dwordx4 v[228:229], off
	v_lshl_add_u64 v[234:235], s[16:17], 0, v[178:179]
	s_mov_b32 m0, s41
	s_nop 0
	global_load_lds_dwordx4 v[234:235], off
	s_setprio 1
	s_barrier
	s_waitcnt lgkmcnt(0)
	v_mfma_f32_16x16x32_bf16 v[62:65], v[146:149], v[162:165], v[62:65]
	v_mfma_f32_16x16x32_bf16 v[58:61], v[154:157], v[162:165], v[58:61]
	v_mfma_f32_16x16x32_bf16 v[54:57], v[146:149], v[184:187], v[54:57]
	v_mfma_f32_16x16x32_bf16 v[50:53], v[154:157], v[184:187], v[50:53]
	v_mfma_f32_16x16x32_bf16 v[38:41], v[146:149], v[192:195], v[38:41]
	v_mfma_f32_16x16x32_bf16 v[34:37], v[154:157], v[192:195], v[34:37]
	v_mfma_f32_16x16x32_bf16 v[22:25], v[146:149], v[200:203], v[22:25]
	v_mfma_f32_16x16x32_bf16 v[18:21], v[154:157], v[200:203], v[18:21]
	v_mfma_f32_16x16x32_bf16 v[62:65], v[150:153], v[166:169], v[62:65]
	v_mfma_f32_16x16x32_bf16 v[58:61], v[158:161], v[166:169], v[58:61]
	v_mfma_f32_16x16x32_bf16 v[54:57], v[150:153], v[188:191], v[54:57]
	v_mfma_f32_16x16x32_bf16 v[50:53], v[158:161], v[188:191], v[50:53]
	v_mfma_f32_16x16x32_bf16 v[38:41], v[150:153], v[196:199], v[38:41]
	v_mfma_f32_16x16x32_bf16 v[34:37], v[158:161], v[196:199], v[34:37]
	v_mfma_f32_16x16x32_bf16 v[22:25], v[150:153], v[204:207], v[22:25]
	v_mfma_f32_16x16x32_bf16 v[18:21], v[158:161], v[204:207], v[18:21]
	s_barrier
	s_setprio 0
	s_add_u32 s20, s14, 0xb0000
	s_addc_u32 s21, s15, 0
	s_add_i32 s60, s56, s35
	v_lshl_add_u64 v[146:147], s[20:21], 0, v[176:177]
	s_mov_b32 m0, s60
	s_nop 0
	global_load_lds_dwordx4 v[146:147], off
	v_lshl_add_u64 v[146:147], s[20:21], 0, v[180:181]
	s_add_i32 m0, s60, 0x2000
	s_nop 0
	global_load_lds_dwordx4 v[146:147], off
	s_waitcnt vmcnt(6)
	s_setprio 1
	s_barrier
	v_mfma_f32_16x16x32_bf16 v[46:49], v[208:211], v[162:165], v[46:49]
	v_mfma_f32_16x16x32_bf16 v[42:45], v[216:219], v[162:165], v[42:45]
	v_mfma_f32_16x16x32_bf16 v[30:33], v[208:211], v[184:187], v[30:33]
	v_mfma_f32_16x16x32_bf16 v[26:29], v[216:219], v[184:187], v[26:29]
	v_mfma_f32_16x16x32_bf16 v[14:17], v[208:211], v[192:195], v[14:17]
	v_mfma_f32_16x16x32_bf16 v[10:13], v[216:219], v[192:195], v[10:13]
	v_mfma_f32_16x16x32_bf16 v[6:9], v[208:211], v[200:203], v[6:9]
	v_mfma_f32_16x16x32_bf16 v[2:5], v[216:219], v[200:203], v[2:5]
	v_mfma_f32_16x16x32_bf16 v[46:49], v[212:215], v[166:169], v[46:49]
	v_mfma_f32_16x16x32_bf16 v[42:45], v[220:223], v[166:169], v[42:45]
	v_mfma_f32_16x16x32_bf16 v[30:33], v[212:215], v[188:191], v[30:33]
	v_mfma_f32_16x16x32_bf16 v[26:29], v[220:223], v[188:191], v[26:29]
	v_mfma_f32_16x16x32_bf16 v[14:17], v[212:215], v[196:199], v[14:17]
	v_mfma_f32_16x16x32_bf16 v[10:13], v[220:223], v[196:199], v[10:13]
	v_mfma_f32_16x16x32_bf16 v[6:9], v[212:215], v[204:207], v[6:9]
	v_mfma_f32_16x16x32_bf16 v[2:5], v[220:223], v[204:207], v[2:5]
	s_barrier
	s_setprio 0
	s_add_i32 s20, 0, 0x18000
	v_add_u32_e32 v145, s20, v141
	ds_read_b128 v[146:149], v145
	ds_read_b128 v[150:153], v145 offset:1024
	ds_read_b128 v[154:157], v145 offset:2048
	ds_read_b128 v[158:161], v145 offset:3072
	s_add_u32 s16, s16, 0xb0000
	s_addc_u32 s17, s17, 0
	s_mov_b32 m0, s48
	v_lshl_add_u64 v[208:209], s[16:17], 0, v[172:173]
	ds_read_b128 v[162:165], v143 offset:32768
	ds_read_b128 v[166:169], v143 offset:33792
	ds_read_b128 v[184:187], v143 offset:34816
	ds_read_b128 v[188:191], v143 offset:35840
	ds_read_b128 v[192:195], v143 offset:36864
	ds_read_b128 v[196:199], v143 offset:37888
	ds_read_b128 v[200:203], v143 offset:38912
	ds_read_b128 v[204:207], v143 offset:39936
	global_load_lds_dwordx4 v[208:209], off
	v_lshl_add_u64 v[208:209], s[16:17], 0, v[178:179]
	s_mov_b32 m0, s49
	s_nop 0
	global_load_lds_dwordx4 v[208:209], off
	s_waitcnt lgkmcnt(8)
	s_setprio 1
	s_barrier
	s_waitcnt lgkmcnt(0)
	v_mfma_f32_16x16x32_bf16 v[126:129], v[146:149], v[162:165], v[126:129]
	v_mfma_f32_16x16x32_bf16 v[122:125], v[154:157], v[162:165], v[122:125]
	v_mfma_f32_16x16x32_bf16 v[118:121], v[146:149], v[184:187], v[118:121]
	v_mfma_f32_16x16x32_bf16 v[114:117], v[154:157], v[184:187], v[114:117]
	v_mfma_f32_16x16x32_bf16 v[102:105], v[146:149], v[192:195], v[102:105]
	v_mfma_f32_16x16x32_bf16 v[98:101], v[154:157], v[192:195], v[98:101]
	v_mfma_f32_16x16x32_bf16 v[86:89], v[146:149], v[200:203], v[86:89]
	v_mfma_f32_16x16x32_bf16 v[82:85], v[154:157], v[200:203], v[82:85]
	v_mfma_f32_16x16x32_bf16 v[126:129], v[150:153], v[166:169], v[126:129]
	v_mfma_f32_16x16x32_bf16 v[122:125], v[158:161], v[166:169], v[122:125]
	v_mfma_f32_16x16x32_bf16 v[118:121], v[150:153], v[188:191], v[118:121]
	v_mfma_f32_16x16x32_bf16 v[114:117], v[158:161], v[188:191], v[114:117]
	v_mfma_f32_16x16x32_bf16 v[102:105], v[150:153], v[196:199], v[102:105]
	v_mfma_f32_16x16x32_bf16 v[98:101], v[158:161], v[196:199], v[98:101]
	v_mfma_f32_16x16x32_bf16 v[86:89], v[150:153], v[204:207], v[86:89]
	v_mfma_f32_16x16x32_bf16 v[82:85], v[158:161], v[204:207], v[82:85]
	s_barrier
	s_setprio 0
	s_add_i32 s16, 0, 0x1c000
	s_add_i32 s17, s20, s35
	v_add_u32_e32 v145, s16, v141
	v_lshl_add_u64 v[224:225], v[224:225], 0, s[8:9]
	s_mov_b32 m0, s17
	ds_read_b128 v[208:211], v145
	ds_read_b128 v[212:215], v145 offset:1024
	ds_read_b128 v[216:219], v145 offset:2048
	ds_read_b128 v[220:223], v145 offset:3072
	global_load_lds_dwordx4 v[224:225], off
	v_lshl_add_u64 v[224:225], v[226:227], 0, s[8:9]
	s_add_i32 m0, s17, 0x2000
	s_nop 0
	global_load_lds_dwordx4 v[224:225], off
	s_setprio 1
	s_barrier
	s_waitcnt lgkmcnt(0)
	v_mfma_f32_16x16x32_bf16 v[110:113], v[208:211], v[162:165], v[110:113]
	v_mfma_f32_16x16x32_bf16 v[106:109], v[216:219], v[162:165], v[106:109]
	v_mfma_f32_16x16x32_bf16 v[94:97], v[208:211], v[184:187], v[94:97]
	v_mfma_f32_16x16x32_bf16 v[90:93], v[216:219], v[184:187], v[90:93]
	v_mfma_f32_16x16x32_bf16 v[78:81], v[208:211], v[192:195], v[78:81]
	v_mfma_f32_16x16x32_bf16 v[74:77], v[216:219], v[192:195], v[74:77]
	v_mfma_f32_16x16x32_bf16 v[70:73], v[208:211], v[200:203], v[70:73]
	v_mfma_f32_16x16x32_bf16 v[66:69], v[216:219], v[200:203], v[66:69]
	v_mfma_f32_16x16x32_bf16 v[110:113], v[212:215], v[166:169], v[110:113]
	v_mfma_f32_16x16x32_bf16 v[106:109], v[220:223], v[166:169], v[106:109]
	v_mfma_f32_16x16x32_bf16 v[94:97], v[212:215], v[188:191], v[94:97]
	v_mfma_f32_16x16x32_bf16 v[90:93], v[220:223], v[188:191], v[90:93]
	v_mfma_f32_16x16x32_bf16 v[78:81], v[212:215], v[196:199], v[78:81]
	v_mfma_f32_16x16x32_bf16 v[74:77], v[220:223], v[196:199], v[74:77]
	v_mfma_f32_16x16x32_bf16 v[70:73], v[212:215], v[204:207], v[70:73]
	v_mfma_f32_16x16x32_bf16 v[66:69], v[220:223], v[204:207], v[66:69]
	s_barrier
	s_setprio 0
	s_mov_b32 m0, s54
	v_lshl_add_u64 v[224:225], v[228:229], 0, s[8:9]
	ds_read_b128 v[162:165], v143 offset:49152
	ds_read_b128 v[166:169], v143 offset:50176
	ds_read_b128 v[184:187], v143 offset:51200
	ds_read_b128 v[188:191], v143 offset:52224
	ds_read_b128 v[192:195], v143 offset:53248
	ds_read_b128 v[196:199], v143 offset:54272
	ds_read_b128 v[200:203], v143 offset:55296
	ds_read_b128 v[204:207], v143 offset:56320
	global_load_lds_dwordx4 v[224:225], off
	v_lshl_add_u64 v[224:225], v[234:235], 0, s[8:9]
	s_mov_b32 m0, s55
	s_nop 0
	global_load_lds_dwordx4 v[224:225], off
	s_setprio 1
	s_barrier
	s_waitcnt lgkmcnt(0)
	v_mfma_f32_16x16x32_bf16 v[62:65], v[146:149], v[162:165], v[62:65]
	v_mfma_f32_16x16x32_bf16 v[58:61], v[154:157], v[162:165], v[58:61]
	v_mfma_f32_16x16x32_bf16 v[54:57], v[146:149], v[184:187], v[54:57]
	v_mfma_f32_16x16x32_bf16 v[50:53], v[154:157], v[184:187], v[50:53]
	v_mfma_f32_16x16x32_bf16 v[38:41], v[146:149], v[192:195], v[38:41]
	v_mfma_f32_16x16x32_bf16 v[34:37], v[154:157], v[192:195], v[34:37]
	v_mfma_f32_16x16x32_bf16 v[22:25], v[146:149], v[200:203], v[22:25]
	v_mfma_f32_16x16x32_bf16 v[18:21], v[154:157], v[200:203], v[18:21]
	v_mfma_f32_16x16x32_bf16 v[62:65], v[150:153], v[166:169], v[62:65]
	v_mfma_f32_16x16x32_bf16 v[58:61], v[158:161], v[166:169], v[58:61]
	v_mfma_f32_16x16x32_bf16 v[54:57], v[150:153], v[188:191], v[54:57]
	v_mfma_f32_16x16x32_bf16 v[50:53], v[158:161], v[188:191], v[50:53]
	v_mfma_f32_16x16x32_bf16 v[38:41], v[150:153], v[196:199], v[38:41]
	v_mfma_f32_16x16x32_bf16 v[34:37], v[158:161], v[196:199], v[34:37]
	v_mfma_f32_16x16x32_bf16 v[22:25], v[150:153], v[204:207], v[22:25]
	v_mfma_f32_16x16x32_bf16 v[18:21], v[158:161], v[204:207], v[18:21]
	s_barrier
	s_setprio 0
	s_add_u32 s14, s14, 0xb0080
	s_addc_u32 s15, s15, 0
	s_add_i32 s16, s16, s35
	v_lshl_add_u64 v[146:147], s[14:15], 0, v[176:177]
	s_mov_b32 m0, s16
	s_nop 0
	global_load_lds_dwordx4 v[146:147], off
	v_lshl_add_u64 v[146:147], s[14:15], 0, v[180:181]
	s_add_i32 m0, s16, 0x2000
	s_nop 0
	global_load_lds_dwordx4 v[146:147], off
	s_waitcnt vmcnt(6)
	s_setprio 1
	s_barrier
	v_mfma_f32_16x16x32_bf16 v[46:49], v[208:211], v[162:165], v[46:49]
	v_mfma_f32_16x16x32_bf16 v[42:45], v[216:219], v[162:165], v[42:45]
	v_mfma_f32_16x16x32_bf16 v[30:33], v[208:211], v[184:187], v[30:33]
	v_mfma_f32_16x16x32_bf16 v[26:29], v[216:219], v[184:187], v[26:29]
	v_mfma_f32_16x16x32_bf16 v[14:17], v[208:211], v[192:195], v[14:17]
	v_mfma_f32_16x16x32_bf16 v[10:13], v[216:219], v[192:195], v[10:13]
	v_mfma_f32_16x16x32_bf16 v[6:9], v[208:211], v[200:203], v[6:9]
	v_mfma_f32_16x16x32_bf16 v[2:5], v[216:219], v[200:203], v[2:5]
	v_mfma_f32_16x16x32_bf16 v[46:49], v[212:215], v[166:169], v[46:49]
	v_mfma_f32_16x16x32_bf16 v[42:45], v[220:223], v[166:169], v[42:45]
	v_mfma_f32_16x16x32_bf16 v[30:33], v[212:215], v[188:191], v[30:33]
	v_mfma_f32_16x16x32_bf16 v[26:29], v[220:223], v[188:191], v[26:29]
	v_mfma_f32_16x16x32_bf16 v[14:17], v[212:215], v[196:199], v[14:17]
	v_mfma_f32_16x16x32_bf16 v[10:13], v[220:223], v[196:199], v[10:13]
	v_mfma_f32_16x16x32_bf16 v[6:9], v[212:215], v[204:207], v[6:9]
	v_mfma_f32_16x16x32_bf16 v[2:5], v[220:223], v[204:207], v[2:5]
	s_add_i32 s87, s87, 2
	s_add_u32 s12, s12, 0x100
	s_addc_u32 s13, s13, 0
	s_add_u32 s78, s78, 0x100
	s_addc_u32 s79, s79, 0
	s_cmp_gt_u32 s87, 19
	s_cbranch_scc0 .Ldfr_p3sk_r
	s_cmpk_gt_u32 s34, 0xff
	s_cbranch_scc1 .Ldfr_p3sk_b
	s_barrier
.Ldfr_p3sk_b:
	s_setprio 0
	s_cmp_eq_u32 s75, 0
	s_cselect_b32 s12, 0, 0x800000
	s_add_u32 s14, s51, s12
	s_addc_u32 s15, s53, 0
	s_lshl_b32 s12, s77, 8
	s_ashr_i32 s13, s12, 31
	s_lshl_b64 s[12:13], s[12:13], 1
	s_add_u32 s12, s14, s12
	v_lshl_add_u32 v148, s76, 8, v140
	s_addc_u32 s13, s15, s13
	v_ashrrev_i32_e32 v149, 31, v148
	v_lshl_add_u64 v[146:147], s[12:13], 0, v[130:131]
	v_lshlrev_b64 v[150:151], 11, v[148:149]
	v_cvt_pk_bf16_f32 v110, v110, v111
	v_cvt_pk_bf16_f32 v111, v112, v113
	v_cvt_pk_bf16_f32 v112, v106, v107
	v_or_b32_e32 v106, 16, v148
	v_cvt_pk_bf16_f32 v46, v46, v47
	v_cvt_pk_bf16_f32 v47, v48, v49
	v_cvt_pk_bf16_f32 v48, v42, v43
	v_add_u32_e32 v42, 0x90, v148
	v_lshl_add_u64 v[150:151], v[146:147], 0, v[150:151]
	v_ashrrev_i32_e32 v107, 31, v106
	v_cvt_pk_bf16_f32 v94, v94, v95
	v_cvt_pk_bf16_f32 v95, v96, v97
	v_cvt_pk_bf16_f32 v96, v90, v91
	v_or_b32_e32 v90, 32, v148
	v_ashrrev_i32_e32 v43, 31, v42
	v_cvt_pk_bf16_f32 v30, v30, v31
	v_cvt_pk_bf16_f32 v31, v32, v33
	v_cvt_pk_bf16_f32 v32, v26, v27
	v_add_u32_e32 v26, 0xa0, v148
	v_cvt_pk_bf16_f32 v113, v108, v109
	v_lshlrev_b64 v[106:107], 11, v[106:107]
	v_ashrrev_i32_e32 v91, 31, v90
	v_cvt_pk_bf16_f32 v78, v78, v79
	v_cvt_pk_bf16_f32 v79, v80, v81
	v_cvt_pk_bf16_f32 v80, v74, v75
	v_or_b32_e32 v74, 48, v148
	v_cvt_pk_bf16_f32 v70, v70, v71
	v_cvt_pk_bf16_f32 v71, v72, v73
	v_cvt_pk_bf16_f32 v72, v66, v67
	v_lshl_add_u64 v[66:67], v[150:151], 0, s[10:11]
	v_cvt_pk_bf16_f32 v49, v44, v45
	v_lshlrev_b64 v[42:43], 11, v[42:43]
	v_ashrrev_i32_e32 v27, 31, v26
	v_cvt_pk_bf16_f32 v14, v14, v15
	v_cvt_pk_bf16_f32 v15, v16, v17
	v_cvt_pk_bf16_f32 v16, v10, v11
	v_add_u32_e32 v10, 0xb0, v148
	global_store_dwordx4 v[150:151], v[110:113], off offset:256 nt
	v_cvt_pk_bf16_f32 v97, v92, v93
	v_lshlrev_b64 v[90:91], 11, v[90:91]
	v_lshl_add_u64 v[110:111], v[146:147], 0, v[106:107]
	v_ashrrev_i32_e32 v75, 31, v74
	v_cvt_pk_bf16_f32 v62, v62, v63
	v_cvt_pk_bf16_f32 v63, v64, v65
	v_cvt_pk_bf16_f32 v64, v58, v59
	v_add_co_u32_e32 v58, vcc, s57, v150
	global_store_dwordx4 v[66:67], v[46:49], off offset:256 nt
	v_cvt_pk_bf16_f32 v33, v28, v29
	v_lshlrev_b64 v[26:27], 11, v[26:27]
	v_lshl_add_u64 v[46:47], v[146:147], 0, v[42:43]
	v_ashrrev_i32_e32 v11, 31, v10
	global_store_dwordx4 v[110:111], v[94:97], off offset:256 nt
	v_cvt_pk_bf16_f32 v81, v76, v77
	v_lshlrev_b64 v[74:75], 11, v[74:75]
	v_lshl_add_u64 v[94:95], v[146:147], 0, v[90:91]
	v_addc_co_u32_e32 v59, vcc, 0, v151, vcc
	global_store_dwordx4 v[46:47], v[30:33], off offset:256 nt
	v_cvt_pk_bf16_f32 v17, v12, v13
	v_lshlrev_b64 v[10:11], 11, v[10:11]
	v_lshl_add_u64 v[30:31], v[146:147], 0, v[26:27]
	v_cvt_pk_bf16_f32 v126, v126, v127
	v_cvt_pk_bf16_f32 v127, v128, v129
	v_cvt_pk_bf16_f32 v128, v122, v123
	v_cvt_pk_bf16_f32 v129, v124, v125
	v_cvt_pk_bf16_f32 v106, v118, v119
	v_cvt_pk_bf16_f32 v107, v120, v121
	v_cvt_pk_bf16_f32 v108, v114, v115
	v_cvt_pk_bf16_f32 v109, v116, v117
	v_cvt_pk_bf16_f32 v90, v102, v103
	v_cvt_pk_bf16_f32 v91, v104, v105
	v_cvt_pk_bf16_f32 v92, v98, v99
	v_cvt_pk_bf16_f32 v93, v100, v101
	global_store_dwordx4 v[94:95], v[78:81], off offset:256 nt
	v_cvt_pk_bf16_f32 v76, v82, v83
	v_cvt_pk_bf16_f32 v77, v84, v85
	v_lshl_add_u64 v[78:79], v[146:147], 0, v[74:75]
	v_cvt_pk_bf16_f32 v74, v86, v87
	v_cvt_pk_bf16_f32 v75, v88, v89
	v_cvt_pk_bf16_f32 v73, v68, v69
	v_cvt_pk_bf16_f32 v65, v60, v61
	v_cvt_pk_bf16_f32 v42, v54, v55
	v_cvt_pk_bf16_f32 v43, v56, v57
	v_cvt_pk_bf16_f32 v44, v50, v51
	v_cvt_pk_bf16_f32 v45, v52, v53
	v_cvt_pk_bf16_f32 v26, v38, v39
	v_cvt_pk_bf16_f32 v27, v40, v41
	v_cvt_pk_bf16_f32 v28, v34, v35
	v_cvt_pk_bf16_f32 v29, v36, v37
	global_store_dwordx4 v[30:31], v[14:17], off offset:256 nt
	v_cvt_pk_bf16_f32 v12, v18, v19
	v_cvt_pk_bf16_f32 v13, v20, v21
	v_lshl_add_u64 v[14:15], v[146:147], 0, v[10:11]
	v_cvt_pk_bf16_f32 v10, v22, v23
	v_cvt_pk_bf16_f32 v11, v24, v25
	v_cvt_pk_bf16_f32 v6, v6, v7
	v_cvt_pk_bf16_f32 v7, v8, v9
	v_cvt_pk_bf16_f32 v8, v2, v3
	v_cvt_pk_bf16_f32 v9, v4, v5
	s_and_b64 vcc, exec, s[4:5]
	s_mov_b32 s75, s72
	s_mov_b32 s77, s73
	s_mov_b32 s76, s74
	s_mov_b64 s[14:15], s[6:7]
	s_mov_b64 s[12:13], s[0:1]
	global_store_dwordx4 v[150:151], v[126:129], off nt
	global_store_dwordx4 v[110:111], v[106:109], off nt
	global_store_dwordx4 v[94:95], v[90:93], off nt
	global_store_dwordx4 v[78:79], v[74:77], off nt
	global_store_dwordx4 v[78:79], v[70:73], off offset:256 nt
	global_store_dwordx4 v[58:59], v[62:65], off nt
	global_store_dwordx4 v[46:47], v[42:45], off nt
	global_store_dwordx4 v[30:31], v[26:29], off nt
	global_store_dwordx4 v[14:15], v[10:13], off nt
	global_store_dwordx4 v[14:15], v[6:9], off offset:256 nt
	s_cmpk_gt_u32 s34, 0xff
	s_cbranch_scc0 .Ldfr_p3sk_c
	s_barrier
.Ldfr_p3sk_c:
	s_cbranch_vccz .LBB0_862
	s_waitcnt vmcnt(0)
	s_cmpk_gt_u32 s34, 0xff
	s_cbranch_scc1 .LBB0_873
	s_barrier

.LBB0_1368:
	s_cmpk_gt_u32 s63, 0xff
	s_cbranch_scc0 .Ldfr_p5_c
	s_barrier

.LBB0_1374:
	s_ashr_i32 s41, s40, 31
	s_xor_b64 s[50:51], s[18:19], -1
	s_lshl_b64 s[20:21], s[40:41], 19
	s_add_u32 s48, s65, s20
	s_addc_u32 s49, s66, s21
	s_and_b64 s[20:21], s[18:19], exec
	s_cselect_b32 s3, s49, s35
	s_cselect_b32 s5, s48, s34
	s_ashr_i32 s39, s38, 31
	s_lshl_b64 s[20:21], s[38:39], 19
	s_add_u32 s52, s67, s20
	s_addc_u32 s53, s68, s21
	s_and_b64 s[18:19], s[18:19], exec
	s_cselect_b32 s39, s53, s55
	s_cselect_b32 s41, s52, s54
	s_add_u32 s34, s34, 0x40080
	s_addc_u32 s35, s35, 0
	s_add_u32 s56, s54, 0x100
	s_addc_u32 s57, s55, 0
	s_mov_b32 vcc_lo, -2
	s_waitcnt vmcnt(0)
	ds_read_b128 v[10:13], v225
	ds_read_b128 v[14:17], v225 offset:1024
	ds_read_b128 v[26:29], v225 offset:2048
	ds_read_b128 v[30:33], v225 offset:3072
	s_add_u32 s18, s34, 0xfffc0080
	s_addc_u32 s19, s35, -1
	s_cmp_eq_u32 vcc_lo, 12
	s_cselect_b32 s19, s3, s19
	s_cselect_b32 s18, s5, s18
	s_cselect_b32 s55, s39, s57
	s_cselect_b32 s54, s41, s56
	v_lshl_add_u64 v[202:203], s[34:35], 0, v[178:179]
	s_add_i32 m0, s72, 0xc000
	ds_read_b128 v[34:37], v226
	ds_read_b128 v[38:41], v226 offset:1024
	ds_read_b128 v[50:53], v226 offset:2048
	ds_read_b128 v[54:57], v226 offset:3072
	ds_read_b128 v[186:189], v226 offset:4096
	ds_read_b128 v[190:193], v226 offset:5120
	ds_read_b128 v[194:197], v226 offset:6144
	ds_read_b128 v[198:201], v226 offset:7168
	global_load_lds_dwordx4 v[202:203], off
	v_lshl_add_u64 v[202:203], s[34:35], 0, v[180:181]
	s_add_i32 m0, s72, 0xe000
	s_nop 0
	global_load_lds_dwordx4 v[202:203], off
	ds_read_b128 v[202:205], v227
	ds_read_b128 v[206:209], v227 offset:1024
	ds_read_b128 v[210:213], v227 offset:2048
	ds_read_b128 v[214:217], v227 offset:3072
	s_waitcnt lgkmcnt(0)
	s_setprio 1
	s_barrier
	v_mfma_f32_16x16x32_bf16 v[158:161], v[10:13], v[34:37], 0
	v_mfma_f32_16x16x32_bf16 v[154:157], v[26:29], v[34:37], 0
	v_mfma_f32_16x16x32_bf16 v[142:145], v[10:13], v[50:53], 0
	v_mfma_f32_16x16x32_bf16 v[138:141], v[26:29], v[50:53], 0
	v_mfma_f32_16x16x32_bf16 v[126:129], v[10:13], v[186:189], 0
	v_mfma_f32_16x16x32_bf16 v[122:125], v[26:29], v[186:189], 0
	v_mfma_f32_16x16x32_bf16 v[110:113], v[10:13], v[194:197], 0
	v_mfma_f32_16x16x32_bf16 v[106:109], v[26:29], v[194:197], 0
	v_mfma_f32_16x16x32_bf16 v[158:161], v[14:17], v[38:41], v[158:161]
	v_mfma_f32_16x16x32_bf16 v[154:157], v[30:33], v[38:41], v[154:157]
	v_mfma_f32_16x16x32_bf16 v[142:145], v[14:17], v[54:57], v[142:145]
	v_mfma_f32_16x16x32_bf16 v[138:141], v[30:33], v[54:57], v[138:141]
	v_mfma_f32_16x16x32_bf16 v[126:129], v[14:17], v[190:193], v[126:129]
	v_mfma_f32_16x16x32_bf16 v[122:125], v[30:33], v[190:193], v[122:125]
	v_mfma_f32_16x16x32_bf16 v[110:113], v[14:17], v[198:201], v[110:113]
	v_mfma_f32_16x16x32_bf16 v[106:109], v[30:33], v[198:201], v[106:109]
	v_mfma_f32_16x16x32_bf16 v[150:153], v[202:205], v[34:37], 0
	v_mfma_f32_16x16x32_bf16 v[34:37], v[210:213], v[34:37], 0
	v_mfma_f32_16x16x32_bf16 v[150:153], v[206:209], v[38:41], v[150:153]
	v_mfma_f32_16x16x32_bf16 v[34:37], v[214:217], v[38:41], v[34:37]
	v_mfma_f32_16x16x32_bf16 v[38:41], v[202:205], v[50:53], 0
	v_mfma_f32_16x16x32_bf16 v[50:53], v[210:213], v[50:53], 0
	v_mfma_f32_16x16x32_bf16 v[114:117], v[210:213], v[186:189], 0
	v_mfma_f32_16x16x32_bf16 v[102:105], v[202:205], v[194:197], 0
	v_mfma_f32_16x16x32_bf16 v[98:101], v[210:213], v[194:197], 0
	v_mfma_f32_16x16x32_bf16 v[38:41], v[206:209], v[54:57], v[38:41]
	v_mfma_f32_16x16x32_bf16 v[50:53], v[214:217], v[54:57], v[50:53]
	v_mfma_f32_16x16x32_bf16 v[54:57], v[202:205], v[186:189], 0
	v_mfma_f32_16x16x32_bf16 v[114:117], v[214:217], v[190:193], v[114:117]
	v_mfma_f32_16x16x32_bf16 v[102:105], v[206:209], v[198:201], v[102:105]
	v_mfma_f32_16x16x32_bf16 v[98:101], v[214:217], v[198:201], v[98:101]
	v_mfma_f32_16x16x32_bf16 v[54:57], v[206:209], v[190:193], v[54:57]
	s_barrier
	s_setprio 0
	s_add_i32 s20, s33, s71
	v_lshl_add_u64 v[222:223], s[54:55], 0, v[164:165]
	s_mov_b32 m0, s20
	s_nop 0
	global_load_lds_dwordx4 v[222:223], off
	v_lshl_add_u64 v[238:239], s[54:55], 0, v[168:169]
	s_add_i32 m0, s20, 0x2000
	s_nop 0
	global_load_lds_dwordx4 v[238:239], off
	s_mov_b32 m0, s72
	v_lshl_add_u64 v[240:241], s[18:19], 0, v[162:163]
	ds_read_b128 v[118:121], v226 offset:16384
	ds_read_b128 v[130:133], v226 offset:17408
	ds_read_b128 v[134:137], v226 offset:18432
	ds_read_b128 v[146:149], v226 offset:19456
	ds_read_b128 v[186:189], v226 offset:20480
	ds_read_b128 v[190:193], v226 offset:21504
	ds_read_b128 v[194:197], v226 offset:22528
	ds_read_b128 v[198:201], v226 offset:23552
	global_load_lds_dwordx4 v[240:241], off
	v_lshl_add_u64 v[242:243], s[18:19], 0, v[166:167]
	s_mov_b32 m0, s73
	s_nop 0
	global_load_lds_dwordx4 v[242:243], off
	s_waitcnt vmcnt(6)
	s_waitcnt lgkmcnt(0)
	s_setprio 1
	s_barrier
	v_mfma_f32_16x16x32_bf16 v[94:97], v[10:13], v[118:121], 0
	v_mfma_f32_16x16x32_bf16 v[90:93], v[26:29], v[118:121], 0
	v_mfma_f32_16x16x32_bf16 v[78:81], v[10:13], v[134:137], 0
	v_mfma_f32_16x16x32_bf16 v[74:77], v[26:29], v[134:137], 0
	v_mfma_f32_16x16x32_bf16 v[62:65], v[10:13], v[186:189], 0
	v_mfma_f32_16x16x32_bf16 v[58:61], v[26:29], v[186:189], 0
	v_mfma_f32_16x16x32_bf16 v[10:13], v[10:13], v[194:197], 0
	v_mfma_f32_16x16x32_bf16 v[94:97], v[14:17], v[130:133], v[94:97]
	v_mfma_f32_16x16x32_bf16 v[90:93], v[30:33], v[130:133], v[90:93]
	v_mfma_f32_16x16x32_bf16 v[78:81], v[14:17], v[146:149], v[78:81]
	v_mfma_f32_16x16x32_bf16 v[74:77], v[30:33], v[146:149], v[74:77]
	v_mfma_f32_16x16x32_bf16 v[62:65], v[14:17], v[190:193], v[62:65]
	v_mfma_f32_16x16x32_bf16 v[58:61], v[30:33], v[190:193], v[58:61]
	v_mfma_f32_16x16x32_bf16 v[10:13], v[14:17], v[198:201], v[10:13]
	v_mfma_f32_16x16x32_bf16 v[14:17], v[26:29], v[194:197], 0
	v_mfma_f32_16x16x32_bf16 v[14:17], v[30:33], v[198:201], v[14:17]
	v_mfma_f32_16x16x32_bf16 v[18:21], v[202:205], v[118:121], 0
	v_mfma_f32_16x16x32_bf16 v[26:29], v[206:209], v[130:133], v[18:21]
	v_mfma_f32_16x16x32_bf16 v[18:21], v[210:213], v[118:121], 0
	v_mfma_f32_16x16x32_bf16 v[30:33], v[214:217], v[130:133], v[18:21]
	v_mfma_f32_16x16x32_bf16 v[18:21], v[202:205], v[134:137], 0
	v_mfma_f32_16x16x32_bf16 v[70:73], v[206:209], v[146:149], v[18:21]
	v_mfma_f32_16x16x32_bf16 v[18:21], v[210:213], v[134:137], 0
	v_mfma_f32_16x16x32_bf16 v[66:69], v[214:217], v[146:149], v[18:21]
	v_mfma_f32_16x16x32_bf16 v[18:21], v[202:205], v[186:189], 0
	v_mfma_f32_16x16x32_bf16 v[46:49], v[206:209], v[190:193], v[18:21]
	v_mfma_f32_16x16x32_bf16 v[18:21], v[210:213], v[186:189], 0
	v_mfma_f32_16x16x32_bf16 v[6:9], v[202:205], v[194:197], 0
	v_mfma_f32_16x16x32_bf16 v[2:5], v[210:213], v[194:197], 0
	v_mfma_f32_16x16x32_bf16 v[42:45], v[214:217], v[190:193], v[18:21]
	v_mfma_f32_16x16x32_bf16 v[6:9], v[206:209], v[198:201], v[6:9]
	v_mfma_f32_16x16x32_bf16 v[2:5], v[214:217], v[198:201], v[2:5]
	s_barrier
	s_setprio 0
	s_add_u32 s20, s54, 0x40000
	s_addc_u32 s21, s55, 0
	s_add_i32 s60, s64, s71
	v_lshl_add_u64 v[246:247], s[20:21], 0, v[164:165]
	s_mov_b32 m0, s60
	s_nop 0
	global_load_lds_dwordx4 v[246:247], off
	v_lshl_add_u64 v[246:247], s[20:21], 0, v[168:169]
	s_add_i32 m0, s60, 0x2000
	s_nop 0
	global_load_lds_dwordx4 v[246:247], off
	s_add_i32 s20, 0, 0x18000
	v_add_u32_e32 v86, s20, v175
	ds_read_b128 v[18:21], v86
	ds_read_b128 v[22:25], v86 offset:1024
	ds_read_b128 v[82:85], v86 offset:2048
	ds_read_b128 v[86:89], v86 offset:3072
	s_add_u32 s18, s18, 0x40000
	s_addc_u32 s19, s19, 0
	s_mov_b32 m0, s74
	v_lshl_add_u64 v[134:135], s[18:19], 0, v[162:163]
	ds_read_b128 v[118:121], v226 offset:32768
	ds_read_b128 v[130:133], v226 offset:33792
	ds_read_b128 v[186:189], v226 offset:34816
	ds_read_b128 v[190:193], v226 offset:35840
	ds_read_b128 v[194:197], v226 offset:36864
	ds_read_b128 v[198:201], v226 offset:37888
	ds_read_b128 v[202:205], v226 offset:38912
	ds_read_b128 v[206:209], v226 offset:39936
	global_load_lds_dwordx4 v[134:135], off
	v_lshl_add_u64 v[134:135], s[18:19], 0, v[166:167]
	s_mov_b32 m0, s75
	s_nop 0
	global_load_lds_dwordx4 v[134:135], off
	s_add_i32 s21, 0, 0x1c000
	v_add_u32_e32 v244, s21, v175
	ds_read_b128 v[210:213], v244
	ds_read_b128 v[214:217], v244 offset:1024
	ds_read_b128 v[218:221], v244 offset:2048
	ds_read_b128 v[234:237], v244 offset:3072
	s_waitcnt vmcnt(8)
	s_waitcnt lgkmcnt(0)
	s_setprio 1
	s_barrier
	v_mfma_f32_16x16x32_bf16 v[134:137], v[18:21], v[118:121], v[158:161]
	v_mfma_f32_16x16x32_bf16 v[158:161], v[22:25], v[130:133], v[134:137]
	v_mfma_f32_16x16x32_bf16 v[134:137], v[82:85], v[118:121], v[154:157]
	v_mfma_f32_16x16x32_bf16 v[154:157], v[86:89], v[130:133], v[134:137]
	v_mfma_f32_16x16x32_bf16 v[134:137], v[18:21], v[186:189], v[142:145]
	v_mfma_f32_16x16x32_bf16 v[142:145], v[22:25], v[190:193], v[134:137]
	v_mfma_f32_16x16x32_bf16 v[134:137], v[82:85], v[186:189], v[138:141]
	v_mfma_f32_16x16x32_bf16 v[126:129], v[18:21], v[194:197], v[126:129]
	v_mfma_f32_16x16x32_bf16 v[122:125], v[82:85], v[194:197], v[122:125]
	v_mfma_f32_16x16x32_bf16 v[110:113], v[18:21], v[202:205], v[110:113]
	v_mfma_f32_16x16x32_bf16 v[106:109], v[82:85], v[202:205], v[106:109]
	v_mfma_f32_16x16x32_bf16 v[138:141], v[86:89], v[190:193], v[134:137]
	v_mfma_f32_16x16x32_bf16 v[126:129], v[22:25], v[198:201], v[126:129]
	v_mfma_f32_16x16x32_bf16 v[122:125], v[86:89], v[198:201], v[122:125]
	v_mfma_f32_16x16x32_bf16 v[110:113], v[22:25], v[206:209], v[110:113]
	v_mfma_f32_16x16x32_bf16 v[106:109], v[86:89], v[206:209], v[106:109]
	v_mfma_f32_16x16x32_bf16 v[34:37], v[218:221], v[118:121], v[34:37]
	v_mfma_f32_16x16x32_bf16 v[134:137], v[210:213], v[118:121], v[150:153]
	v_mfma_f32_16x16x32_bf16 v[146:149], v[234:237], v[130:133], v[34:37]
	v_mfma_f32_16x16x32_bf16 v[34:37], v[210:213], v[186:189], v[38:41]
	v_mfma_f32_16x16x32_bf16 v[150:153], v[214:217], v[130:133], v[134:137]
	v_mfma_f32_16x16x32_bf16 v[134:137], v[214:217], v[190:193], v[34:37]
	v_mfma_f32_16x16x32_bf16 v[34:37], v[218:221], v[186:189], v[50:53]
	v_mfma_f32_16x16x32_bf16 v[130:133], v[234:237], v[190:193], v[34:37]
	v_mfma_f32_16x16x32_bf16 v[34:37], v[210:213], v[194:197], v[54:57]
	v_mfma_f32_16x16x32_bf16 v[118:121], v[214:217], v[198:201], v[34:37]
	v_mfma_f32_16x16x32_bf16 v[34:37], v[218:221], v[194:197], v[114:117]
	v_mfma_f32_16x16x32_bf16 v[114:117], v[234:237], v[198:201], v[34:37]
	v_mfma_f32_16x16x32_bf16 v[34:37], v[210:213], v[202:205], v[102:105]
	v_mfma_f32_16x16x32_bf16 v[102:105], v[214:217], v[206:209], v[34:37]
	v_mfma_f32_16x16x32_bf16 v[34:37], v[218:221], v[202:205], v[98:101]
	v_mfma_f32_16x16x32_bf16 v[98:101], v[234:237], v[206:209], v[34:37]
	s_barrier
	s_setprio 0
	s_add_i32 s18, s20, s71
	v_lshl_add_u64 v[248:249], v[222:223], 0, s[24:25]
	s_mov_b32 m0, s18
	s_nop 0
	global_load_lds_dwordx4 v[248:249], off
	v_lshl_add_u64 v[248:249], v[238:239], 0, s[24:25]
	s_add_i32 m0, s18, 0x2000
	s_nop 0
	global_load_lds_dwordx4 v[248:249], off
	s_mov_b32 m0, s95
	v_lshl_add_u64 v[202:203], v[240:241], 0, s[24:25]
	s_nop 2
	ds_read_b128 v[34:37], v226 offset:49152
	ds_read_b128 v[38:41], v226 offset:50176
	ds_read_b128 v[50:53], v226 offset:51200
	ds_read_b128 v[54:57], v226 offset:52224
	ds_read_b128 v[186:189], v226 offset:53248
	ds_read_b128 v[190:193], v226 offset:54272
	ds_read_b128 v[194:197], v226 offset:55296
	ds_read_b128 v[198:201], v226 offset:56320
	global_load_lds_dwordx4 v[202:203], off
	v_lshl_add_u64 v[202:203], v[242:243], 0, s[24:25]
	s_mov_b32 m0, s96
	s_nop 0
	global_load_lds_dwordx4 v[202:203], off
	s_add_u32 s18, s54, 0x40080
	s_addc_u32 s19, s55, 0
	s_add_i32 s20, s21, s71
	v_lshl_add_u64 v[250:251], s[18:19], 0, v[164:165]
	s_mov_b32 m0, s20
	s_nop 0
	global_load_lds_dwordx4 v[250:251], off
	v_lshl_add_u64 v[250:251], s[18:19], 0, v[168:169]
	s_add_i32 m0, s20, 0x2000
	s_nop 0
	global_load_lds_dwordx4 v[250:251], off
	s_waitcnt vmcnt(6)
	s_waitcnt lgkmcnt(0)
	s_setprio 1
	s_barrier
	v_mfma_f32_16x16x32_bf16 v[94:97], v[18:21], v[34:37], v[94:97]
	v_mfma_f32_16x16x32_bf16 v[78:81], v[18:21], v[50:53], v[78:81]
	v_mfma_f32_16x16x32_bf16 v[62:65], v[18:21], v[186:189], v[62:65]
	v_mfma_f32_16x16x32_bf16 v[10:13], v[18:21], v[194:197], v[10:13]
	v_mfma_f32_16x16x32_bf16 v[94:97], v[22:25], v[38:41], v[94:97]
	v_mfma_f32_16x16x32_bf16 v[90:93], v[82:85], v[34:37], v[90:93]
	v_mfma_f32_16x16x32_bf16 v[78:81], v[22:25], v[54:57], v[78:81]
	v_mfma_f32_16x16x32_bf16 v[74:77], v[82:85], v[50:53], v[74:77]
	v_mfma_f32_16x16x32_bf16 v[62:65], v[22:25], v[190:193], v[62:65]
	v_mfma_f32_16x16x32_bf16 v[58:61], v[82:85], v[186:189], v[58:61]
	v_mfma_f32_16x16x32_bf16 v[22:25], v[22:25], v[198:201], v[10:13]
	v_mfma_f32_16x16x32_bf16 v[10:13], v[82:85], v[194:197], v[14:17]
	v_mfma_f32_16x16x32_bf16 v[90:93], v[86:89], v[38:41], v[90:93]
	v_mfma_f32_16x16x32_bf16 v[74:77], v[86:89], v[54:57], v[74:77]
	v_mfma_f32_16x16x32_bf16 v[58:61], v[86:89], v[190:193], v[58:61]
	v_mfma_f32_16x16x32_bf16 v[18:21], v[86:89], v[198:201], v[10:13]
	v_mfma_f32_16x16x32_bf16 v[10:13], v[210:213], v[34:37], v[26:29]
	v_mfma_f32_16x16x32_bf16 v[86:89], v[214:217], v[38:41], v[10:13]
	v_mfma_f32_16x16x32_bf16 v[10:13], v[218:221], v[34:37], v[30:33]
	v_mfma_f32_16x16x32_bf16 v[82:85], v[234:237], v[38:41], v[10:13]
	v_mfma_f32_16x16x32_bf16 v[10:13], v[210:213], v[50:53], v[70:73]
	v_mfma_f32_16x16x32_bf16 v[70:73], v[214:217], v[54:57], v[10:13]
	v_mfma_f32_16x16x32_bf16 v[10:13], v[218:221], v[50:53], v[66:69]
	v_mfma_f32_16x16x32_bf16 v[66:69], v[234:237], v[54:57], v[10:13]
	v_mfma_f32_16x16x32_bf16 v[10:13], v[210:213], v[186:189], v[46:49]
	v_mfma_f32_16x16x32_bf16 v[46:49], v[214:217], v[190:193], v[10:13]
	v_mfma_f32_16x16x32_bf16 v[10:13], v[218:221], v[186:189], v[42:45]
	v_mfma_f32_16x16x32_bf16 v[6:9], v[210:213], v[194:197], v[6:9]
	v_mfma_f32_16x16x32_bf16 v[2:5], v[218:221], v[194:197], v[2:5]
	v_mfma_f32_16x16x32_bf16 v[42:45], v[234:237], v[190:193], v[10:13]
	v_mfma_f32_16x16x32_bf16 v[6:9], v[214:217], v[198:201], v[6:9]
	v_mfma_f32_16x16x32_bf16 v[2:5], v[234:237], v[198:201], v[2:5]
	s_add_i32 vcc_lo, vcc_lo, 2
	s_add_u32 s34, s34, 0x100
	s_addc_u32 s35, s35, 0
	s_add_u32 s56, s56, 0x100
	s_addc_u32 s57, s57, 0
	s_cmp_gt_u32 vcc_lo, 13

.LBB0_1375:
	ds_read_b128 v[10:13], v225
	ds_read_b128 v[14:17], v225 offset:1024
	ds_read_b128 v[26:29], v225 offset:2048
	ds_read_b128 v[30:33], v225 offset:3072
	s_add_u32 s18, s34, 0xfffc0080
	s_addc_u32 s19, s35, -1
	s_cmp_eq_u32 vcc_lo, 12
	s_cselect_b32 s19, s3, s19
	s_cselect_b32 s18, s5, s18
	s_cselect_b32 s55, s39, s57
	s_cselect_b32 s54, s41, s56
	v_lshl_add_u64 v[202:203], s[34:35], 0, v[178:179]
	s_add_i32 m0, s72, 0xc000
	ds_read_b128 v[34:37], v226
	ds_read_b128 v[38:41], v226 offset:1024
	ds_read_b128 v[50:53], v226 offset:2048
	ds_read_b128 v[54:57], v226 offset:3072
	ds_read_b128 v[186:189], v226 offset:4096
	ds_read_b128 v[190:193], v226 offset:5120
	ds_read_b128 v[194:197], v226 offset:6144
	ds_read_b128 v[198:201], v226 offset:7168
	global_load_lds_dwordx4 v[202:203], off
	v_lshl_add_u64 v[202:203], s[34:35], 0, v[180:181]
	s_add_i32 m0, s72, 0xe000
	s_nop 0
	global_load_lds_dwordx4 v[202:203], off
	ds_read_b128 v[202:205], v227
	ds_read_b128 v[206:209], v227 offset:1024
	ds_read_b128 v[210:213], v227 offset:2048
	ds_read_b128 v[214:217], v227 offset:3072
	s_waitcnt lgkmcnt(0)
	s_setprio 1
	s_barrier
	v_mfma_f32_16x16x32_bf16 v[158:161], v[10:13], v[34:37], v[158:161]
	v_mfma_f32_16x16x32_bf16 v[154:157], v[26:29], v[34:37], v[154:157]
	v_mfma_f32_16x16x32_bf16 v[142:145], v[10:13], v[50:53], v[142:145]
	v_mfma_f32_16x16x32_bf16 v[138:141], v[26:29], v[50:53], v[138:141]
	v_mfma_f32_16x16x32_bf16 v[126:129], v[10:13], v[186:189], v[126:129]
	v_mfma_f32_16x16x32_bf16 v[122:125], v[26:29], v[186:189], v[122:125]
	v_mfma_f32_16x16x32_bf16 v[110:113], v[10:13], v[194:197], v[110:113]
	v_mfma_f32_16x16x32_bf16 v[106:109], v[26:29], v[194:197], v[106:109]
	v_mfma_f32_16x16x32_bf16 v[158:161], v[14:17], v[38:41], v[158:161]
	v_mfma_f32_16x16x32_bf16 v[154:157], v[30:33], v[38:41], v[154:157]
	v_mfma_f32_16x16x32_bf16 v[142:145], v[14:17], v[54:57], v[142:145]
	v_mfma_f32_16x16x32_bf16 v[138:141], v[30:33], v[54:57], v[138:141]
	v_mfma_f32_16x16x32_bf16 v[126:129], v[14:17], v[190:193], v[126:129]
	v_mfma_f32_16x16x32_bf16 v[122:125], v[30:33], v[190:193], v[122:125]
	v_mfma_f32_16x16x32_bf16 v[110:113], v[14:17], v[198:201], v[110:113]
	v_mfma_f32_16x16x32_bf16 v[106:109], v[30:33], v[198:201], v[106:109]
	v_mfma_f32_16x16x32_bf16 v[150:153], v[202:205], v[34:37], v[150:153]
	v_mfma_f32_16x16x32_bf16 v[34:37], v[210:213], v[34:37], v[146:149]
	v_mfma_f32_16x16x32_bf16 v[150:153], v[206:209], v[38:41], v[150:153]
	v_mfma_f32_16x16x32_bf16 v[34:37], v[214:217], v[38:41], v[34:37]
	v_mfma_f32_16x16x32_bf16 v[38:41], v[202:205], v[50:53], v[134:137]
	v_mfma_f32_16x16x32_bf16 v[50:53], v[210:213], v[50:53], v[130:133]
	v_mfma_f32_16x16x32_bf16 v[114:117], v[210:213], v[186:189], v[114:117]
	v_mfma_f32_16x16x32_bf16 v[102:105], v[202:205], v[194:197], v[102:105]
	v_mfma_f32_16x16x32_bf16 v[98:101], v[210:213], v[194:197], v[98:101]
	v_mfma_f32_16x16x32_bf16 v[38:41], v[206:209], v[54:57], v[38:41]
	v_mfma_f32_16x16x32_bf16 v[50:53], v[214:217], v[54:57], v[50:53]
	v_mfma_f32_16x16x32_bf16 v[54:57], v[202:205], v[186:189], v[118:121]
	v_mfma_f32_16x16x32_bf16 v[114:117], v[214:217], v[190:193], v[114:117]
	v_mfma_f32_16x16x32_bf16 v[102:105], v[206:209], v[198:201], v[102:105]
	v_mfma_f32_16x16x32_bf16 v[98:101], v[214:217], v[198:201], v[98:101]
	v_mfma_f32_16x16x32_bf16 v[54:57], v[206:209], v[190:193], v[54:57]
	s_barrier
	s_setprio 0
	s_add_i32 s20, s33, s71
	v_lshl_add_u64 v[222:223], s[54:55], 0, v[164:165]
	s_mov_b32 m0, s20
	s_nop 0
	global_load_lds_dwordx4 v[222:223], off
	v_lshl_add_u64 v[238:239], s[54:55], 0, v[168:169]
	s_add_i32 m0, s20, 0x2000
	s_nop 0
	global_load_lds_dwordx4 v[238:239], off
	s_mov_b32 m0, s72
	v_lshl_add_u64 v[240:241], s[18:19], 0, v[162:163]
	ds_read_b128 v[118:121], v226 offset:16384
	ds_read_b128 v[130:133], v226 offset:17408
	ds_read_b128 v[134:137], v226 offset:18432
	ds_read_b128 v[146:149], v226 offset:19456
	ds_read_b128 v[186:189], v226 offset:20480
	ds_read_b128 v[190:193], v226 offset:21504
	ds_read_b128 v[194:197], v226 offset:22528
	ds_read_b128 v[198:201], v226 offset:23552
	global_load_lds_dwordx4 v[240:241], off
	v_lshl_add_u64 v[242:243], s[18:19], 0, v[166:167]
	s_mov_b32 m0, s73
	s_nop 0
	global_load_lds_dwordx4 v[242:243], off
	s_waitcnt vmcnt(6)
	s_waitcnt lgkmcnt(0)
	s_setprio 1
	s_barrier
	v_mfma_f32_16x16x32_bf16 v[94:97], v[10:13], v[118:121], v[94:97]
	v_mfma_f32_16x16x32_bf16 v[90:93], v[26:29], v[118:121], v[90:93]
	v_mfma_f32_16x16x32_bf16 v[78:81], v[10:13], v[134:137], v[78:81]
	v_mfma_f32_16x16x32_bf16 v[74:77], v[26:29], v[134:137], v[74:77]
	v_mfma_f32_16x16x32_bf16 v[62:65], v[10:13], v[186:189], v[62:65]
	v_mfma_f32_16x16x32_bf16 v[58:61], v[26:29], v[186:189], v[58:61]
	v_mfma_f32_16x16x32_bf16 v[10:13], v[10:13], v[194:197], v[22:25]
	v_mfma_f32_16x16x32_bf16 v[94:97], v[14:17], v[130:133], v[94:97]
	v_mfma_f32_16x16x32_bf16 v[90:93], v[30:33], v[130:133], v[90:93]
	v_mfma_f32_16x16x32_bf16 v[78:81], v[14:17], v[146:149], v[78:81]
	v_mfma_f32_16x16x32_bf16 v[74:77], v[30:33], v[146:149], v[74:77]
	v_mfma_f32_16x16x32_bf16 v[62:65], v[14:17], v[190:193], v[62:65]
	v_mfma_f32_16x16x32_bf16 v[58:61], v[30:33], v[190:193], v[58:61]
	v_mfma_f32_16x16x32_bf16 v[10:13], v[14:17], v[198:201], v[10:13]
	v_mfma_f32_16x16x32_bf16 v[14:17], v[26:29], v[194:197], v[18:21]
	v_mfma_f32_16x16x32_bf16 v[14:17], v[30:33], v[198:201], v[14:17]
	v_mfma_f32_16x16x32_bf16 v[18:21], v[202:205], v[118:121], v[86:89]
	v_mfma_f32_16x16x32_bf16 v[26:29], v[206:209], v[130:133], v[18:21]
	v_mfma_f32_16x16x32_bf16 v[18:21], v[210:213], v[118:121], v[82:85]
	v_mfma_f32_16x16x32_bf16 v[30:33], v[214:217], v[130:133], v[18:21]
	v_mfma_f32_16x16x32_bf16 v[18:21], v[202:205], v[134:137], v[70:73]
	v_mfma_f32_16x16x32_bf16 v[70:73], v[206:209], v[146:149], v[18:21]
	v_mfma_f32_16x16x32_bf16 v[18:21], v[210:213], v[134:137], v[66:69]
	v_mfma_f32_16x16x32_bf16 v[66:69], v[214:217], v[146:149], v[18:21]
	v_mfma_f32_16x16x32_bf16 v[18:21], v[202:205], v[186:189], v[46:49]
	v_mfma_f32_16x16x32_bf16 v[46:49], v[206:209], v[190:193], v[18:21]
	v_mfma_f32_16x16x32_bf16 v[18:21], v[210:213], v[186:189], v[42:45]
	v_mfma_f32_16x16x32_bf16 v[6:9], v[202:205], v[194:197], v[6:9]
	v_mfma_f32_16x16x32_bf16 v[2:5], v[210:213], v[194:197], v[2:5]
	v_mfma_f32_16x16x32_bf16 v[42:45], v[214:217], v[190:193], v[18:21]
	v_mfma_f32_16x16x32_bf16 v[6:9], v[206:209], v[198:201], v[6:9]
	v_mfma_f32_16x16x32_bf16 v[2:5], v[214:217], v[198:201], v[2:5]
	s_barrier
	s_setprio 0
	s_add_u32 s20, s54, 0x40000
	s_addc_u32 s21, s55, 0
	s_add_i32 s60, s64, s71
	v_lshl_add_u64 v[246:247], s[20:21], 0, v[164:165]
	s_mov_b32 m0, s60
	s_nop 0
	global_load_lds_dwordx4 v[246:247], off
	v_lshl_add_u64 v[246:247], s[20:21], 0, v[168:169]
	s_add_i32 m0, s60, 0x2000
	s_nop 0
	global_load_lds_dwordx4 v[246:247], off
	s_add_i32 s20, 0, 0x18000
	v_add_u32_e32 v86, s20, v175
	ds_read_b128 v[18:21], v86
	ds_read_b128 v[22:25], v86 offset:1024
	ds_read_b128 v[82:85], v86 offset:2048
	ds_read_b128 v[86:89], v86 offset:3072
	s_add_u32 s18, s18, 0x40000
	s_addc_u32 s19, s19, 0
	s_mov_b32 m0, s74
	v_lshl_add_u64 v[134:135], s[18:19], 0, v[162:163]
	ds_read_b128 v[118:121], v226 offset:32768
	ds_read_b128 v[130:133], v226 offset:33792
	ds_read_b128 v[186:189], v226 offset:34816
	ds_read_b128 v[190:193], v226 offset:35840
	ds_read_b128 v[194:197], v226 offset:36864
	ds_read_b128 v[198:201], v226 offset:37888
	ds_read_b128 v[202:205], v226 offset:38912
	ds_read_b128 v[206:209], v226 offset:39936
	global_load_lds_dwordx4 v[134:135], off
	v_lshl_add_u64 v[134:135], s[18:19], 0, v[166:167]
	s_mov_b32 m0, s75
	s_nop 0
	global_load_lds_dwordx4 v[134:135], off
	s_add_i32 s21, 0, 0x1c000
	v_add_u32_e32 v244, s21, v175
	ds_read_b128 v[210:213], v244
	ds_read_b128 v[214:217], v244 offset:1024
	ds_read_b128 v[218:221], v244 offset:2048
	ds_read_b128 v[234:237], v244 offset:3072
	s_waitcnt vmcnt(8)
	s_waitcnt lgkmcnt(0)
	s_setprio 1
	s_barrier
	v_mfma_f32_16x16x32_bf16 v[134:137], v[18:21], v[118:121], v[158:161]
	v_mfma_f32_16x16x32_bf16 v[158:161], v[22:25], v[130:133], v[134:137]
	v_mfma_f32_16x16x32_bf16 v[134:137], v[82:85], v[118:121], v[154:157]
	v_mfma_f32_16x16x32_bf16 v[154:157], v[86:89], v[130:133], v[134:137]
	v_mfma_f32_16x16x32_bf16 v[134:137], v[18:21], v[186:189], v[142:145]
	v_mfma_f32_16x16x32_bf16 v[142:145], v[22:25], v[190:193], v[134:137]
	v_mfma_f32_16x16x32_bf16 v[134:137], v[82:85], v[186:189], v[138:141]
	v_mfma_f32_16x16x32_bf16 v[126:129], v[18:21], v[194:197], v[126:129]
	v_mfma_f32_16x16x32_bf16 v[122:125], v[82:85], v[194:197], v[122:125]
	v_mfma_f32_16x16x32_bf16 v[110:113], v[18:21], v[202:205], v[110:113]
	v_mfma_f32_16x16x32_bf16 v[106:109], v[82:85], v[202:205], v[106:109]
	v_mfma_f32_16x16x32_bf16 v[138:141], v[86:89], v[190:193], v[134:137]
	v_mfma_f32_16x16x32_bf16 v[126:129], v[22:25], v[198:201], v[126:129]
	v_mfma_f32_16x16x32_bf16 v[122:125], v[86:89], v[198:201], v[122:125]
	v_mfma_f32_16x16x32_bf16 v[110:113], v[22:25], v[206:209], v[110:113]
	v_mfma_f32_16x16x32_bf16 v[106:109], v[86:89], v[206:209], v[106:109]
	v_mfma_f32_16x16x32_bf16 v[34:37], v[218:221], v[118:121], v[34:37]
	v_mfma_f32_16x16x32_bf16 v[134:137], v[210:213], v[118:121], v[150:153]
	v_mfma_f32_16x16x32_bf16 v[146:149], v[234:237], v[130:133], v[34:37]
	v_mfma_f32_16x16x32_bf16 v[34:37], v[210:213], v[186:189], v[38:41]
	v_mfma_f32_16x16x32_bf16 v[150:153], v[214:217], v[130:133], v[134:137]
	v_mfma_f32_16x16x32_bf16 v[134:137], v[214:217], v[190:193], v[34:37]
	v_mfma_f32_16x16x32_bf16 v[34:37], v[218:221], v[186:189], v[50:53]
	v_mfma_f32_16x16x32_bf16 v[130:133], v[234:237], v[190:193], v[34:37]
	v_mfma_f32_16x16x32_bf16 v[34:37], v[210:213], v[194:197], v[54:57]
	v_mfma_f32_16x16x32_bf16 v[118:121], v[214:217], v[198:201], v[34:37]
	v_mfma_f32_16x16x32_bf16 v[34:37], v[218:221], v[194:197], v[114:117]
	v_mfma_f32_16x16x32_bf16 v[114:117], v[234:237], v[198:201], v[34:37]
	v_mfma_f32_16x16x32_bf16 v[34:37], v[210:213], v[202:205], v[102:105]
	v_mfma_f32_16x16x32_bf16 v[102:105], v[214:217], v[206:209], v[34:37]
	v_mfma_f32_16x16x32_bf16 v[34:37], v[218:221], v[202:205], v[98:101]
	v_mfma_f32_16x16x32_bf16 v[98:101], v[234:237], v[206:209], v[34:37]
	s_barrier
	s_setprio 0
	s_add_i32 s18, s20, s71
	v_lshl_add_u64 v[248:249], v[222:223], 0, s[24:25]
	s_mov_b32 m0, s18
	s_nop 0
	global_load_lds_dwordx4 v[248:249], off
	v_lshl_add_u64 v[248:249], v[238:239], 0, s[24:25]
	s_add_i32 m0, s18, 0x2000
	s_nop 0
	global_load_lds_dwordx4 v[248:249], off
	s_mov_b32 m0, s95
	v_lshl_add_u64 v[202:203], v[240:241], 0, s[24:25]
	s_nop 2
	ds_read_b128 v[34:37], v226 offset:49152
	ds_read_b128 v[38:41], v226 offset:50176
	ds_read_b128 v[50:53], v226 offset:51200
	ds_read_b128 v[54:57], v226 offset:52224
	ds_read_b128 v[186:189], v226 offset:53248
	ds_read_b128 v[190:193], v226 offset:54272
	ds_read_b128 v[194:197], v226 offset:55296
	ds_read_b128 v[198:201], v226 offset:56320
	global_load_lds_dwordx4 v[202:203], off
	v_lshl_add_u64 v[202:203], v[242:243], 0, s[24:25]
	s_mov_b32 m0, s96
	s_nop 0
	global_load_lds_dwordx4 v[202:203], off
	s_add_u32 s18, s54, 0x40080
	s_addc_u32 s19, s55, 0
	s_add_i32 s20, s21, s71
	v_lshl_add_u64 v[250:251], s[18:19], 0, v[164:165]
	s_mov_b32 m0, s20
	s_nop 0
	global_load_lds_dwordx4 v[250:251], off
	v_lshl_add_u64 v[250:251], s[18:19], 0, v[168:169]
	s_add_i32 m0, s20, 0x2000
	s_nop 0
	global_load_lds_dwordx4 v[250:251], off
	s_waitcnt vmcnt(6)
	s_waitcnt lgkmcnt(0)
	s_setprio 1
	s_barrier
	v_mfma_f32_16x16x32_bf16 v[94:97], v[18:21], v[34:37], v[94:97]
	v_mfma_f32_16x16x32_bf16 v[78:81], v[18:21], v[50:53], v[78:81]
	v_mfma_f32_16x16x32_bf16 v[62:65], v[18:21], v[186:189], v[62:65]
	v_mfma_f32_16x16x32_bf16 v[10:13], v[18:21], v[194:197], v[10:13]
	v_mfma_f32_16x16x32_bf16 v[94:97], v[22:25], v[38:41], v[94:97]
	v_mfma_f32_16x16x32_bf16 v[90:93], v[82:85], v[34:37], v[90:93]
	v_mfma_f32_16x16x32_bf16 v[78:81], v[22:25], v[54:57], v[78:81]
	v_mfma_f32_16x16x32_bf16 v[74:77], v[82:85], v[50:53], v[74:77]
	v_mfma_f32_16x16x32_bf16 v[62:65], v[22:25], v[190:193], v[62:65]
	v_mfma_f32_16x16x32_bf16 v[58:61], v[82:85], v[186:189], v[58:61]
	v_mfma_f32_16x16x32_bf16 v[22:25], v[22:25], v[198:201], v[10:13]
	v_mfma_f32_16x16x32_bf16 v[10:13], v[82:85], v[194:197], v[14:17]
	v_mfma_f32_16x16x32_bf16 v[90:93], v[86:89], v[38:41], v[90:93]
	v_mfma_f32_16x16x32_bf16 v[74:77], v[86:89], v[54:57], v[74:77]
	v_mfma_f32_16x16x32_bf16 v[58:61], v[86:89], v[190:193], v[58:61]
	v_mfma_f32_16x16x32_bf16 v[18:21], v[86:89], v[198:201], v[10:13]
	v_mfma_f32_16x16x32_bf16 v[10:13], v[210:213], v[34:37], v[26:29]
	v_mfma_f32_16x16x32_bf16 v[86:89], v[214:217], v[38:41], v[10:13]
	v_mfma_f32_16x16x32_bf16 v[10:13], v[218:221], v[34:37], v[30:33]
	v_mfma_f32_16x16x32_bf16 v[82:85], v[234:237], v[38:41], v[10:13]
	v_mfma_f32_16x16x32_bf16 v[10:13], v[210:213], v[50:53], v[70:73]
	v_mfma_f32_16x16x32_bf16 v[70:73], v[214:217], v[54:57], v[10:13]
	v_mfma_f32_16x16x32_bf16 v[10:13], v[218:221], v[50:53], v[66:69]
	v_mfma_f32_16x16x32_bf16 v[66:69], v[234:237], v[54:57], v[10:13]
	v_mfma_f32_16x16x32_bf16 v[10:13], v[210:213], v[186:189], v[46:49]
	v_mfma_f32_16x16x32_bf16 v[46:49], v[214:217], v[190:193], v[10:13]
	v_mfma_f32_16x16x32_bf16 v[10:13], v[218:221], v[186:189], v[42:45]
	v_mfma_f32_16x16x32_bf16 v[6:9], v[210:213], v[194:197], v[6:9]
	v_mfma_f32_16x16x32_bf16 v[2:5], v[218:221], v[194:197], v[2:5]
	v_mfma_f32_16x16x32_bf16 v[42:45], v[234:237], v[190:193], v[10:13]
	v_mfma_f32_16x16x32_bf16 v[6:9], v[214:217], v[198:201], v[6:9]
	v_mfma_f32_16x16x32_bf16 v[2:5], v[234:237], v[198:201], v[2:5]
	s_add_i32 vcc_lo, vcc_lo, 2
	s_add_u32 s34, s34, 0x100
	s_addc_u32 s35, s35, 0
	s_add_u32 s56, s56, 0x100
	s_addc_u32 s57, s57, 0
	s_cmp_gt_u32 vcc_lo, 13
	s_cbranch_scc0 .Ldfr_p5_r
	s_cmpk_gt_u32 s63, 0xff
	s_cbranch_scc1 .Ldfr_p5_b
	s_barrier
.Ldfr_p5_b:
	s_setprio 0
	s_min_i32 s3, s4, 0x80
	s_ashr_i32 s5, s3, 3
	s_lshl_b32 s3, s2, 8
	s_mul_hi_i32 s19, s5, 0x6000
	s_mulk_i32 s5, 0x6000
	v_or_b32_e32 v186, s3, v224
	s_add_u32 s18, s77, s5
	s_addc_u32 s19, s78, s19
	v_ashrrev_i32_e32 v187, 31, v186
	v_lshl_add_u64 v[10:11], v[186:187], 2, s[18:19]
	global_load_dwordx4 v[50:53], v[10:11], off offset:16
	global_load_dwordx4 v[54:57], v[10:11], off
	global_load_dwordx4 v[26:29], v[10:11], off offset:528
	global_load_dwordx4 v[30:33], v[10:11], off offset:512
	s_add_i32 s5, s2, -2
	s_cmp_gt_u32 s5, 3
	s_cbranch_scc1 .LBB0_1378
	v_lshl_add_u64 v[14:15], v[186:187], 2, s[6:7]
	global_load_dwordx4 v[38:41], v[14:15], off offset:-2048
	global_load_dwordx4 v[34:37], v[14:15], off offset:-2032
	global_load_dwordx4 v[10:13], v[14:15], off offset:-1536
	s_nop 0
	global_load_dwordx4 v[14:17], v[14:15], off offset:-1520

.LBB0_2837:
	s_or_b64 exec, exec, s[18:19]
	s_cmpk_gt_u32 s33, 0xff
	s_cbranch_scc0 .Ldfr_p10_c
	s_barrier
.Ldfr_p10_c:
	s_and_b64 vcc, exec, s[4:5]
	s_mov_b32 s0, s34
	s_mov_b32 s42, s36
	s_mov_b64 s[46:47], s[40:41]
	s_mov_b64 s[44:45], s[38:39]
	s_cbranch_vccnz .LBB0_2862

.LBB0_2844:
	s_ashr_i32 s37, s36, 31
	v_cmp_lt_i64_e32 vcc, s[18:19], v[192:193]
	s_lshl_b64 s[18:19], s[36:37], 19
	s_add_u32 s38, s48, s18
	s_addc_u32 s39, s49, s19
	s_and_b64 s[18:19], vcc, exec
	s_cselect_b32 s37, s39, s45
	s_cselect_b32 s43, s38, s44
	s_ashr_i32 s35, s34, 31
	s_lshl_b64 s[18:19], s[34:35], 19
	s_add_u32 s40, s50, s18
	s_addc_u32 s41, s51, s19
	s_and_b64 s[18:19], vcc, exec
	s_cselect_b32 s35, s41, s47
	s_cselect_b32 s70, s40, s46
	s_add_u32 s44, s44, 0x40080
	s_addc_u32 s45, s45, 0
	s_add_u32 s71, s46, 0x100
	s_addc_u32 s72, s47, 0
	s_mov_b32 s73, -2
	s_waitcnt lgkmcnt(0)
	s_waitcnt vmcnt(0)
	ds_read_b128 v[98:101], v173
	ds_read_b128 v[102:105], v173 offset:1024
	ds_read_b128 v[106:109], v173 offset:2048
	ds_read_b128 v[110:113], v173 offset:3072
	s_add_u32 s18, s44, 0xfffc0080
	s_addc_u32 s19, s45, -1
	s_cmp_eq_u32 s73, 12
	s_cselect_b32 s19, s37, s19
	s_cselect_b32 s18, s43, s18
	s_cselect_b32 s47, s35, s72
	s_cselect_b32 s46, s70, s71
	v_lshl_add_u64 v[204:205], s[44:45], 0, v[188:189]
	s_add_i32 m0, s53, 0xc000
	ds_read_b128 v[146:149], v185
	ds_read_b128 v[150:153], v185 offset:1024
	ds_read_b128 v[154:157], v185 offset:2048
	ds_read_b128 v[158:161], v185 offset:3072
	ds_read_b128 v[162:165], v185 offset:4096
	ds_read_b128 v[166:169], v185 offset:5120
	ds_read_b128 v[196:199], v185 offset:6144
	ds_read_b128 v[200:203], v185 offset:7168
	global_load_lds_dwordx4 v[204:205], off
	v_lshl_add_u64 v[204:205], s[44:45], 0, v[190:191]
	s_add_i32 m0, s53, 0xe000
	s_nop 0
	global_load_lds_dwordx4 v[204:205], off
	ds_read_b128 v[204:207], v222
	ds_read_b128 v[208:211], v222 offset:1024
	ds_read_b128 v[212:215], v222 offset:2048
	ds_read_b128 v[216:219], v222 offset:3072
	s_waitcnt lgkmcnt(0)
	s_setprio 1
	s_barrier
	v_mfma_f32_16x16x32_bf16 v[142:145], v[98:101], v[146:149], 0
	v_mfma_f32_16x16x32_bf16 v[138:141], v[106:109], v[146:149], 0
	v_mfma_f32_16x16x32_bf16 v[126:129], v[98:101], v[154:157], 0
	v_mfma_f32_16x16x32_bf16 v[122:125], v[106:109], v[154:157], 0
	v_mfma_f32_16x16x32_bf16 v[94:97], v[98:101], v[162:165], 0
	v_mfma_f32_16x16x32_bf16 v[90:93], v[106:109], v[162:165], 0
	v_mfma_f32_16x16x32_bf16 v[78:81], v[98:101], v[196:199], 0
	v_mfma_f32_16x16x32_bf16 v[74:77], v[106:109], v[196:199], 0
	v_mfma_f32_16x16x32_bf16 v[142:145], v[102:105], v[150:153], v[142:145]
	v_mfma_f32_16x16x32_bf16 v[138:141], v[110:113], v[150:153], v[138:141]
	v_mfma_f32_16x16x32_bf16 v[126:129], v[102:105], v[158:161], v[126:129]
	v_mfma_f32_16x16x32_bf16 v[122:125], v[110:113], v[158:161], v[122:125]
	v_mfma_f32_16x16x32_bf16 v[94:97], v[102:105], v[166:169], v[94:97]
	v_mfma_f32_16x16x32_bf16 v[90:93], v[110:113], v[166:169], v[90:93]
	v_mfma_f32_16x16x32_bf16 v[78:81], v[102:105], v[200:203], v[78:81]
	v_mfma_f32_16x16x32_bf16 v[74:77], v[110:113], v[200:203], v[74:77]
	v_mfma_f32_16x16x32_bf16 v[134:137], v[204:207], v[146:149], 0
	v_mfma_f32_16x16x32_bf16 v[130:133], v[212:215], v[146:149], 0
	v_mfma_f32_16x16x32_bf16 v[118:121], v[204:207], v[154:157], 0
	v_mfma_f32_16x16x32_bf16 v[114:117], v[212:215], v[154:157], 0
	v_mfma_f32_16x16x32_bf16 v[86:89], v[204:207], v[162:165], 0
	v_mfma_f32_16x16x32_bf16 v[82:85], v[212:215], v[162:165], 0
	v_mfma_f32_16x16x32_bf16 v[70:73], v[204:207], v[196:199], 0
	v_mfma_f32_16x16x32_bf16 v[66:69], v[212:215], v[196:199], 0
	v_mfma_f32_16x16x32_bf16 v[134:137], v[208:211], v[150:153], v[134:137]
	v_mfma_f32_16x16x32_bf16 v[130:133], v[216:219], v[150:153], v[130:133]
	v_mfma_f32_16x16x32_bf16 v[118:121], v[208:211], v[158:161], v[118:121]
	v_mfma_f32_16x16x32_bf16 v[114:117], v[216:219], v[158:161], v[114:117]
	v_mfma_f32_16x16x32_bf16 v[86:89], v[208:211], v[166:169], v[86:89]
	v_mfma_f32_16x16x32_bf16 v[82:85], v[216:219], v[166:169], v[82:85]
	v_mfma_f32_16x16x32_bf16 v[70:73], v[208:211], v[200:203], v[70:73]
	v_mfma_f32_16x16x32_bf16 v[66:69], v[216:219], v[200:203], v[66:69]
	s_barrier
	s_setprio 0
	s_add_i32 s20, s65, s52
	v_lshl_add_u64 v[220:221], s[46:47], 0, v[176:177]
	s_mov_b32 m0, s20
	s_nop 0
	global_load_lds_dwordx4 v[220:221], off
	v_lshl_add_u64 v[224:225], s[46:47], 0, v[180:181]
	s_add_i32 m0, s20, 0x2000
	s_nop 0
	global_load_lds_dwordx4 v[224:225], off
	s_mov_b32 m0, s53
	v_lshl_add_u64 v[226:227], s[18:19], 0, v[174:175]
	ds_read_b128 v[146:149], v185 offset:16384
	ds_read_b128 v[150:153], v185 offset:17408
	ds_read_b128 v[154:157], v185 offset:18432
	ds_read_b128 v[158:161], v185 offset:19456
	ds_read_b128 v[162:165], v185 offset:20480
	ds_read_b128 v[166:169], v185 offset:21504
	ds_read_b128 v[196:199], v185 offset:22528
	ds_read_b128 v[200:203], v185 offset:23552
	global_load_lds_dwordx4 v[226:227], off
	v_lshl_add_u64 v[228:229], s[18:19], 0, v[178:179]
	s_mov_b32 m0, s54
	s_nop 0
	global_load_lds_dwordx4 v[228:229], off
	s_waitcnt vmcnt(6)
	s_waitcnt lgkmcnt(0)
	s_setprio 1
	s_barrier
	v_mfma_f32_16x16x32_bf16 v[62:65], v[98:101], v[146:149], 0
	v_mfma_f32_16x16x32_bf16 v[58:61], v[106:109], v[146:149], 0
	v_mfma_f32_16x16x32_bf16 v[46:49], v[98:101], v[154:157], 0
	v_mfma_f32_16x16x32_bf16 v[42:45], v[106:109], v[154:157], 0
	v_mfma_f32_16x16x32_bf16 v[30:33], v[98:101], v[162:165], 0
	v_mfma_f32_16x16x32_bf16 v[26:29], v[106:109], v[162:165], 0
	v_mfma_f32_16x16x32_bf16 v[14:17], v[98:101], v[196:199], 0
	v_mfma_f32_16x16x32_bf16 v[10:13], v[106:109], v[196:199], 0
	v_mfma_f32_16x16x32_bf16 v[62:65], v[102:105], v[150:153], v[62:65]
	v_mfma_f32_16x16x32_bf16 v[58:61], v[110:113], v[150:153], v[58:61]
	v_mfma_f32_16x16x32_bf16 v[46:49], v[102:105], v[158:161], v[46:49]
	v_mfma_f32_16x16x32_bf16 v[42:45], v[110:113], v[158:161], v[42:45]
	v_mfma_f32_16x16x32_bf16 v[30:33], v[102:105], v[166:169], v[30:33]
	v_mfma_f32_16x16x32_bf16 v[26:29], v[110:113], v[166:169], v[26:29]
	v_mfma_f32_16x16x32_bf16 v[14:17], v[102:105], v[200:203], v[14:17]
	v_mfma_f32_16x16x32_bf16 v[10:13], v[110:113], v[200:203], v[10:13]
	v_mfma_f32_16x16x32_bf16 v[54:57], v[204:207], v[146:149], 0
	v_mfma_f32_16x16x32_bf16 v[50:53], v[212:215], v[146:149], 0
	v_mfma_f32_16x16x32_bf16 v[38:41], v[204:207], v[154:157], 0
	v_mfma_f32_16x16x32_bf16 v[34:37], v[212:215], v[154:157], 0
	v_mfma_f32_16x16x32_bf16 v[22:25], v[204:207], v[162:165], 0
	v_mfma_f32_16x16x32_bf16 v[18:21], v[212:215], v[162:165], 0
	v_mfma_f32_16x16x32_bf16 v[6:9], v[204:207], v[196:199], 0
	v_mfma_f32_16x16x32_bf16 v[2:5], v[212:215], v[196:199], 0
	v_mfma_f32_16x16x32_bf16 v[54:57], v[208:211], v[150:153], v[54:57]
	v_mfma_f32_16x16x32_bf16 v[50:53], v[216:219], v[150:153], v[50:53]
	v_mfma_f32_16x16x32_bf16 v[38:41], v[208:211], v[158:161], v[38:41]
	v_mfma_f32_16x16x32_bf16 v[34:37], v[216:219], v[158:161], v[34:37]
	v_mfma_f32_16x16x32_bf16 v[22:25], v[208:211], v[166:169], v[22:25]
	v_mfma_f32_16x16x32_bf16 v[18:21], v[216:219], v[166:169], v[18:21]
	v_mfma_f32_16x16x32_bf16 v[6:9], v[208:211], v[200:203], v[6:9]
	v_mfma_f32_16x16x32_bf16 v[2:5], v[216:219], v[200:203], v[2:5]
	s_barrier
	s_setprio 0
	s_add_u32 s20, s46, 0x40000
	s_addc_u32 s21, s47, 0
	s_add_i32 s74, s66, s52
	v_lshl_add_u64 v[246:247], s[20:21], 0, v[176:177]
	s_mov_b32 m0, s74
	s_nop 0
	global_load_lds_dwordx4 v[246:247], off
	v_lshl_add_u64 v[246:247], s[20:21], 0, v[180:181]
	s_add_i32 m0, s74, 0x2000
	s_nop 0
	global_load_lds_dwordx4 v[246:247], off
	s_add_i32 s20, 0, 0x18000
	v_add_u32_e32 v110, s20, v171
	ds_read_b128 v[98:101], v110
	ds_read_b128 v[102:105], v110 offset:1024
	ds_read_b128 v[106:109], v110 offset:2048
	ds_read_b128 v[110:113], v110 offset:3072
	s_add_u32 s18, s18, 0x40000
	s_addc_u32 s19, s19, 0
	s_mov_b32 m0, s55
	v_lshl_add_u64 v[204:205], s[18:19], 0, v[174:175]
	ds_read_b128 v[146:149], v185 offset:32768
	ds_read_b128 v[150:153], v185 offset:33792
	ds_read_b128 v[154:157], v185 offset:34816
	ds_read_b128 v[158:161], v185 offset:35840
	ds_read_b128 v[162:165], v185 offset:36864
	ds_read_b128 v[166:169], v185 offset:37888
	ds_read_b128 v[196:199], v185 offset:38912
	ds_read_b128 v[200:203], v185 offset:39936
	global_load_lds_dwordx4 v[204:205], off
	v_lshl_add_u64 v[204:205], s[18:19], 0, v[178:179]
	s_mov_b32 m0, s56
	s_nop 0
	global_load_lds_dwordx4 v[204:205], off
	s_add_i32 s21, 0, 0x1c000
	v_add_u32_e32 v182, s21, v171
	ds_read_b128 v[204:207], v182
	ds_read_b128 v[208:211], v182 offset:1024
	ds_read_b128 v[212:215], v182 offset:2048
	ds_read_b128 v[216:219], v182 offset:3072
	s_waitcnt vmcnt(8)
	s_waitcnt lgkmcnt(0)
	s_setprio 1
	s_barrier
	v_mfma_f32_16x16x32_bf16 v[142:145], v[98:101], v[146:149], v[142:145]
	v_mfma_f32_16x16x32_bf16 v[138:141], v[106:109], v[146:149], v[138:141]
	v_mfma_f32_16x16x32_bf16 v[126:129], v[98:101], v[154:157], v[126:129]
	v_mfma_f32_16x16x32_bf16 v[122:125], v[106:109], v[154:157], v[122:125]
	v_mfma_f32_16x16x32_bf16 v[94:97], v[98:101], v[162:165], v[94:97]
	v_mfma_f32_16x16x32_bf16 v[90:93], v[106:109], v[162:165], v[90:93]
	v_mfma_f32_16x16x32_bf16 v[78:81], v[98:101], v[196:199], v[78:81]
	v_mfma_f32_16x16x32_bf16 v[74:77], v[106:109], v[196:199], v[74:77]
	v_mfma_f32_16x16x32_bf16 v[142:145], v[102:105], v[150:153], v[142:145]
	v_mfma_f32_16x16x32_bf16 v[138:141], v[110:113], v[150:153], v[138:141]
	v_mfma_f32_16x16x32_bf16 v[126:129], v[102:105], v[158:161], v[126:129]
	v_mfma_f32_16x16x32_bf16 v[122:125], v[110:113], v[158:161], v[122:125]
	v_mfma_f32_16x16x32_bf16 v[94:97], v[102:105], v[166:169], v[94:97]
	v_mfma_f32_16x16x32_bf16 v[90:93], v[110:113], v[166:169], v[90:93]
	v_mfma_f32_16x16x32_bf16 v[78:81], v[102:105], v[200:203], v[78:81]
	v_mfma_f32_16x16x32_bf16 v[74:77], v[110:113], v[200:203], v[74:77]
	v_mfma_f32_16x16x32_bf16 v[134:137], v[204:207], v[146:149], v[134:137]
	v_mfma_f32_16x16x32_bf16 v[130:133], v[212:215], v[146:149], v[130:133]
	v_mfma_f32_16x16x32_bf16 v[118:121], v[204:207], v[154:157], v[118:121]
	v_mfma_f32_16x16x32_bf16 v[114:117], v[212:215], v[154:157], v[114:117]
	v_mfma_f32_16x16x32_bf16 v[86:89], v[204:207], v[162:165], v[86:89]
	v_mfma_f32_16x16x32_bf16 v[82:85], v[212:215], v[162:165], v[82:85]
	v_mfma_f32_16x16x32_bf16 v[70:73], v[204:207], v[196:199], v[70:73]
	v_mfma_f32_16x16x32_bf16 v[66:69], v[212:215], v[196:199], v[66:69]
	v_mfma_f32_16x16x32_bf16 v[134:137], v[208:211], v[150:153], v[134:137]
	v_mfma_f32_16x16x32_bf16 v[130:133], v[216:219], v[150:153], v[130:133]
	v_mfma_f32_16x16x32_bf16 v[118:121], v[208:211], v[158:161], v[118:121]
	v_mfma_f32_16x16x32_bf16 v[114:117], v[216:219], v[158:161], v[114:117]
	v_mfma_f32_16x16x32_bf16 v[86:89], v[208:211], v[166:169], v[86:89]
	v_mfma_f32_16x16x32_bf16 v[82:85], v[216:219], v[166:169], v[82:85]
	v_mfma_f32_16x16x32_bf16 v[70:73], v[208:211], v[200:203], v[70:73]
	v_mfma_f32_16x16x32_bf16 v[66:69], v[216:219], v[200:203], v[66:69]
	s_barrier
	s_setprio 0
	s_add_i32 s18, s20, s52
	v_lshl_add_u64 v[220:221], v[220:221], 0, s[10:11]
	s_mov_b32 m0, s18
	s_nop 0
	global_load_lds_dwordx4 v[220:221], off
	v_lshl_add_u64 v[220:221], v[224:225], 0, s[10:11]
	s_add_i32 m0, s18, 0x2000
	s_nop 0
	global_load_lds_dwordx4 v[220:221], off
	s_mov_b32 m0, s62
	v_lshl_add_u64 v[220:221], v[226:227], 0, s[10:11]
	ds_read_b128 v[146:149], v185 offset:49152
	ds_read_b128 v[150:153], v185 offset:50176
	ds_read_b128 v[154:157], v185 offset:51200
	ds_read_b128 v[158:161], v185 offset:52224
	ds_read_b128 v[162:165], v185 offset:53248
	ds_read_b128 v[166:169], v185 offset:54272
	ds_read_b128 v[196:199], v185 offset:55296
	ds_read_b128 v[200:203], v185 offset:56320
	global_load_lds_dwordx4 v[220:221], off
	v_lshl_add_u64 v[220:221], v[228:229], 0, s[10:11]
	s_mov_b32 m0, s63
	s_nop 0
	global_load_lds_dwordx4 v[220:221], off
	s_add_u32 s18, s46, 0x40080
	s_addc_u32 s19, s47, 0
	s_add_i32 s20, s21, s52
	v_lshl_add_u64 v[248:249], s[18:19], 0, v[176:177]
	s_mov_b32 m0, s20
	s_nop 0
	global_load_lds_dwordx4 v[248:249], off
	v_lshl_add_u64 v[248:249], s[18:19], 0, v[180:181]
	s_add_i32 m0, s20, 0x2000
	s_nop 0
	global_load_lds_dwordx4 v[248:249], off
	s_waitcnt vmcnt(6)
	s_waitcnt lgkmcnt(0)
	s_setprio 1
	s_barrier
	v_mfma_f32_16x16x32_bf16 v[62:65], v[98:101], v[146:149], v[62:65]
	v_mfma_f32_16x16x32_bf16 v[58:61], v[106:109], v[146:149], v[58:61]
	v_mfma_f32_16x16x32_bf16 v[46:49], v[98:101], v[154:157], v[46:49]
	v_mfma_f32_16x16x32_bf16 v[42:45], v[106:109], v[154:157], v[42:45]
	v_mfma_f32_16x16x32_bf16 v[30:33], v[98:101], v[162:165], v[30:33]
	v_mfma_f32_16x16x32_bf16 v[26:29], v[106:109], v[162:165], v[26:29]
	v_mfma_f32_16x16x32_bf16 v[14:17], v[98:101], v[196:199], v[14:17]
	v_mfma_f32_16x16x32_bf16 v[10:13], v[106:109], v[196:199], v[10:13]
	v_mfma_f32_16x16x32_bf16 v[62:65], v[102:105], v[150:153], v[62:65]
	v_mfma_f32_16x16x32_bf16 v[58:61], v[110:113], v[150:153], v[58:61]
	v_mfma_f32_16x16x32_bf16 v[46:49], v[102:105], v[158:161], v[46:49]
	v_mfma_f32_16x16x32_bf16 v[42:45], v[110:113], v[158:161], v[42:45]
	v_mfma_f32_16x16x32_bf16 v[30:33], v[102:105], v[166:169], v[30:33]
	v_mfma_f32_16x16x32_bf16 v[26:29], v[110:113], v[166:169], v[26:29]
	v_mfma_f32_16x16x32_bf16 v[14:17], v[102:105], v[200:203], v[14:17]
	v_mfma_f32_16x16x32_bf16 v[10:13], v[110:113], v[200:203], v[10:13]
	v_mfma_f32_16x16x32_bf16 v[54:57], v[204:207], v[146:149], v[54:57]
	v_mfma_f32_16x16x32_bf16 v[50:53], v[212:215], v[146:149], v[50:53]
	v_mfma_f32_16x16x32_bf16 v[38:41], v[204:207], v[154:157], v[38:41]
	v_mfma_f32_16x16x32_bf16 v[34:37], v[212:215], v[154:157], v[34:37]
	v_mfma_f32_16x16x32_bf16 v[22:25], v[204:207], v[162:165], v[22:25]
	v_mfma_f32_16x16x32_bf16 v[18:21], v[212:215], v[162:165], v[18:21]
	v_mfma_f32_16x16x32_bf16 v[6:9], v[204:207], v[196:199], v[6:9]
	v_mfma_f32_16x16x32_bf16 v[2:5], v[212:215], v[196:199], v[2:5]
	v_mfma_f32_16x16x32_bf16 v[54:57], v[208:211], v[150:153], v[54:57]
	v_mfma_f32_16x16x32_bf16 v[50:53], v[216:219], v[150:153], v[50:53]
	v_mfma_f32_16x16x32_bf16 v[38:41], v[208:211], v[158:161], v[38:41]
	v_mfma_f32_16x16x32_bf16 v[34:37], v[216:219], v[158:161], v[34:37]
	v_mfma_f32_16x16x32_bf16 v[22:25], v[208:211], v[166:169], v[22:25]
	v_mfma_f32_16x16x32_bf16 v[18:21], v[216:219], v[166:169], v[18:21]
	v_mfma_f32_16x16x32_bf16 v[6:9], v[208:211], v[200:203], v[6:9]
	v_mfma_f32_16x16x32_bf16 v[2:5], v[216:219], v[200:203], v[2:5]
	s_add_i32 s73, s73, 2
	s_add_u32 s44, s44, 0x100
	s_addc_u32 s45, s45, 0
	s_add_u32 s71, s71, 0x100
	s_addc_u32 s72, s72, 0
	s_cmp_gt_u32 s73, 13

.LBB0_2845:
	ds_read_b128 v[98:101], v173
	ds_read_b128 v[102:105], v173 offset:1024
	ds_read_b128 v[106:109], v173 offset:2048
	ds_read_b128 v[110:113], v173 offset:3072
	s_add_u32 s18, s44, 0xfffc0080
	s_addc_u32 s19, s45, -1
	s_cmp_eq_u32 s73, 12
	s_cselect_b32 s19, s37, s19
	s_cselect_b32 s18, s43, s18
	s_cselect_b32 s47, s35, s72
	s_cselect_b32 s46, s70, s71
	v_lshl_add_u64 v[204:205], s[44:45], 0, v[188:189]
	s_add_i32 m0, s53, 0xc000
	ds_read_b128 v[146:149], v185
	ds_read_b128 v[150:153], v185 offset:1024
	ds_read_b128 v[154:157], v185 offset:2048
	ds_read_b128 v[158:161], v185 offset:3072
	ds_read_b128 v[162:165], v185 offset:4096
	ds_read_b128 v[166:169], v185 offset:5120
	ds_read_b128 v[196:199], v185 offset:6144
	ds_read_b128 v[200:203], v185 offset:7168
	global_load_lds_dwordx4 v[204:205], off
	v_lshl_add_u64 v[204:205], s[44:45], 0, v[190:191]
	s_add_i32 m0, s53, 0xe000
	s_nop 0
	global_load_lds_dwordx4 v[204:205], off
	ds_read_b128 v[204:207], v222
	ds_read_b128 v[208:211], v222 offset:1024
	ds_read_b128 v[212:215], v222 offset:2048
	ds_read_b128 v[216:219], v222 offset:3072
	s_waitcnt lgkmcnt(0)
	s_setprio 1
	s_barrier
	v_mfma_f32_16x16x32_bf16 v[142:145], v[98:101], v[146:149], v[142:145]
	v_mfma_f32_16x16x32_bf16 v[138:141], v[106:109], v[146:149], v[138:141]
	v_mfma_f32_16x16x32_bf16 v[126:129], v[98:101], v[154:157], v[126:129]
	v_mfma_f32_16x16x32_bf16 v[122:125], v[106:109], v[154:157], v[122:125]
	v_mfma_f32_16x16x32_bf16 v[94:97], v[98:101], v[162:165], v[94:97]
	v_mfma_f32_16x16x32_bf16 v[90:93], v[106:109], v[162:165], v[90:93]
	v_mfma_f32_16x16x32_bf16 v[78:81], v[98:101], v[196:199], v[78:81]
	v_mfma_f32_16x16x32_bf16 v[74:77], v[106:109], v[196:199], v[74:77]
	v_mfma_f32_16x16x32_bf16 v[142:145], v[102:105], v[150:153], v[142:145]
	v_mfma_f32_16x16x32_bf16 v[138:141], v[110:113], v[150:153], v[138:141]
	v_mfma_f32_16x16x32_bf16 v[126:129], v[102:105], v[158:161], v[126:129]
	v_mfma_f32_16x16x32_bf16 v[122:125], v[110:113], v[158:161], v[122:125]
	v_mfma_f32_16x16x32_bf16 v[94:97], v[102:105], v[166:169], v[94:97]
	v_mfma_f32_16x16x32_bf16 v[90:93], v[110:113], v[166:169], v[90:93]
	v_mfma_f32_16x16x32_bf16 v[78:81], v[102:105], v[200:203], v[78:81]
	v_mfma_f32_16x16x32_bf16 v[74:77], v[110:113], v[200:203], v[74:77]
	v_mfma_f32_16x16x32_bf16 v[134:137], v[204:207], v[146:149], v[134:137]
	v_mfma_f32_16x16x32_bf16 v[130:133], v[212:215], v[146:149], v[130:133]
	v_mfma_f32_16x16x32_bf16 v[118:121], v[204:207], v[154:157], v[118:121]
	v_mfma_f32_16x16x32_bf16 v[114:117], v[212:215], v[154:157], v[114:117]
	v_mfma_f32_16x16x32_bf16 v[86:89], v[204:207], v[162:165], v[86:89]
	v_mfma_f32_16x16x32_bf16 v[82:85], v[212:215], v[162:165], v[82:85]
	v_mfma_f32_16x16x32_bf16 v[70:73], v[204:207], v[196:199], v[70:73]
	v_mfma_f32_16x16x32_bf16 v[66:69], v[212:215], v[196:199], v[66:69]
	v_mfma_f32_16x16x32_bf16 v[134:137], v[208:211], v[150:153], v[134:137]
	v_mfma_f32_16x16x32_bf16 v[130:133], v[216:219], v[150:153], v[130:133]
	v_mfma_f32_16x16x32_bf16 v[118:121], v[208:211], v[158:161], v[118:121]
	v_mfma_f32_16x16x32_bf16 v[114:117], v[216:219], v[158:161], v[114:117]
	v_mfma_f32_16x16x32_bf16 v[86:89], v[208:211], v[166:169], v[86:89]
	v_mfma_f32_16x16x32_bf16 v[82:85], v[216:219], v[166:169], v[82:85]
	v_mfma_f32_16x16x32_bf16 v[70:73], v[208:211], v[200:203], v[70:73]
	v_mfma_f32_16x16x32_bf16 v[66:69], v[216:219], v[200:203], v[66:69]
	s_barrier
	s_setprio 0
	s_add_i32 s20, s65, s52
	v_lshl_add_u64 v[220:221], s[46:47], 0, v[176:177]
	s_mov_b32 m0, s20
	s_nop 0
	global_load_lds_dwordx4 v[220:221], off
	v_lshl_add_u64 v[224:225], s[46:47], 0, v[180:181]
	s_add_i32 m0, s20, 0x2000
	s_nop 0
	global_load_lds_dwordx4 v[224:225], off
	s_mov_b32 m0, s53
	v_lshl_add_u64 v[226:227], s[18:19], 0, v[174:175]
	ds_read_b128 v[146:149], v185 offset:16384
	ds_read_b128 v[150:153], v185 offset:17408
	ds_read_b128 v[154:157], v185 offset:18432
	ds_read_b128 v[158:161], v185 offset:19456
	ds_read_b128 v[162:165], v185 offset:20480
	ds_read_b128 v[166:169], v185 offset:21504
	ds_read_b128 v[196:199], v185 offset:22528
	ds_read_b128 v[200:203], v185 offset:23552
	global_load_lds_dwordx4 v[226:227], off
	v_lshl_add_u64 v[228:229], s[18:19], 0, v[178:179]
	s_mov_b32 m0, s54
	s_nop 0
	global_load_lds_dwordx4 v[228:229], off
	s_waitcnt vmcnt(6)
	s_waitcnt lgkmcnt(0)
	s_setprio 1
	s_barrier
	v_mfma_f32_16x16x32_bf16 v[62:65], v[98:101], v[146:149], v[62:65]
	v_mfma_f32_16x16x32_bf16 v[58:61], v[106:109], v[146:149], v[58:61]
	v_mfma_f32_16x16x32_bf16 v[46:49], v[98:101], v[154:157], v[46:49]
	v_mfma_f32_16x16x32_bf16 v[42:45], v[106:109], v[154:157], v[42:45]
	v_mfma_f32_16x16x32_bf16 v[30:33], v[98:101], v[162:165], v[30:33]
	v_mfma_f32_16x16x32_bf16 v[26:29], v[106:109], v[162:165], v[26:29]
	v_mfma_f32_16x16x32_bf16 v[14:17], v[98:101], v[196:199], v[14:17]
	v_mfma_f32_16x16x32_bf16 v[10:13], v[106:109], v[196:199], v[10:13]
	v_mfma_f32_16x16x32_bf16 v[62:65], v[102:105], v[150:153], v[62:65]
	v_mfma_f32_16x16x32_bf16 v[58:61], v[110:113], v[150:153], v[58:61]
	v_mfma_f32_16x16x32_bf16 v[46:49], v[102:105], v[158:161], v[46:49]
	v_mfma_f32_16x16x32_bf16 v[42:45], v[110:113], v[158:161], v[42:45]
	v_mfma_f32_16x16x32_bf16 v[30:33], v[102:105], v[166:169], v[30:33]
	v_mfma_f32_16x16x32_bf16 v[26:29], v[110:113], v[166:169], v[26:29]
	v_mfma_f32_16x16x32_bf16 v[14:17], v[102:105], v[200:203], v[14:17]
	v_mfma_f32_16x16x32_bf16 v[10:13], v[110:113], v[200:203], v[10:13]
	v_mfma_f32_16x16x32_bf16 v[54:57], v[204:207], v[146:149], v[54:57]
	v_mfma_f32_16x16x32_bf16 v[50:53], v[212:215], v[146:149], v[50:53]
	v_mfma_f32_16x16x32_bf16 v[38:41], v[204:207], v[154:157], v[38:41]
	v_mfma_f32_16x16x32_bf16 v[34:37], v[212:215], v[154:157], v[34:37]
	v_mfma_f32_16x16x32_bf16 v[22:25], v[204:207], v[162:165], v[22:25]
	v_mfma_f32_16x16x32_bf16 v[18:21], v[212:215], v[162:165], v[18:21]
	v_mfma_f32_16x16x32_bf16 v[6:9], v[204:207], v[196:199], v[6:9]
	v_mfma_f32_16x16x32_bf16 v[2:5], v[212:215], v[196:199], v[2:5]
	v_mfma_f32_16x16x32_bf16 v[54:57], v[208:211], v[150:153], v[54:57]
	v_mfma_f32_16x16x32_bf16 v[50:53], v[216:219], v[150:153], v[50:53]
	v_mfma_f32_16x16x32_bf16 v[38:41], v[208:211], v[158:161], v[38:41]
	v_mfma_f32_16x16x32_bf16 v[34:37], v[216:219], v[158:161], v[34:37]
	v_mfma_f32_16x16x32_bf16 v[22:25], v[208:211], v[166:169], v[22:25]
	v_mfma_f32_16x16x32_bf16 v[18:21], v[216:219], v[166:169], v[18:21]
	v_mfma_f32_16x16x32_bf16 v[6:9], v[208:211], v[200:203], v[6:9]
	v_mfma_f32_16x16x32_bf16 v[2:5], v[216:219], v[200:203], v[2:5]
	s_barrier
	s_setprio 0
	s_add_u32 s20, s46, 0x40000
	s_addc_u32 s21, s47, 0
	s_add_i32 s74, s66, s52
	v_lshl_add_u64 v[246:247], s[20:21], 0, v[176:177]
	s_mov_b32 m0, s74
	s_nop 0
	global_load_lds_dwordx4 v[246:247], off
	v_lshl_add_u64 v[246:247], s[20:21], 0, v[180:181]
	s_add_i32 m0, s74, 0x2000
	s_nop 0
	global_load_lds_dwordx4 v[246:247], off
	s_add_i32 s20, 0, 0x18000
	v_add_u32_e32 v110, s20, v171
	ds_read_b128 v[98:101], v110
	ds_read_b128 v[102:105], v110 offset:1024
	ds_read_b128 v[106:109], v110 offset:2048
	ds_read_b128 v[110:113], v110 offset:3072
	s_add_u32 s18, s18, 0x40000
	s_addc_u32 s19, s19, 0
	s_mov_b32 m0, s55
	v_lshl_add_u64 v[204:205], s[18:19], 0, v[174:175]
	ds_read_b128 v[146:149], v185 offset:32768
	ds_read_b128 v[150:153], v185 offset:33792
	ds_read_b128 v[154:157], v185 offset:34816
	ds_read_b128 v[158:161], v185 offset:35840
	ds_read_b128 v[162:165], v185 offset:36864
	ds_read_b128 v[166:169], v185 offset:37888
	ds_read_b128 v[196:199], v185 offset:38912
	ds_read_b128 v[200:203], v185 offset:39936
	global_load_lds_dwordx4 v[204:205], off
	v_lshl_add_u64 v[204:205], s[18:19], 0, v[178:179]
	s_mov_b32 m0, s56
	s_nop 0
	global_load_lds_dwordx4 v[204:205], off
	s_add_i32 s21, 0, 0x1c000
	v_add_u32_e32 v182, s21, v171
	ds_read_b128 v[204:207], v182
	ds_read_b128 v[208:211], v182 offset:1024
	ds_read_b128 v[212:215], v182 offset:2048
	ds_read_b128 v[216:219], v182 offset:3072
	s_waitcnt vmcnt(8)
	s_waitcnt lgkmcnt(0)
	s_setprio 1
	s_barrier
	v_mfma_f32_16x16x32_bf16 v[142:145], v[98:101], v[146:149], v[142:145]
	v_mfma_f32_16x16x32_bf16 v[138:141], v[106:109], v[146:149], v[138:141]
	v_mfma_f32_16x16x32_bf16 v[126:129], v[98:101], v[154:157], v[126:129]
	v_mfma_f32_16x16x32_bf16 v[122:125], v[106:109], v[154:157], v[122:125]
	v_mfma_f32_16x16x32_bf16 v[94:97], v[98:101], v[162:165], v[94:97]
	v_mfma_f32_16x16x32_bf16 v[90:93], v[106:109], v[162:165], v[90:93]
	v_mfma_f32_16x16x32_bf16 v[78:81], v[98:101], v[196:199], v[78:81]
	v_mfma_f32_16x16x32_bf16 v[74:77], v[106:109], v[196:199], v[74:77]
	v_mfma_f32_16x16x32_bf16 v[142:145], v[102:105], v[150:153], v[142:145]
	v_mfma_f32_16x16x32_bf16 v[138:141], v[110:113], v[150:153], v[138:141]
	v_mfma_f32_16x16x32_bf16 v[126:129], v[102:105], v[158:161], v[126:129]
	v_mfma_f32_16x16x32_bf16 v[122:125], v[110:113], v[158:161], v[122:125]
	v_mfma_f32_16x16x32_bf16 v[94:97], v[102:105], v[166:169], v[94:97]
	v_mfma_f32_16x16x32_bf16 v[90:93], v[110:113], v[166:169], v[90:93]
	v_mfma_f32_16x16x32_bf16 v[78:81], v[102:105], v[200:203], v[78:81]
	v_mfma_f32_16x16x32_bf16 v[74:77], v[110:113], v[200:203], v[74:77]
	v_mfma_f32_16x16x32_bf16 v[134:137], v[204:207], v[146:149], v[134:137]
	v_mfma_f32_16x16x32_bf16 v[130:133], v[212:215], v[146:149], v[130:133]
	v_mfma_f32_16x16x32_bf16 v[118:121], v[204:207], v[154:157], v[118:121]
	v_mfma_f32_16x16x32_bf16 v[114:117], v[212:215], v[154:157], v[114:117]
	v_mfma_f32_16x16x32_bf16 v[86:89], v[204:207], v[162:165], v[86:89]
	v_mfma_f32_16x16x32_bf16 v[82:85], v[212:215], v[162:165], v[82:85]
	v_mfma_f32_16x16x32_bf16 v[70:73], v[204:207], v[196:199], v[70:73]
	v_mfma_f32_16x16x32_bf16 v[66:69], v[212:215], v[196:199], v[66:69]
	v_mfma_f32_16x16x32_bf16 v[134:137], v[208:211], v[150:153], v[134:137]
	v_mfma_f32_16x16x32_bf16 v[130:133], v[216:219], v[150:153], v[130:133]
	v_mfma_f32_16x16x32_bf16 v[118:121], v[208:211], v[158:161], v[118:121]
	v_mfma_f32_16x16x32_bf16 v[114:117], v[216:219], v[158:161], v[114:117]
	v_mfma_f32_16x16x32_bf16 v[86:89], v[208:211], v[166:169], v[86:89]
	v_mfma_f32_16x16x32_bf16 v[82:85], v[216:219], v[166:169], v[82:85]
	v_mfma_f32_16x16x32_bf16 v[70:73], v[208:211], v[200:203], v[70:73]
	v_mfma_f32_16x16x32_bf16 v[66:69], v[216:219], v[200:203], v[66:69]
	s_barrier
	s_setprio 0
	s_add_i32 s18, s20, s52
	v_lshl_add_u64 v[220:221], v[220:221], 0, s[10:11]
	s_mov_b32 m0, s18
	s_nop 0
	global_load_lds_dwordx4 v[220:221], off
	v_lshl_add_u64 v[220:221], v[224:225], 0, s[10:11]
	s_add_i32 m0, s18, 0x2000
	s_nop 0
	global_load_lds_dwordx4 v[220:221], off
	s_mov_b32 m0, s62
	v_lshl_add_u64 v[220:221], v[226:227], 0, s[10:11]
	ds_read_b128 v[146:149], v185 offset:49152
	ds_read_b128 v[150:153], v185 offset:50176
	ds_read_b128 v[154:157], v185 offset:51200
	ds_read_b128 v[158:161], v185 offset:52224
	ds_read_b128 v[162:165], v185 offset:53248
	ds_read_b128 v[166:169], v185 offset:54272
	ds_read_b128 v[196:199], v185 offset:55296
	ds_read_b128 v[200:203], v185 offset:56320
	global_load_lds_dwordx4 v[220:221], off
	v_lshl_add_u64 v[220:221], v[228:229], 0, s[10:11]
	s_mov_b32 m0, s63
	s_nop 0
	global_load_lds_dwordx4 v[220:221], off
	s_add_u32 s18, s46, 0x40080
	s_addc_u32 s19, s47, 0
	s_add_i32 s20, s21, s52
	v_lshl_add_u64 v[248:249], s[18:19], 0, v[176:177]
	s_mov_b32 m0, s20
	s_nop 0
	global_load_lds_dwordx4 v[248:249], off
	v_lshl_add_u64 v[248:249], s[18:19], 0, v[180:181]
	s_add_i32 m0, s20, 0x2000
	s_nop 0
	global_load_lds_dwordx4 v[248:249], off
	s_waitcnt vmcnt(6)
	s_waitcnt lgkmcnt(0)
	s_setprio 1
	s_barrier
	v_mfma_f32_16x16x32_bf16 v[62:65], v[98:101], v[146:149], v[62:65]
	v_mfma_f32_16x16x32_bf16 v[58:61], v[106:109], v[146:149], v[58:61]
	v_mfma_f32_16x16x32_bf16 v[46:49], v[98:101], v[154:157], v[46:49]
	v_mfma_f32_16x16x32_bf16 v[42:45], v[106:109], v[154:157], v[42:45]
	v_mfma_f32_16x16x32_bf16 v[30:33], v[98:101], v[162:165], v[30:33]
	v_mfma_f32_16x16x32_bf16 v[26:29], v[106:109], v[162:165], v[26:29]
	v_mfma_f32_16x16x32_bf16 v[14:17], v[98:101], v[196:199], v[14:17]
	v_mfma_f32_16x16x32_bf16 v[10:13], v[106:109], v[196:199], v[10:13]
	v_mfma_f32_16x16x32_bf16 v[62:65], v[102:105], v[150:153], v[62:65]
	v_mfma_f32_16x16x32_bf16 v[58:61], v[110:113], v[150:153], v[58:61]
	v_mfma_f32_16x16x32_bf16 v[46:49], v[102:105], v[158:161], v[46:49]
	v_mfma_f32_16x16x32_bf16 v[42:45], v[110:113], v[158:161], v[42:45]
	v_mfma_f32_16x16x32_bf16 v[30:33], v[102:105], v[166:169], v[30:33]
	v_mfma_f32_16x16x32_bf16 v[26:29], v[110:113], v[166:169], v[26:29]
	v_mfma_f32_16x16x32_bf16 v[14:17], v[102:105], v[200:203], v[14:17]
	v_mfma_f32_16x16x32_bf16 v[10:13], v[110:113], v[200:203], v[10:13]
	v_mfma_f32_16x16x32_bf16 v[54:57], v[204:207], v[146:149], v[54:57]
	v_mfma_f32_16x16x32_bf16 v[50:53], v[212:215], v[146:149], v[50:53]
	v_mfma_f32_16x16x32_bf16 v[38:41], v[204:207], v[154:157], v[38:41]
	v_mfma_f32_16x16x32_bf16 v[34:37], v[212:215], v[154:157], v[34:37]
	v_mfma_f32_16x16x32_bf16 v[22:25], v[204:207], v[162:165], v[22:25]
	v_mfma_f32_16x16x32_bf16 v[18:21], v[212:215], v[162:165], v[18:21]
	v_mfma_f32_16x16x32_bf16 v[6:9], v[204:207], v[196:199], v[6:9]
	v_mfma_f32_16x16x32_bf16 v[2:5], v[212:215], v[196:199], v[2:5]
	v_mfma_f32_16x16x32_bf16 v[54:57], v[208:211], v[150:153], v[54:57]
	v_mfma_f32_16x16x32_bf16 v[50:53], v[216:219], v[150:153], v[50:53]
	v_mfma_f32_16x16x32_bf16 v[38:41], v[208:211], v[158:161], v[38:41]
	v_mfma_f32_16x16x32_bf16 v[34:37], v[216:219], v[158:161], v[34:37]
	v_mfma_f32_16x16x32_bf16 v[22:25], v[208:211], v[166:169], v[22:25]
	v_mfma_f32_16x16x32_bf16 v[18:21], v[216:219], v[166:169], v[18:21]
	v_mfma_f32_16x16x32_bf16 v[6:9], v[208:211], v[200:203], v[6:9]
	v_mfma_f32_16x16x32_bf16 v[2:5], v[216:219], v[200:203], v[2:5]
	s_add_i32 s73, s73, 2
	s_add_u32 s44, s44, 0x100
	s_addc_u32 s45, s45, 0
	s_add_u32 s71, s71, 0x100
	s_addc_u32 s72, s72, 0
	s_cmp_gt_u32 s73, 13
	s_cbranch_scc0 .Ldfr_p10_r
	s_cmpk_gt_u32 s33, 0xff
	s_cbranch_scc1 .Ldfr_p10_b
	s_barrier
.Ldfr_p10_b:
	s_setprio 0
	s_ashr_i32 s18, s42, 3
	s_mul_hi_i32 s19, s18, 0x9000
	s_mul_i32 s18, s18, 0x9000
	s_add_u32 s20, s58, s18
	s_addc_u32 s21, s59, s19
	s_lshl_b32 s44, s0, 8
	v_lshl_add_u32 v220, s42, 8, v1
	s_ashr_i32 s45, s44, 31
	s_lshl_b64 s[18:19], s[44:45], 2
	v_ashrrev_i32_e32 v221, 31, v220
	v_lshl_add_u64 v[146:147], s[44:45], 1, v[186:187]
	v_lshlrev_b64 v[98:99], 11, v[220:221]
	s_add_u32 s18, s20, s18
	v_lshl_add_u64 v[98:99], v[146:147], 0, v[98:99]
	s_addc_u32 s19, s21, s19
	v_lshlrev_b32_e32 v182, 2, v184
	global_load_dwordx4 v[224:227], v[98:99], off
	global_load_dwordx4 v[234:237], v[98:99], off offset:256
	v_lshl_add_u64 v[98:99], s[18:19], 0, v[182:183]
	v_add_co_u32_e32 v102, vcc, s68, v98
	v_lshl_add_u64 v[100:101], v[98:99], 0, s[16:17]
	s_nop 0
	v_addc_co_u32_e32 v103, vcc, 0, v99, vcc
	global_load_dwordx4 v[198:201], v[102:103], off
	global_load_dwordx4 v[238:241], v[100:101], off offset:16
	global_load_dwordx4 v[202:205], v[102:103], off offset:512
	v_lshl_add_u64 v[100:101], v[98:99], 0, s[24:25]
	global_load_dwordx4 v[242:245], v[100:101], off offset:16
	v_add_co_u32_e32 v100, vcc, s67, v98
	v_or_b32_e32 v218, 16, v220
	s_nop 0
	v_addc_co_u32_e32 v101, vcc, 0, v99, vcc
	global_load_dwordx4 v[110:113], v[100:101], off
	global_load_dwordx4 v[106:109], v[100:101], off offset:512
	v_lshl_add_u64 v[100:101], v[98:99], 0, s[12:13]
	v_lshl_add_u64 v[98:99], v[98:99], 0, s[14:15]
	global_load_dwordx4 v[102:105], v[100:101], off offset:16
	v_or_b32_e32 v216, 32, v220
	global_load_dwordx4 v[98:101], v[98:99], off offset:16
	v_or_b32_e32 v214, 48, v220
	v_ashrrev_i32_e32 v219, 31, v218
	v_ashrrev_i32_e32 v217, 31, v216
	v_ashrrev_i32_e32 v215, 31, v214
	v_lshlrev_b64 v[148:149], 11, v[218:219]
	v_lshlrev_b64 v[150:151], 11, v[216:217]
	v_lshlrev_b64 v[152:153], 11, v[214:215]
	v_lshl_add_u64 v[148:149], v[146:147], 0, v[148:149]
	v_lshl_add_u64 v[150:151], v[146:147], 0, v[150:151]
	v_lshl_add_u64 v[146:147], v[146:147], 0, v[152:153]
	global_load_dwordx4 v[166:169], v[148:149], off
	global_load_dwordx4 v[162:165], v[148:149], off offset:256
	global_load_dwordx4 v[158:161], v[150:151], off
	global_load_dwordx4 v[154:157], v[150:151], off offset:256
	s_nop 0
	global_load_dwordx4 v[150:153], v[146:147], off
	s_nop 0
	global_load_dwordx4 v[146:149], v[146:147], off offset:256
	v_or_b32_e32 v196, s44, v184
	v_mov_b32_e32 v197, s45
	s_lshl_b32 s42, s0, 2
	s_ashr_i32 s43, s42, 31
	s_waitcnt vmcnt(0)
	v_lshlrev_b32_e32 v228, 16, v224
	v_and_b32_e32 v229, 0xffff0000, v224
	v_lshlrev_b32_e32 v224, 16, v225
	v_and_b32_e32 v225, 0xffff0000, v225
	v_lshlrev_b32_e32 v250, 16, v236
	v_and_b32_e32 v251, 0xffff0000, v236
	v_lshlrev_b32_e32 v248, 16, v226
	v_and_b32_e32 v249, 0xffff0000, v226
	v_lshlrev_b32_e32 v246, 16, v234
	v_and_b32_e32 v247, 0xffff0000, v234
	v_lshlrev_b32_e32 v234, 16, v235
	v_and_b32_e32 v235, 0xffff0000, v235
	v_pk_add_f32 v[210:211], v[202:203], 1.0 op_sel_hi:[1,0]
	v_pk_add_f32 v[206:207], v[204:205], 1.0 op_sel_hi:[1,0]
	v_pk_add_f32 v[208:209], v[200:201], 1.0 op_sel_hi:[1,0]
	v_pk_fma_f32 v[144:145], v[144:145], v[112:113], v[224:225]
	v_pk_fma_f32 v[142:143], v[142:143], v[110:111], v[228:229]
	v_pk_fma_f32 v[134:135], v[134:135], v[106:107], v[246:247]
	v_pk_fma_f32 v[136:137], v[136:137], v[108:109], v[234:235]
	v_pk_fma_f32 v[138:139], v[138:139], v[102:103], v[248:249]
	v_pk_mul_f32 v[234:235], v[210:211], v[134:135]
	v_pk_fma_f32 v[224:225], v[130:131], v[98:99], v[250:251]
	v_lshlrev_b32_e32 v130, 16, v227
	v_and_b32_e32 v131, 0xffff0000, v227
	v_pk_fma_f32 v[140:141], v[140:141], v[104:105], v[130:131]
	v_lshlrev_b32_e32 v130, 16, v237
	v_and_b32_e32 v131, 0xffff0000, v237
	v_pk_fma_f32 v[236:237], v[132:133], v[100:101], v[130:131]
	v_lshlrev_b64 v[130:131], 10, v[220:221]
	v_lshl_add_u64 v[130:131], v[130:131], 0, v[196:197]
	v_lshlrev_b64 v[248:249], 1, v[130:131]
	v_lshl_add_u64 v[250:251], s[28:29], 0, v[248:249]
	v_cvt_pk_bf16_f32 v130, v142, v143
	v_cvt_pk_bf16_f32 v131, v144, v145
	v_cvt_pk_bf16_f32 v132, v138, v139
	v_cvt_pk_bf16_f32 v133, v140, v141
	global_store_dwordx4 v[250:251], v[130:133], off nt
	v_pk_add_f32 v[200:201], v[240:241], 1.0 op_sel_hi:[1,0]
	v_pk_mul_f32 v[240:241], v[206:207], v[136:137]
	v_cvt_pk_bf16_f32 v130, v134, v135
	v_cvt_pk_bf16_f32 v131, v136, v137
	v_cvt_pk_bf16_f32 v132, v224, v225
	v_cvt_pk_bf16_f32 v133, v236, v237
	global_store_dwordx4 v[250:251], v[130:133], off offset:256 nt
	v_pk_add_f32 v[204:205], v[238:239], 1.0 op_sel_hi:[1,0]
	v_pk_add_f32 v[202:203], v[242:243], 1.0 op_sel_hi:[1,0]
	v_pk_mul_f32 v[132:133], v[134:135], v[134:135]
	v_pk_mul_f32 v[134:135], v[136:137], v[136:137]
	v_pk_fma_f32 v[132:133], v[142:143], v[142:143], v[132:133]
	v_pk_fma_f32 v[134:135], v[144:145], v[144:145], v[134:135]
	v_add_f32_e32 v132, v132, v133
	v_pk_mul_f32 v[136:137], v[224:225], v[224:225]
	v_add_f32_e32 v132, v134, v132
	v_pk_fma_f32 v[136:137], v[138:139], v[138:139], v[136:137]
	v_add_f32_e32 v132, v135, v132
	v_pk_mul_f32 v[242:243], v[204:205], v[138:139]
	v_pk_mul_f32 v[138:139], v[236:237], v[236:237]
	v_add_f32_e32 v132, v136, v132
	v_pk_fma_f32 v[138:139], v[140:141], v[140:141], v[138:139]
	v_add_f32_e32 v132, v137, v132
	v_add_f32_e32 v132, v138, v132
	v_and_b32_e32 v133, 64, v223
	v_add_f32_e32 v134, v139, v132
	v_xor_b32_e32 v132, 16, v223
	v_add_u32_e32 v135, 64, v133
	v_cmp_lt_i32_e32 vcc, v132, v135
	v_pk_add_f32 v[212:213], v[198:199], 1.0 op_sel_hi:[1,0]
	v_pk_mul_f32 v[238:239], v[208:209], v[144:145]
	v_cndmask_b32_e32 v132, v223, v132, vcc
	v_pk_mul_f32 v[228:229], v[212:213], v[142:143]
	v_lshlrev_b32_e32 v142, 2, v132
	v_pk_mul_f32 v[226:227], v[200:201], v[140:141]
	ds_bpermute_b32 v136, v142, v134
	v_lshl_add_u64 v[248:249], s[6:7], 0, v[248:249]
	v_cvt_pk_bf16_f32 v130, v228, v229
	v_cvt_pk_bf16_f32 v131, v238, v239
	v_cvt_pk_bf16_f32 v132, v242, v243
	v_cvt_pk_bf16_f32 v133, v226, v227
	global_store_dwordx4 v[248:249], v[130:133], off nt
	v_pk_add_f32 v[198:199], v[244:245], 1.0 op_sel_hi:[1,0]
	v_pk_mul_f32 v[244:245], v[202:203], v[224:225]
	v_xor_b32_e32 v131, 32, v223
	v_cmp_lt_i32_e32 vcc, v131, v135
	s_waitcnt lgkmcnt(0)
	v_add_f32_e32 v130, v134, v136
	v_pk_mul_f32 v[246:247], v[198:199], v[236:237]
	v_cndmask_b32_e32 v131, v223, v131, vcc
	v_lshlrev_b32_e32 v143, 2, v131
	ds_bpermute_b32 v131, v143, v130
	v_cvt_pk_bf16_f32 v132, v234, v235
	v_cvt_pk_bf16_f32 v133, v240, v241
	v_cvt_pk_bf16_f32 v134, v244, v245
	v_cvt_pk_bf16_f32 v135, v246, v247
	global_store_dwordx4 v[248:249], v[132:135], off offset:256 nt
	s_and_saveexec_b64 s[18:19], s[2:3]
	s_cbranch_execz .LBB0_2848
	s_waitcnt lgkmcnt(0)
	v_add_f32_e32 v132, v130, v131
	v_lshlrev_b64 v[130:131], 6, v[220:221]
	v_lshl_add_u64 v[130:131], s[8:9], 0, v[130:131]
	v_lshl_add_u64 v[130:131], s[42:43], 2, v[130:131]
	s_lshl_b32 s0, s61, 2
	v_lshl_add_u64 v[130:131], v[130:131], 0, s[0:1]
	global_store_dword v[130:131], v132, off

.LBB0_3264:
	s_ashr_i32 s11, s10, 31
	v_cmp_lt_i64_e32 vcc, s[12:13], v[162:163]
	s_lshl_b64 s[12:13], s[10:11], 19
	s_add_u32 s12, s36, s12
	s_addc_u32 s13, s37, s13
	s_and_b64 s[14:15], vcc, exec
	s_cselect_b32 s11, s13, s25
	s_cselect_b32 s57, s12, s24
	s_ashr_i32 s9, s8, 31
	s_lshl_b64 s[14:15], s[8:9], 19
	s_add_u32 s14, s38, s14
	s_addc_u32 s15, s39, s15
	s_and_b64 s[18:19], vcc, exec
	s_cselect_b32 s9, s15, s35
	s_cselect_b32 s60, s14, s34
	s_add_u32 s24, s24, 0x40080
	s_addc_u32 s25, s25, 0
	s_add_u32 s61, s34, 0x100
	s_addc_u32 s62, s35, 0
	s_mov_b32 s63, -2
	ds_read_b128 v[130:133], v171
	ds_read_b128 v[134:137], v171 offset:1024
	ds_read_b128 v[138:141], v171 offset:2048
	ds_read_b128 v[142:145], v171 offset:3072
	s_add_u32 s18, s24, 0xfffc0080
	s_addc_u32 s19, s25, -1
	s_cmp_eq_u32 s63, 12
	s_cselect_b32 s19, s11, s19
	s_cselect_b32 s18, s57, s18
	s_cselect_b32 s35, s9, s62
	s_cselect_b32 s34, s60, s61
	v_lshl_add_u64 v[174:175], s[24:25], 0, v[158:159]
	s_add_i32 m0, s43, 0xc000
	ds_read_b128 v[166:169], v173
	ds_read_b128 v[178:181], v173 offset:1024
	ds_read_b128 v[182:185], v173 offset:2048
	ds_read_b128 v[186:189], v173 offset:3072
	ds_read_b128 v[190:193], v173 offset:4096
	ds_read_b128 v[194:197], v173 offset:5120
	ds_read_b128 v[198:201], v173 offset:6144
	ds_read_b128 v[202:205], v173 offset:7168
	global_load_lds_dwordx4 v[174:175], off
	v_lshl_add_u64 v[174:175], s[24:25], 0, v[160:161]
	s_add_i32 m0, s43, 0xe000
	s_nop 0
	global_load_lds_dwordx4 v[174:175], off
	ds_read_b128 v[206:209], v177
	ds_read_b128 v[210:213], v177 offset:1024
	ds_read_b128 v[214:217], v177 offset:2048
	ds_read_b128 v[218:221], v177 offset:3072
	s_waitcnt lgkmcnt(0)
	s_setprio 1
	s_barrier
	v_mfma_f32_16x16x32_bf16 v[126:129], v[130:133], v[166:169], 0
	v_mfma_f32_16x16x32_bf16 v[122:125], v[138:141], v[166:169], 0
	v_mfma_f32_16x16x32_bf16 v[110:113], v[130:133], v[182:185], 0
	v_mfma_f32_16x16x32_bf16 v[106:109], v[138:141], v[182:185], 0
	v_mfma_f32_16x16x32_bf16 v[94:97], v[130:133], v[190:193], 0
	v_mfma_f32_16x16x32_bf16 v[90:93], v[138:141], v[190:193], 0
	v_mfma_f32_16x16x32_bf16 v[78:81], v[130:133], v[198:201], 0
	v_mfma_f32_16x16x32_bf16 v[74:77], v[138:141], v[198:201], 0
	v_mfma_f32_16x16x32_bf16 v[126:129], v[134:137], v[178:181], v[126:129]
	v_mfma_f32_16x16x32_bf16 v[122:125], v[142:145], v[178:181], v[122:125]
	v_mfma_f32_16x16x32_bf16 v[110:113], v[134:137], v[186:189], v[110:113]
	v_mfma_f32_16x16x32_bf16 v[106:109], v[142:145], v[186:189], v[106:109]
	v_mfma_f32_16x16x32_bf16 v[94:97], v[134:137], v[194:197], v[94:97]
	v_mfma_f32_16x16x32_bf16 v[90:93], v[142:145], v[194:197], v[90:93]
	v_mfma_f32_16x16x32_bf16 v[78:81], v[134:137], v[202:205], v[78:81]
	v_mfma_f32_16x16x32_bf16 v[74:77], v[142:145], v[202:205], v[74:77]
	v_mfma_f32_16x16x32_bf16 v[118:121], v[206:209], v[166:169], 0
	v_mfma_f32_16x16x32_bf16 v[114:117], v[214:217], v[166:169], 0
	v_mfma_f32_16x16x32_bf16 v[102:105], v[206:209], v[182:185], 0
	v_mfma_f32_16x16x32_bf16 v[98:101], v[214:217], v[182:185], 0
	v_mfma_f32_16x16x32_bf16 v[86:89], v[206:209], v[190:193], 0
	v_mfma_f32_16x16x32_bf16 v[82:85], v[214:217], v[190:193], 0
	v_mfma_f32_16x16x32_bf16 v[70:73], v[206:209], v[198:201], 0
	v_mfma_f32_16x16x32_bf16 v[66:69], v[214:217], v[198:201], 0
	v_mfma_f32_16x16x32_bf16 v[118:121], v[210:213], v[178:181], v[118:121]
	v_mfma_f32_16x16x32_bf16 v[114:117], v[218:221], v[178:181], v[114:117]
	v_mfma_f32_16x16x32_bf16 v[102:105], v[210:213], v[186:189], v[102:105]
	v_mfma_f32_16x16x32_bf16 v[98:101], v[218:221], v[186:189], v[98:101]
	v_mfma_f32_16x16x32_bf16 v[86:89], v[210:213], v[194:197], v[86:89]
	v_mfma_f32_16x16x32_bf16 v[82:85], v[218:221], v[194:197], v[82:85]
	v_mfma_f32_16x16x32_bf16 v[70:73], v[210:213], v[202:205], v[70:73]
	v_mfma_f32_16x16x32_bf16 v[66:69], v[218:221], v[202:205], v[66:69]
	s_barrier
	s_setprio 0
	s_add_i32 s20, s54, s42
	v_lshl_add_u64 v[174:175], s[34:35], 0, v[150:151]
	s_mov_b32 m0, s20
	s_nop 0
	global_load_lds_dwordx4 v[174:175], off
	v_lshl_add_u64 v[222:223], s[34:35], 0, v[146:147]
	s_add_i32 m0, s20, 0x2000
	s_nop 0
	global_load_lds_dwordx4 v[222:223], off
	s_mov_b32 m0, s43
	v_lshl_add_u64 v[224:225], s[18:19], 0, v[152:153]
	ds_read_b128 v[166:169], v173 offset:16384
	ds_read_b128 v[178:181], v173 offset:17408
	ds_read_b128 v[182:185], v173 offset:18432
	ds_read_b128 v[186:189], v173 offset:19456
	ds_read_b128 v[190:193], v173 offset:20480
	ds_read_b128 v[194:197], v173 offset:21504
	ds_read_b128 v[198:201], v173 offset:22528
	ds_read_b128 v[202:205], v173 offset:23552
	global_load_lds_dwordx4 v[224:225], off
	v_lshl_add_u64 v[226:227], s[18:19], 0, v[148:149]
	s_mov_b32 m0, s44
	s_nop 0
	global_load_lds_dwordx4 v[226:227], off
	s_waitcnt vmcnt(6)
	s_waitcnt lgkmcnt(0)
	s_setprio 1
	s_barrier
	v_mfma_f32_16x16x32_bf16 v[62:65], v[130:133], v[166:169], 0
	v_mfma_f32_16x16x32_bf16 v[58:61], v[138:141], v[166:169], 0
	v_mfma_f32_16x16x32_bf16 v[46:49], v[130:133], v[182:185], 0
	v_mfma_f32_16x16x32_bf16 v[42:45], v[138:141], v[182:185], 0
	v_mfma_f32_16x16x32_bf16 v[30:33], v[130:133], v[190:193], 0
	v_mfma_f32_16x16x32_bf16 v[26:29], v[138:141], v[190:193], 0
	v_mfma_f32_16x16x32_bf16 v[14:17], v[130:133], v[198:201], 0
	v_mfma_f32_16x16x32_bf16 v[10:13], v[138:141], v[198:201], 0
	v_mfma_f32_16x16x32_bf16 v[62:65], v[134:137], v[178:181], v[62:65]
	v_mfma_f32_16x16x32_bf16 v[58:61], v[142:145], v[178:181], v[58:61]
	v_mfma_f32_16x16x32_bf16 v[46:49], v[134:137], v[186:189], v[46:49]
	v_mfma_f32_16x16x32_bf16 v[42:45], v[142:145], v[186:189], v[42:45]
	v_mfma_f32_16x16x32_bf16 v[30:33], v[134:137], v[194:197], v[30:33]
	v_mfma_f32_16x16x32_bf16 v[26:29], v[142:145], v[194:197], v[26:29]
	v_mfma_f32_16x16x32_bf16 v[14:17], v[134:137], v[202:205], v[14:17]
	v_mfma_f32_16x16x32_bf16 v[10:13], v[142:145], v[202:205], v[10:13]
	v_mfma_f32_16x16x32_bf16 v[54:57], v[206:209], v[166:169], 0
	v_mfma_f32_16x16x32_bf16 v[50:53], v[214:217], v[166:169], 0
	v_mfma_f32_16x16x32_bf16 v[38:41], v[206:209], v[182:185], 0
	v_mfma_f32_16x16x32_bf16 v[34:37], v[214:217], v[182:185], 0
	v_mfma_f32_16x16x32_bf16 v[22:25], v[206:209], v[190:193], 0
	v_mfma_f32_16x16x32_bf16 v[18:21], v[214:217], v[190:193], 0
	v_mfma_f32_16x16x32_bf16 v[6:9], v[206:209], v[198:201], 0
	v_mfma_f32_16x16x32_bf16 v[2:5], v[214:217], v[198:201], 0
	v_mfma_f32_16x16x32_bf16 v[54:57], v[210:213], v[178:181], v[54:57]
	v_mfma_f32_16x16x32_bf16 v[50:53], v[218:221], v[178:181], v[50:53]
	v_mfma_f32_16x16x32_bf16 v[38:41], v[210:213], v[186:189], v[38:41]
	v_mfma_f32_16x16x32_bf16 v[34:37], v[218:221], v[186:189], v[34:37]
	v_mfma_f32_16x16x32_bf16 v[22:25], v[210:213], v[194:197], v[22:25]
	v_mfma_f32_16x16x32_bf16 v[18:21], v[218:221], v[194:197], v[18:21]
	v_mfma_f32_16x16x32_bf16 v[6:9], v[210:213], v[202:205], v[6:9]
	v_mfma_f32_16x16x32_bf16 v[2:5], v[218:221], v[202:205], v[2:5]
	s_barrier
	s_setprio 0
	s_add_u32 s20, s34, 0x40000
	s_addc_u32 s21, s35, 0
	s_add_i32 s64, s55, s42
	v_lshl_add_u64 v[246:247], s[20:21], 0, v[150:151]
	s_mov_b32 m0, s64
	s_nop 0
	global_load_lds_dwordx4 v[246:247], off
	v_lshl_add_u64 v[246:247], s[20:21], 0, v[146:147]
	s_add_i32 m0, s64, 0x2000
	s_nop 0
	global_load_lds_dwordx4 v[246:247], off
	s_add_i32 s20, 0, 0x18000
	v_add_u32_e32 v142, s20, v157
	ds_read_b128 v[130:133], v142
	ds_read_b128 v[134:137], v142 offset:1024
	ds_read_b128 v[138:141], v142 offset:2048
	ds_read_b128 v[142:145], v142 offset:3072
	s_add_u32 s18, s18, 0x40000
	s_addc_u32 s19, s19, 0
	s_mov_b32 m0, s45
	v_lshl_add_u64 v[206:207], s[18:19], 0, v[152:153]
	ds_read_b128 v[166:169], v173 offset:32768
	ds_read_b128 v[178:181], v173 offset:33792
	ds_read_b128 v[182:185], v173 offset:34816
	ds_read_b128 v[186:189], v173 offset:35840
	ds_read_b128 v[190:193], v173 offset:36864
	ds_read_b128 v[194:197], v173 offset:37888
	ds_read_b128 v[198:201], v173 offset:38912
	ds_read_b128 v[202:205], v173 offset:39936
	global_load_lds_dwordx4 v[206:207], off
	v_lshl_add_u64 v[206:207], s[18:19], 0, v[148:149]
	s_mov_b32 m0, s46
	s_nop 0
	global_load_lds_dwordx4 v[206:207], off
	s_add_i32 s21, 0, 0x1c000
	v_add_u32_e32 v154, s21, v157
	ds_read_b128 v[206:209], v154
	ds_read_b128 v[210:213], v154 offset:1024
	ds_read_b128 v[214:217], v154 offset:2048
	ds_read_b128 v[218:221], v154 offset:3072
	s_waitcnt vmcnt(8)
	s_waitcnt lgkmcnt(0)
	s_setprio 1
	s_barrier
	v_mfma_f32_16x16x32_bf16 v[126:129], v[130:133], v[166:169], v[126:129]
	v_mfma_f32_16x16x32_bf16 v[122:125], v[138:141], v[166:169], v[122:125]
	v_mfma_f32_16x16x32_bf16 v[110:113], v[130:133], v[182:185], v[110:113]
	v_mfma_f32_16x16x32_bf16 v[106:109], v[138:141], v[182:185], v[106:109]
	v_mfma_f32_16x16x32_bf16 v[94:97], v[130:133], v[190:193], v[94:97]
	v_mfma_f32_16x16x32_bf16 v[90:93], v[138:141], v[190:193], v[90:93]
	v_mfma_f32_16x16x32_bf16 v[78:81], v[130:133], v[198:201], v[78:81]
	v_mfma_f32_16x16x32_bf16 v[74:77], v[138:141], v[198:201], v[74:77]
	v_mfma_f32_16x16x32_bf16 v[126:129], v[134:137], v[178:181], v[126:129]
	v_mfma_f32_16x16x32_bf16 v[122:125], v[142:145], v[178:181], v[122:125]
	v_mfma_f32_16x16x32_bf16 v[110:113], v[134:137], v[186:189], v[110:113]
	v_mfma_f32_16x16x32_bf16 v[106:109], v[142:145], v[186:189], v[106:109]
	v_mfma_f32_16x16x32_bf16 v[94:97], v[134:137], v[194:197], v[94:97]
	v_mfma_f32_16x16x32_bf16 v[90:93], v[142:145], v[194:197], v[90:93]
	v_mfma_f32_16x16x32_bf16 v[78:81], v[134:137], v[202:205], v[78:81]
	v_mfma_f32_16x16x32_bf16 v[74:77], v[142:145], v[202:205], v[74:77]
	v_mfma_f32_16x16x32_bf16 v[118:121], v[206:209], v[166:169], v[118:121]
	v_mfma_f32_16x16x32_bf16 v[114:117], v[214:217], v[166:169], v[114:117]
	v_mfma_f32_16x16x32_bf16 v[102:105], v[206:209], v[182:185], v[102:105]
	v_mfma_f32_16x16x32_bf16 v[98:101], v[214:217], v[182:185], v[98:101]
	v_mfma_f32_16x16x32_bf16 v[86:89], v[206:209], v[190:193], v[86:89]
	v_mfma_f32_16x16x32_bf16 v[82:85], v[214:217], v[190:193], v[82:85]
	v_mfma_f32_16x16x32_bf16 v[70:73], v[206:209], v[198:201], v[70:73]
	v_mfma_f32_16x16x32_bf16 v[66:69], v[214:217], v[198:201], v[66:69]
	v_mfma_f32_16x16x32_bf16 v[118:121], v[210:213], v[178:181], v[118:121]
	v_mfma_f32_16x16x32_bf16 v[114:117], v[218:221], v[178:181], v[114:117]
	v_mfma_f32_16x16x32_bf16 v[102:105], v[210:213], v[186:189], v[102:105]
	v_mfma_f32_16x16x32_bf16 v[98:101], v[218:221], v[186:189], v[98:101]
	v_mfma_f32_16x16x32_bf16 v[86:89], v[210:213], v[194:197], v[86:89]
	v_mfma_f32_16x16x32_bf16 v[82:85], v[218:221], v[194:197], v[82:85]
	v_mfma_f32_16x16x32_bf16 v[70:73], v[210:213], v[202:205], v[70:73]
	v_mfma_f32_16x16x32_bf16 v[66:69], v[218:221], v[202:205], v[66:69]
	s_barrier
	s_setprio 0
	s_add_i32 s18, s20, s42
	v_lshl_add_u64 v[174:175], v[174:175], 0, s[6:7]
	s_mov_b32 m0, s18
	s_nop 0
	global_load_lds_dwordx4 v[174:175], off
	v_lshl_add_u64 v[174:175], v[222:223], 0, s[6:7]
	s_add_i32 m0, s18, 0x2000
	s_nop 0
	global_load_lds_dwordx4 v[174:175], off
	s_mov_b32 m0, s50
	v_lshl_add_u64 v[174:175], v[224:225], 0, s[6:7]
	ds_read_b128 v[166:169], v173 offset:49152
	ds_read_b128 v[178:181], v173 offset:50176
	ds_read_b128 v[182:185], v173 offset:51200
	ds_read_b128 v[186:189], v173 offset:52224
	ds_read_b128 v[190:193], v173 offset:53248
	ds_read_b128 v[194:197], v173 offset:54272
	ds_read_b128 v[198:201], v173 offset:55296
	ds_read_b128 v[202:205], v173 offset:56320
	global_load_lds_dwordx4 v[174:175], off
	v_lshl_add_u64 v[174:175], v[226:227], 0, s[6:7]
	s_mov_b32 m0, s51
	s_nop 0
	global_load_lds_dwordx4 v[174:175], off
	s_add_u32 s18, s34, 0x40080
	s_addc_u32 s19, s35, 0
	s_add_i32 s20, s21, s42
	v_lshl_add_u64 v[248:249], s[18:19], 0, v[150:151]
	s_mov_b32 m0, s20
	s_nop 0
	global_load_lds_dwordx4 v[248:249], off
	v_lshl_add_u64 v[248:249], s[18:19], 0, v[146:147]
	s_add_i32 m0, s20, 0x2000
	s_nop 0
	global_load_lds_dwordx4 v[248:249], off
	s_waitcnt vmcnt(6)
	s_waitcnt lgkmcnt(0)
	s_setprio 1
	s_barrier
	v_mfma_f32_16x16x32_bf16 v[62:65], v[130:133], v[166:169], v[62:65]
	v_mfma_f32_16x16x32_bf16 v[58:61], v[138:141], v[166:169], v[58:61]
	v_mfma_f32_16x16x32_bf16 v[46:49], v[130:133], v[182:185], v[46:49]
	v_mfma_f32_16x16x32_bf16 v[42:45], v[138:141], v[182:185], v[42:45]
	v_mfma_f32_16x16x32_bf16 v[30:33], v[130:133], v[190:193], v[30:33]
	v_mfma_f32_16x16x32_bf16 v[26:29], v[138:141], v[190:193], v[26:29]
	v_mfma_f32_16x16x32_bf16 v[14:17], v[130:133], v[198:201], v[14:17]
	v_mfma_f32_16x16x32_bf16 v[10:13], v[138:141], v[198:201], v[10:13]
	v_mfma_f32_16x16x32_bf16 v[62:65], v[134:137], v[178:181], v[62:65]
	v_mfma_f32_16x16x32_bf16 v[58:61], v[142:145], v[178:181], v[58:61]
	v_mfma_f32_16x16x32_bf16 v[46:49], v[134:137], v[186:189], v[46:49]
	v_mfma_f32_16x16x32_bf16 v[42:45], v[142:145], v[186:189], v[42:45]
	v_mfma_f32_16x16x32_bf16 v[30:33], v[134:137], v[194:197], v[30:33]
	v_mfma_f32_16x16x32_bf16 v[26:29], v[142:145], v[194:197], v[26:29]
	v_mfma_f32_16x16x32_bf16 v[14:17], v[134:137], v[202:205], v[14:17]
	v_mfma_f32_16x16x32_bf16 v[10:13], v[142:145], v[202:205], v[10:13]
	v_mfma_f32_16x16x32_bf16 v[54:57], v[206:209], v[166:169], v[54:57]
	v_mfma_f32_16x16x32_bf16 v[50:53], v[214:217], v[166:169], v[50:53]
	v_mfma_f32_16x16x32_bf16 v[38:41], v[206:209], v[182:185], v[38:41]
	v_mfma_f32_16x16x32_bf16 v[34:37], v[214:217], v[182:185], v[34:37]
	v_mfma_f32_16x16x32_bf16 v[22:25], v[206:209], v[190:193], v[22:25]
	v_mfma_f32_16x16x32_bf16 v[18:21], v[214:217], v[190:193], v[18:21]
	v_mfma_f32_16x16x32_bf16 v[6:9], v[206:209], v[198:201], v[6:9]
	v_mfma_f32_16x16x32_bf16 v[2:5], v[214:217], v[198:201], v[2:5]
	v_mfma_f32_16x16x32_bf16 v[54:57], v[210:213], v[178:181], v[54:57]
	v_mfma_f32_16x16x32_bf16 v[50:53], v[218:221], v[178:181], v[50:53]
	v_mfma_f32_16x16x32_bf16 v[38:41], v[210:213], v[186:189], v[38:41]
	v_mfma_f32_16x16x32_bf16 v[34:37], v[218:221], v[186:189], v[34:37]
	v_mfma_f32_16x16x32_bf16 v[22:25], v[210:213], v[194:197], v[22:25]
	v_mfma_f32_16x16x32_bf16 v[18:21], v[218:221], v[194:197], v[18:21]
	v_mfma_f32_16x16x32_bf16 v[6:9], v[210:213], v[202:205], v[6:9]
	v_mfma_f32_16x16x32_bf16 v[2:5], v[218:221], v[202:205], v[2:5]
	s_add_i32 s63, s63, 2
	s_add_u32 s24, s24, 0x100
	s_addc_u32 s25, s25, 0
	s_add_u32 s61, s61, 0x100
	s_addc_u32 s62, s62, 0
	s_cmp_gt_u32 s63, 13

.LBB0_3265:
	ds_read_b128 v[130:133], v171
	ds_read_b128 v[134:137], v171 offset:1024
	ds_read_b128 v[138:141], v171 offset:2048
	ds_read_b128 v[142:145], v171 offset:3072
	s_add_u32 s18, s24, 0xfffc0080
	s_addc_u32 s19, s25, -1
	s_cmp_eq_u32 s63, 12
	s_cselect_b32 s19, s11, s19
	s_cselect_b32 s18, s57, s18
	s_cselect_b32 s35, s9, s62
	s_cselect_b32 s34, s60, s61
	v_lshl_add_u64 v[174:175], s[24:25], 0, v[158:159]
	s_add_i32 m0, s43, 0xc000
	ds_read_b128 v[166:169], v173
	ds_read_b128 v[178:181], v173 offset:1024
	ds_read_b128 v[182:185], v173 offset:2048
	ds_read_b128 v[186:189], v173 offset:3072
	ds_read_b128 v[190:193], v173 offset:4096
	ds_read_b128 v[194:197], v173 offset:5120
	ds_read_b128 v[198:201], v173 offset:6144
	ds_read_b128 v[202:205], v173 offset:7168
	global_load_lds_dwordx4 v[174:175], off
	v_lshl_add_u64 v[174:175], s[24:25], 0, v[160:161]
	s_add_i32 m0, s43, 0xe000
	s_nop 0
	global_load_lds_dwordx4 v[174:175], off
	ds_read_b128 v[206:209], v177
	ds_read_b128 v[210:213], v177 offset:1024
	ds_read_b128 v[214:217], v177 offset:2048
	ds_read_b128 v[218:221], v177 offset:3072
	s_waitcnt lgkmcnt(0)
	s_setprio 1
	s_barrier
	v_mfma_f32_16x16x32_bf16 v[126:129], v[130:133], v[166:169], v[126:129]
	v_mfma_f32_16x16x32_bf16 v[122:125], v[138:141], v[166:169], v[122:125]
	v_mfma_f32_16x16x32_bf16 v[110:113], v[130:133], v[182:185], v[110:113]
	v_mfma_f32_16x16x32_bf16 v[106:109], v[138:141], v[182:185], v[106:109]
	v_mfma_f32_16x16x32_bf16 v[94:97], v[130:133], v[190:193], v[94:97]
	v_mfma_f32_16x16x32_bf16 v[90:93], v[138:141], v[190:193], v[90:93]
	v_mfma_f32_16x16x32_bf16 v[78:81], v[130:133], v[198:201], v[78:81]
	v_mfma_f32_16x16x32_bf16 v[74:77], v[138:141], v[198:201], v[74:77]
	v_mfma_f32_16x16x32_bf16 v[126:129], v[134:137], v[178:181], v[126:129]
	v_mfma_f32_16x16x32_bf16 v[122:125], v[142:145], v[178:181], v[122:125]
	v_mfma_f32_16x16x32_bf16 v[110:113], v[134:137], v[186:189], v[110:113]
	v_mfma_f32_16x16x32_bf16 v[106:109], v[142:145], v[186:189], v[106:109]
	v_mfma_f32_16x16x32_bf16 v[94:97], v[134:137], v[194:197], v[94:97]
	v_mfma_f32_16x16x32_bf16 v[90:93], v[142:145], v[194:197], v[90:93]
	v_mfma_f32_16x16x32_bf16 v[78:81], v[134:137], v[202:205], v[78:81]
	v_mfma_f32_16x16x32_bf16 v[74:77], v[142:145], v[202:205], v[74:77]
	v_mfma_f32_16x16x32_bf16 v[118:121], v[206:209], v[166:169], v[118:121]
	v_mfma_f32_16x16x32_bf16 v[114:117], v[214:217], v[166:169], v[114:117]
	v_mfma_f32_16x16x32_bf16 v[102:105], v[206:209], v[182:185], v[102:105]
	v_mfma_f32_16x16x32_bf16 v[98:101], v[214:217], v[182:185], v[98:101]
	v_mfma_f32_16x16x32_bf16 v[86:89], v[206:209], v[190:193], v[86:89]
	v_mfma_f32_16x16x32_bf16 v[82:85], v[214:217], v[190:193], v[82:85]
	v_mfma_f32_16x16x32_bf16 v[70:73], v[206:209], v[198:201], v[70:73]
	v_mfma_f32_16x16x32_bf16 v[66:69], v[214:217], v[198:201], v[66:69]
	v_mfma_f32_16x16x32_bf16 v[118:121], v[210:213], v[178:181], v[118:121]
	v_mfma_f32_16x16x32_bf16 v[114:117], v[218:221], v[178:181], v[114:117]
	v_mfma_f32_16x16x32_bf16 v[102:105], v[210:213], v[186:189], v[102:105]
	v_mfma_f32_16x16x32_bf16 v[98:101], v[218:221], v[186:189], v[98:101]
	v_mfma_f32_16x16x32_bf16 v[86:89], v[210:213], v[194:197], v[86:89]
	v_mfma_f32_16x16x32_bf16 v[82:85], v[218:221], v[194:197], v[82:85]
	v_mfma_f32_16x16x32_bf16 v[70:73], v[210:213], v[202:205], v[70:73]
	v_mfma_f32_16x16x32_bf16 v[66:69], v[218:221], v[202:205], v[66:69]
	s_barrier
	s_setprio 0
	s_add_i32 s20, s54, s42
	v_lshl_add_u64 v[174:175], s[34:35], 0, v[150:151]
	s_mov_b32 m0, s20
	s_nop 0
	global_load_lds_dwordx4 v[174:175], off
	v_lshl_add_u64 v[222:223], s[34:35], 0, v[146:147]
	s_add_i32 m0, s20, 0x2000
	s_nop 0
	global_load_lds_dwordx4 v[222:223], off
	s_mov_b32 m0, s43
	v_lshl_add_u64 v[224:225], s[18:19], 0, v[152:153]
	ds_read_b128 v[166:169], v173 offset:16384
	ds_read_b128 v[178:181], v173 offset:17408
	ds_read_b128 v[182:185], v173 offset:18432
	ds_read_b128 v[186:189], v173 offset:19456
	ds_read_b128 v[190:193], v173 offset:20480
	ds_read_b128 v[194:197], v173 offset:21504
	ds_read_b128 v[198:201], v173 offset:22528
	ds_read_b128 v[202:205], v173 offset:23552
	global_load_lds_dwordx4 v[224:225], off
	v_lshl_add_u64 v[226:227], s[18:19], 0, v[148:149]
	s_mov_b32 m0, s44
	s_nop 0
	global_load_lds_dwordx4 v[226:227], off
	s_waitcnt vmcnt(6)
	s_waitcnt lgkmcnt(0)
	s_setprio 1
	s_barrier
	v_mfma_f32_16x16x32_bf16 v[62:65], v[130:133], v[166:169], v[62:65]
	v_mfma_f32_16x16x32_bf16 v[58:61], v[138:141], v[166:169], v[58:61]
	v_mfma_f32_16x16x32_bf16 v[46:49], v[130:133], v[182:185], v[46:49]
	v_mfma_f32_16x16x32_bf16 v[42:45], v[138:141], v[182:185], v[42:45]
	v_mfma_f32_16x16x32_bf16 v[30:33], v[130:133], v[190:193], v[30:33]
	v_mfma_f32_16x16x32_bf16 v[26:29], v[138:141], v[190:193], v[26:29]
	v_mfma_f32_16x16x32_bf16 v[14:17], v[130:133], v[198:201], v[14:17]
	v_mfma_f32_16x16x32_bf16 v[10:13], v[138:141], v[198:201], v[10:13]
	v_mfma_f32_16x16x32_bf16 v[62:65], v[134:137], v[178:181], v[62:65]
	v_mfma_f32_16x16x32_bf16 v[58:61], v[142:145], v[178:181], v[58:61]
	v_mfma_f32_16x16x32_bf16 v[46:49], v[134:137], v[186:189], v[46:49]
	v_mfma_f32_16x16x32_bf16 v[42:45], v[142:145], v[186:189], v[42:45]
	v_mfma_f32_16x16x32_bf16 v[30:33], v[134:137], v[194:197], v[30:33]
	v_mfma_f32_16x16x32_bf16 v[26:29], v[142:145], v[194:197], v[26:29]
	v_mfma_f32_16x16x32_bf16 v[14:17], v[134:137], v[202:205], v[14:17]
	v_mfma_f32_16x16x32_bf16 v[10:13], v[142:145], v[202:205], v[10:13]
	v_mfma_f32_16x16x32_bf16 v[54:57], v[206:209], v[166:169], v[54:57]
	v_mfma_f32_16x16x32_bf16 v[50:53], v[214:217], v[166:169], v[50:53]
	v_mfma_f32_16x16x32_bf16 v[38:41], v[206:209], v[182:185], v[38:41]
	v_mfma_f32_16x16x32_bf16 v[34:37], v[214:217], v[182:185], v[34:37]
	v_mfma_f32_16x16x32_bf16 v[22:25], v[206:209], v[190:193], v[22:25]
	v_mfma_f32_16x16x32_bf16 v[18:21], v[214:217], v[190:193], v[18:21]
	v_mfma_f32_16x16x32_bf16 v[6:9], v[206:209], v[198:201], v[6:9]
	v_mfma_f32_16x16x32_bf16 v[2:5], v[214:217], v[198:201], v[2:5]
	v_mfma_f32_16x16x32_bf16 v[54:57], v[210:213], v[178:181], v[54:57]
	v_mfma_f32_16x16x32_bf16 v[50:53], v[218:221], v[178:181], v[50:53]
	v_mfma_f32_16x16x32_bf16 v[38:41], v[210:213], v[186:189], v[38:41]
	v_mfma_f32_16x16x32_bf16 v[34:37], v[218:221], v[186:189], v[34:37]
	v_mfma_f32_16x16x32_bf16 v[22:25], v[210:213], v[194:197], v[22:25]
	v_mfma_f32_16x16x32_bf16 v[18:21], v[218:221], v[194:197], v[18:21]
	v_mfma_f32_16x16x32_bf16 v[6:9], v[210:213], v[202:205], v[6:9]
	v_mfma_f32_16x16x32_bf16 v[2:5], v[218:221], v[202:205], v[2:5]
	s_barrier
	s_setprio 0
	s_add_u32 s20, s34, 0x40000
	s_addc_u32 s21, s35, 0
	s_add_i32 s64, s55, s42
	v_lshl_add_u64 v[246:247], s[20:21], 0, v[150:151]
	s_mov_b32 m0, s64
	s_nop 0
	global_load_lds_dwordx4 v[246:247], off
	v_lshl_add_u64 v[246:247], s[20:21], 0, v[146:147]
	s_add_i32 m0, s64, 0x2000
	s_nop 0
	global_load_lds_dwordx4 v[246:247], off
	s_add_i32 s20, 0, 0x18000
	v_add_u32_e32 v142, s20, v157
	ds_read_b128 v[130:133], v142
	ds_read_b128 v[134:137], v142 offset:1024
	ds_read_b128 v[138:141], v142 offset:2048
	ds_read_b128 v[142:145], v142 offset:3072
	s_add_u32 s18, s18, 0x40000
	s_addc_u32 s19, s19, 0
	s_mov_b32 m0, s45
	v_lshl_add_u64 v[206:207], s[18:19], 0, v[152:153]
	ds_read_b128 v[166:169], v173 offset:32768
	ds_read_b128 v[178:181], v173 offset:33792
	ds_read_b128 v[182:185], v173 offset:34816
	ds_read_b128 v[186:189], v173 offset:35840
	ds_read_b128 v[190:193], v173 offset:36864
	ds_read_b128 v[194:197], v173 offset:37888
	ds_read_b128 v[198:201], v173 offset:38912
	ds_read_b128 v[202:205], v173 offset:39936
	global_load_lds_dwordx4 v[206:207], off
	v_lshl_add_u64 v[206:207], s[18:19], 0, v[148:149]
	s_mov_b32 m0, s46
	s_nop 0
	global_load_lds_dwordx4 v[206:207], off
	s_add_i32 s21, 0, 0x1c000
	v_add_u32_e32 v154, s21, v157
	ds_read_b128 v[206:209], v154
	ds_read_b128 v[210:213], v154 offset:1024
	ds_read_b128 v[214:217], v154 offset:2048
	ds_read_b128 v[218:221], v154 offset:3072
	s_waitcnt vmcnt(8)
	s_waitcnt lgkmcnt(0)
	s_setprio 1
	s_barrier
	v_mfma_f32_16x16x32_bf16 v[126:129], v[130:133], v[166:169], v[126:129]
	v_mfma_f32_16x16x32_bf16 v[122:125], v[138:141], v[166:169], v[122:125]
	v_mfma_f32_16x16x32_bf16 v[110:113], v[130:133], v[182:185], v[110:113]
	v_mfma_f32_16x16x32_bf16 v[106:109], v[138:141], v[182:185], v[106:109]
	v_mfma_f32_16x16x32_bf16 v[94:97], v[130:133], v[190:193], v[94:97]
	v_mfma_f32_16x16x32_bf16 v[90:93], v[138:141], v[190:193], v[90:93]
	v_mfma_f32_16x16x32_bf16 v[78:81], v[130:133], v[198:201], v[78:81]
	v_mfma_f32_16x16x32_bf16 v[74:77], v[138:141], v[198:201], v[74:77]
	v_mfma_f32_16x16x32_bf16 v[126:129], v[134:137], v[178:181], v[126:129]
	v_mfma_f32_16x16x32_bf16 v[122:125], v[142:145], v[178:181], v[122:125]
	v_mfma_f32_16x16x32_bf16 v[110:113], v[134:137], v[186:189], v[110:113]
	v_mfma_f32_16x16x32_bf16 v[106:109], v[142:145], v[186:189], v[106:109]
	v_mfma_f32_16x16x32_bf16 v[94:97], v[134:137], v[194:197], v[94:97]
	v_mfma_f32_16x16x32_bf16 v[90:93], v[142:145], v[194:197], v[90:93]
	v_mfma_f32_16x16x32_bf16 v[78:81], v[134:137], v[202:205], v[78:81]
	v_mfma_f32_16x16x32_bf16 v[74:77], v[142:145], v[202:205], v[74:77]
	v_mfma_f32_16x16x32_bf16 v[118:121], v[206:209], v[166:169], v[118:121]
	v_mfma_f32_16x16x32_bf16 v[114:117], v[214:217], v[166:169], v[114:117]
	v_mfma_f32_16x16x32_bf16 v[102:105], v[206:209], v[182:185], v[102:105]
	v_mfma_f32_16x16x32_bf16 v[98:101], v[214:217], v[182:185], v[98:101]
	v_mfma_f32_16x16x32_bf16 v[86:89], v[206:209], v[190:193], v[86:89]
	v_mfma_f32_16x16x32_bf16 v[82:85], v[214:217], v[190:193], v[82:85]
	v_mfma_f32_16x16x32_bf16 v[70:73], v[206:209], v[198:201], v[70:73]
	v_mfma_f32_16x16x32_bf16 v[66:69], v[214:217], v[198:201], v[66:69]
	v_mfma_f32_16x16x32_bf16 v[118:121], v[210:213], v[178:181], v[118:121]
	v_mfma_f32_16x16x32_bf16 v[114:117], v[218:221], v[178:181], v[114:117]
	v_mfma_f32_16x16x32_bf16 v[102:105], v[210:213], v[186:189], v[102:105]
	v_mfma_f32_16x16x32_bf16 v[98:101], v[218:221], v[186:189], v[98:101]
	v_mfma_f32_16x16x32_bf16 v[86:89], v[210:213], v[194:197], v[86:89]
	v_mfma_f32_16x16x32_bf16 v[82:85], v[218:221], v[194:197], v[82:85]
	v_mfma_f32_16x16x32_bf16 v[70:73], v[210:213], v[202:205], v[70:73]
	v_mfma_f32_16x16x32_bf16 v[66:69], v[218:221], v[202:205], v[66:69]
	s_barrier
	s_setprio 0
	s_add_i32 s18, s20, s42
	v_lshl_add_u64 v[174:175], v[174:175], 0, s[6:7]
	s_mov_b32 m0, s18
	s_nop 0
	global_load_lds_dwordx4 v[174:175], off
	v_lshl_add_u64 v[174:175], v[222:223], 0, s[6:7]
	s_add_i32 m0, s18, 0x2000
	s_nop 0
	global_load_lds_dwordx4 v[174:175], off
	s_mov_b32 m0, s50
	v_lshl_add_u64 v[174:175], v[224:225], 0, s[6:7]
	ds_read_b128 v[166:169], v173 offset:49152
	ds_read_b128 v[178:181], v173 offset:50176
	ds_read_b128 v[182:185], v173 offset:51200
	ds_read_b128 v[186:189], v173 offset:52224
	ds_read_b128 v[190:193], v173 offset:53248
	ds_read_b128 v[194:197], v173 offset:54272
	ds_read_b128 v[198:201], v173 offset:55296
	ds_read_b128 v[202:205], v173 offset:56320
	global_load_lds_dwordx4 v[174:175], off
	v_lshl_add_u64 v[174:175], v[226:227], 0, s[6:7]
	s_mov_b32 m0, s51
	s_nop 0
	global_load_lds_dwordx4 v[174:175], off
	s_add_u32 s18, s34, 0x40080
	s_addc_u32 s19, s35, 0
	s_add_i32 s20, s21, s42
	v_lshl_add_u64 v[248:249], s[18:19], 0, v[150:151]
	s_mov_b32 m0, s20
	s_nop 0
	global_load_lds_dwordx4 v[248:249], off
	v_lshl_add_u64 v[248:249], s[18:19], 0, v[146:147]
	s_add_i32 m0, s20, 0x2000
	s_nop 0
	global_load_lds_dwordx4 v[248:249], off
	s_waitcnt vmcnt(6)
	s_waitcnt lgkmcnt(0)
	s_setprio 1
	s_barrier
	v_mfma_f32_16x16x32_bf16 v[62:65], v[130:133], v[166:169], v[62:65]
	v_mfma_f32_16x16x32_bf16 v[58:61], v[138:141], v[166:169], v[58:61]
	v_mfma_f32_16x16x32_bf16 v[46:49], v[130:133], v[182:185], v[46:49]
	v_mfma_f32_16x16x32_bf16 v[42:45], v[138:141], v[182:185], v[42:45]
	v_mfma_f32_16x16x32_bf16 v[30:33], v[130:133], v[190:193], v[30:33]
	v_mfma_f32_16x16x32_bf16 v[26:29], v[138:141], v[190:193], v[26:29]
	v_mfma_f32_16x16x32_bf16 v[14:17], v[130:133], v[198:201], v[14:17]
	v_mfma_f32_16x16x32_bf16 v[10:13], v[138:141], v[198:201], v[10:13]
	v_mfma_f32_16x16x32_bf16 v[62:65], v[134:137], v[178:181], v[62:65]
	v_mfma_f32_16x16x32_bf16 v[58:61], v[142:145], v[178:181], v[58:61]
	v_mfma_f32_16x16x32_bf16 v[46:49], v[134:137], v[186:189], v[46:49]
	v_mfma_f32_16x16x32_bf16 v[42:45], v[142:145], v[186:189], v[42:45]
	v_mfma_f32_16x16x32_bf16 v[30:33], v[134:137], v[194:197], v[30:33]
	v_mfma_f32_16x16x32_bf16 v[26:29], v[142:145], v[194:197], v[26:29]
	v_mfma_f32_16x16x32_bf16 v[14:17], v[134:137], v[202:205], v[14:17]
	v_mfma_f32_16x16x32_bf16 v[10:13], v[142:145], v[202:205], v[10:13]
	v_mfma_f32_16x16x32_bf16 v[54:57], v[206:209], v[166:169], v[54:57]
	v_mfma_f32_16x16x32_bf16 v[50:53], v[214:217], v[166:169], v[50:53]
	v_mfma_f32_16x16x32_bf16 v[38:41], v[206:209], v[182:185], v[38:41]
	v_mfma_f32_16x16x32_bf16 v[34:37], v[214:217], v[182:185], v[34:37]
	v_mfma_f32_16x16x32_bf16 v[22:25], v[206:209], v[190:193], v[22:25]
	v_mfma_f32_16x16x32_bf16 v[18:21], v[214:217], v[190:193], v[18:21]
	v_mfma_f32_16x16x32_bf16 v[6:9], v[206:209], v[198:201], v[6:9]
	v_mfma_f32_16x16x32_bf16 v[2:5], v[214:217], v[198:201], v[2:5]
	v_mfma_f32_16x16x32_bf16 v[54:57], v[210:213], v[178:181], v[54:57]
	v_mfma_f32_16x16x32_bf16 v[50:53], v[218:221], v[178:181], v[50:53]
	v_mfma_f32_16x16x32_bf16 v[38:41], v[210:213], v[186:189], v[38:41]
	v_mfma_f32_16x16x32_bf16 v[34:37], v[218:221], v[186:189], v[34:37]
	v_mfma_f32_16x16x32_bf16 v[22:25], v[210:213], v[194:197], v[22:25]
	v_mfma_f32_16x16x32_bf16 v[18:21], v[218:221], v[194:197], v[18:21]
	v_mfma_f32_16x16x32_bf16 v[6:9], v[210:213], v[202:205], v[6:9]
	v_mfma_f32_16x16x32_bf16 v[2:5], v[218:221], v[202:205], v[2:5]
	s_add_i32 s63, s63, 2
	s_add_u32 s24, s24, 0x100
	s_addc_u32 s25, s25, 0
	s_add_u32 s61, s61, 0x100
	s_addc_u32 s62, s62, 0
	s_cmp_gt_u32 s63, 13
	s_cbranch_scc0 .Ldfr_p12_r
	s_cmpk_gt_u32 s33, 0xff
	s_cbranch_scc1 .Ldfr_p12_b
	s_barrier
.Ldfr_p12_b:
	s_setprio 0
	s_ashr_i32 s9, s16, 3
	s_mul_hi_i32 s11, s9, 0x5800
	s_mulk_i32 s9, 0x5800
	s_add_u32 s9, s48, s9
	s_addc_u32 s11, s49, s11
	s_lshl_b32 s18, s17, 8
	s_ashr_i32 s19, s18, 31
	s_lshl_b64 s[18:19], s[18:19], 2
	v_lshl_add_u32 v180, s16, 8, v1
	s_add_u32 s18, s9, s18
	s_addc_u32 s19, s11, s19
	v_lshlrev_b32_e32 v130, 2, v156
	v_ashrrev_i32_e32 v181, 31, v180
	global_load_dwordx4 v[142:145], v130, s[18:19]
	v_lshl_add_u64 v[182:183], v[180:181], 2, s[4:5]
	global_load_dword v190, v[182:183], off
	global_load_dwordx4 v[138:141], v130, s[18:19] offset:512
	global_load_dwordx4 v[134:137], v130, s[18:19] offset:16
	s_nop 0
	global_load_dwordx4 v[130:133], v130, s[18:19] offset:528
	v_or_b32_e32 v192, 16, v180
	v_ashrrev_i32_e32 v193, 31, v192
	v_lshl_add_u64 v[168:169], v[192:193], 2, s[4:5]
	global_load_dword v194, v[168:169], off
	v_or_b32_e32 v188, 32, v180
	v_or_b32_e32 v184, 48, v180
	v_mov_b64_e32 v[166:167], s[0:1]
	v_add_u32_e32 v178, 0x90, v180
	v_add_u32_e32 v174, 0xa0, v180
	v_add_u32_e32 v168, 0xb0, v180
	v_ashrrev_i32_e32 v189, 31, v188
	v_ashrrev_i32_e32 v185, 31, v184
	v_add_u32_e32 v193, 0x80, v180
	v_mad_i64_i32 v[196:197], s[18:19], v180, s56, v[166:167]
	v_ashrrev_i32_e32 v179, 31, v178
	v_ashrrev_i32_e32 v175, 31, v174
	v_ashrrev_i32_e32 v169, 31, v168
	v_lshl_add_u64 v[180:181], v[188:189], 2, s[4:5]
	v_lshl_add_u64 v[186:187], v[184:185], 2, s[4:5]
	v_lshl_add_u64 v[198:199], v[178:179], 2, s[4:5]
	v_lshl_add_u64 v[200:201], v[174:175], 2, s[4:5]
	v_lshl_add_u64 v[202:203], v[168:169], 2, s[4:5]
	global_load_dword v204, v[180:181], off
	s_nop 0
	global_load_dword v186, v[186:187], off
	s_nop 0
	global_load_dword v180, v[198:199], off
	global_load_dword v176, v[200:201], off
	global_load_dword v172, v[202:203], off
	s_nop 0
	global_load_dword v182, v[182:183], off offset:512
	s_lshl_b32 s16, s17, 7
	s_ashr_i32 s17, s16, 31
	s_lshl_b64 s[16:17], s[16:17], 1
	v_lshlrev_b32_e32 v154, 1, v156
	v_lshl_add_u64 v[196:197], v[196:197], 0, s[16:17]
	s_and_b64 vcc, exec, s[2:3]
	s_mov_b64 s[34:35], s[14:15]
	s_mov_b64 s[24:25], s[12:13]
	s_waitcnt vmcnt(0)
	v_pk_fma_f32 v[118:119], v[118:119], v[190:191], v[138:139] op_sel_hi:[1,0,1]
	v_pk_fma_f32 v[126:127], v[126:127], v[190:191], v[142:143] op_sel_hi:[1,0,1]
	v_pk_fma_f32 v[128:129], v[128:129], v[190:191], v[144:145] op_sel_hi:[1,0,1]
	v_pk_fma_f32 v[122:123], v[122:123], v[190:191], v[134:135] op_sel_hi:[1,0,1]
	v_pk_fma_f32 v[124:125], v[124:125], v[190:191], v[136:137] op_sel_hi:[1,0,1]
	v_mul_f32_e32 v169, 0xbfb8aa3b, v126
	v_mul_f32_e32 v175, 0xbfb8aa3b, v127
	v_mul_f32_e32 v179, 0xbfb8aa3b, v128
	v_mul_f32_e32 v181, 0xbfb8aa3b, v129
	v_mul_f32_e32 v183, 0xbfb8aa3b, v122
	v_mul_f32_e32 v185, 0xbfb8aa3b, v123
	v_mul_f32_e32 v187, 0xbfb8aa3b, v124
	v_mul_f32_e32 v189, 0xbfb8aa3b, v125
	v_exp_f32_e32 v169, v169
	v_exp_f32_e32 v175, v175
	v_exp_f32_e32 v179, v179
	v_exp_f32_e32 v181, v181
	v_exp_f32_e32 v183, v183
	v_exp_f32_e32 v185, v185
	v_exp_f32_e32 v187, v187
	v_exp_f32_e32 v189, v189
	v_add_f32_e32 v169, 1.0, v169
	v_add_f32_e32 v175, 1.0, v175
	v_add_f32_e32 v179, 1.0, v179
	v_add_f32_e32 v181, 1.0, v181
	v_add_f32_e32 v183, 1.0, v183
	v_add_f32_e32 v185, 1.0, v185
	v_add_f32_e32 v187, 1.0, v187
	v_add_f32_e32 v189, 1.0, v189
	v_pk_fma_f32 v[120:121], v[120:121], v[190:191], v[140:141] op_sel_hi:[1,0,1]
	v_pk_fma_f32 v[114:115], v[114:115], v[190:191], v[130:131] op_sel_hi:[1,0,1]
	v_pk_fma_f32 v[116:117], v[116:117], v[190:191], v[132:133] op_sel_hi:[1,0,1]
	v_rcp_f32_e32 v190, v169
	v_rcp_f32_e32 v191, v175
	v_rcp_f32_e32 v198, v179
	v_rcp_f32_e32 v199, v181
	v_rcp_f32_e32 v200, v183
	v_rcp_f32_e32 v201, v185
	v_rcp_f32_e32 v202, v187
	v_rcp_f32_e32 v203, v189
	v_pk_mul_f32 v[126:127], v[126:127], v[190:191]
	v_pk_mul_f32 v[128:129], v[128:129], v[198:199]
	v_pk_mul_f32 v[122:123], v[122:123], v[200:201]
	v_pk_mul_f32 v[124:125], v[124:125], v[202:203]
	v_pk_mul_f32 v[118:119], v[118:119], v[126:127]
	v_pk_mul_f32 v[120:121], v[120:121], v[128:129]
	v_pk_mul_f32 v[122:123], v[114:115], v[122:123]
	v_pk_mul_f32 v[124:125], v[116:117], v[124:125]
	v_pk_fma_f32 v[110:111], v[110:111], v[194:195], v[142:143] op_sel_hi:[1,0,1]
	v_lshl_add_u64 v[126:127], v[196:197], 0, v[154:155]
	v_cvt_pk_bf16_f32 v114, v118, v119
	v_cvt_pk_bf16_f32 v115, v120, v121
	v_cvt_pk_bf16_f32 v116, v122, v123
	v_cvt_pk_bf16_f32 v117, v124, v125
	v_mul_f32_e32 v118, 0xbfb8aa3b, v110
	v_mul_f32_e32 v119, 0xbfb8aa3b, v111
	v_pk_fma_f32 v[112:113], v[112:113], v[194:195], v[144:145] op_sel_hi:[1,0,1]
	v_exp_f32_e32 v118, v118
	v_exp_f32_e32 v119, v119
	global_store_dwordx4 v[126:127], v[114:117], off nt
	v_pk_fma_f32 v[102:103], v[102:103], v[194:195], v[138:139] op_sel_hi:[1,0,1]
	v_pk_fma_f32 v[106:107], v[106:107], v[194:195], v[134:135] op_sel_hi:[1,0,1]
	v_mul_f32_e32 v116, 0xbfb8aa3b, v112
	v_mul_f32_e32 v117, 0xbfb8aa3b, v113
	v_exp_f32_e32 v116, v116
	v_exp_f32_e32 v117, v117
	v_add_f32_e32 v114, 1.0, v118
	v_add_f32_e32 v115, 1.0, v119
	v_rcp_f32_e32 v114, v114
	v_rcp_f32_e32 v115, v115
	v_add_f32_e32 v116, 1.0, v116
	v_add_f32_e32 v117, 1.0, v117
	v_rcp_f32_e32 v116, v116
	v_rcp_f32_e32 v117, v117
	v_pk_mul_f32 v[110:111], v[110:111], v[114:115]
	v_pk_fma_f32 v[104:105], v[104:105], v[194:195], v[140:141] op_sel_hi:[1,0,1]
	v_pk_mul_f32 v[102:103], v[102:103], v[110:111]
	v_pk_mul_f32 v[110:111], v[112:113], v[116:117]
	v_mul_f32_e32 v112, 0xbfb8aa3b, v106
	v_mul_f32_e32 v113, 0xbfb8aa3b, v107
	v_exp_f32_e32 v112, v112
	v_exp_f32_e32 v113, v113
	v_pk_fma_f32 v[108:109], v[108:109], v[194:195], v[136:137] op_sel_hi:[1,0,1]
	v_pk_mul_f32 v[104:105], v[104:105], v[110:111]
	v_add_f32_e32 v110, 1.0, v112
	v_add_f32_e32 v111, 1.0, v113
	v_mul_f32_e32 v112, 0xbfb8aa3b, v108
	v_mul_f32_e32 v113, 0xbfb8aa3b, v109
	v_exp_f32_e32 v112, v112
	v_exp_f32_e32 v113, v113
	v_rcp_f32_e32 v110, v110
	v_rcp_f32_e32 v111, v111
	v_add_f32_e32 v112, 1.0, v112
	v_add_f32_e32 v113, 1.0, v113
	v_rcp_f32_e32 v112, v112
	v_rcp_f32_e32 v113, v113
	v_pk_mul_f32 v[106:107], v[106:107], v[110:111]
	v_pk_fma_f32 v[98:99], v[98:99], v[194:195], v[130:131] op_sel_hi:[1,0,1]
	v_pk_fma_f32 v[100:101], v[100:101], v[194:195], v[132:133] op_sel_hi:[1,0,1]
	v_pk_mul_f32 v[106:107], v[98:99], v[106:107]
	v_pk_mul_f32 v[98:99], v[108:109], v[112:113]
	v_pk_fma_f32 v[94:95], v[94:95], v[204:205], v[142:143] op_sel_hi:[1,0,1]
	v_pk_mul_f32 v[108:109], v[100:101], v[98:99]
	v_mad_i64_i32 v[98:99], s[18:19], v192, s56, v[166:167]
	v_lshl_add_u64 v[98:99], v[98:99], 0, s[16:17]
	v_lshl_add_u64 v[110:111], v[98:99], 0, v[154:155]
	v_cvt_pk_bf16_f32 v98, v102, v103
	v_cvt_pk_bf16_f32 v99, v104, v105
	v_cvt_pk_bf16_f32 v100, v106, v107
	v_cvt_pk_bf16_f32 v101, v108, v109
	v_mul_f32_e32 v102, 0xbfb8aa3b, v94
	v_mul_f32_e32 v103, 0xbfb8aa3b, v95
	v_pk_fma_f32 v[96:97], v[96:97], v[204:205], v[144:145] op_sel_hi:[1,0,1]
	v_exp_f32_e32 v102, v102
	v_exp_f32_e32 v103, v103
	global_store_dwordx4 v[110:111], v[98:101], off nt
	v_pk_fma_f32 v[86:87], v[86:87], v[204:205], v[138:139] op_sel_hi:[1,0,1]
	v_pk_fma_f32 v[90:91], v[90:91], v[204:205], v[134:135] op_sel_hi:[1,0,1]
	v_mul_f32_e32 v100, 0xbfb8aa3b, v96
	v_mul_f32_e32 v101, 0xbfb8aa3b, v97
	v_exp_f32_e32 v100, v100
	v_exp_f32_e32 v101, v101
	v_add_f32_e32 v98, 1.0, v102
	v_add_f32_e32 v99, 1.0, v103
	v_rcp_f32_e32 v98, v98
	v_rcp_f32_e32 v99, v99
	v_add_f32_e32 v100, 1.0, v100
	v_add_f32_e32 v101, 1.0, v101
	v_rcp_f32_e32 v100, v100
	v_rcp_f32_e32 v101, v101
	v_pk_mul_f32 v[94:95], v[94:95], v[98:99]
	v_pk_fma_f32 v[88:89], v[88:89], v[204:205], v[140:141] op_sel_hi:[1,0,1]
	v_pk_mul_f32 v[86:87], v[86:87], v[94:95]
	v_pk_mul_f32 v[94:95], v[96:97], v[100:101]
	v_mul_f32_e32 v96, 0xbfb8aa3b, v90
	v_mul_f32_e32 v97, 0xbfb8aa3b, v91
	v_exp_f32_e32 v96, v96
	v_exp_f32_e32 v97, v97
	v_pk_fma_f32 v[92:93], v[92:93], v[204:205], v[136:137] op_sel_hi:[1,0,1]
	v_pk_mul_f32 v[88:89], v[88:89], v[94:95]
	v_add_f32_e32 v94, 1.0, v96
	v_add_f32_e32 v95, 1.0, v97
	v_mul_f32_e32 v96, 0xbfb8aa3b, v92
	v_mul_f32_e32 v97, 0xbfb8aa3b, v93
	v_exp_f32_e32 v96, v96
	v_exp_f32_e32 v97, v97
	v_rcp_f32_e32 v94, v94
	v_rcp_f32_e32 v95, v95
	v_add_f32_e32 v96, 1.0, v96
	v_add_f32_e32 v97, 1.0, v97
	v_rcp_f32_e32 v96, v96
	v_rcp_f32_e32 v97, v97
	v_pk_mul_f32 v[90:91], v[90:91], v[94:95]
	v_pk_fma_f32 v[82:83], v[82:83], v[204:205], v[130:131] op_sel_hi:[1,0,1]
	v_pk_fma_f32 v[84:85], v[84:85], v[204:205], v[132:133] op_sel_hi:[1,0,1]
	v_pk_mul_f32 v[90:91], v[82:83], v[90:91]
	v_pk_mul_f32 v[82:83], v[92:93], v[96:97]
	v_pk_fma_f32 v[78:79], v[78:79], v[186:187], v[142:143] op_sel_hi:[1,0,1]
	v_pk_mul_f32 v[92:93], v[84:85], v[82:83]
	v_mad_i64_i32 v[82:83], s[18:19], v188, s56, v[166:167]
	v_lshl_add_u64 v[82:83], v[82:83], 0, s[16:17]
	v_lshl_add_u64 v[94:95], v[82:83], 0, v[154:155]
	v_cvt_pk_bf16_f32 v82, v86, v87
	v_cvt_pk_bf16_f32 v83, v88, v89
	v_cvt_pk_bf16_f32 v84, v90, v91
	v_cvt_pk_bf16_f32 v85, v92, v93
	v_mul_f32_e32 v86, 0xbfb8aa3b, v78
	v_mul_f32_e32 v87, 0xbfb8aa3b, v79
	v_pk_fma_f32 v[80:81], v[80:81], v[186:187], v[144:145] op_sel_hi:[1,0,1]
	v_exp_f32_e32 v86, v86
	v_exp_f32_e32 v87, v87
	global_store_dwordx4 v[94:95], v[82:85], off nt
	v_pk_fma_f32 v[70:71], v[70:71], v[186:187], v[138:139] op_sel_hi:[1,0,1]
	v_pk_fma_f32 v[74:75], v[74:75], v[186:187], v[134:135] op_sel_hi:[1,0,1]
	v_mul_f32_e32 v84, 0xbfb8aa3b, v80
	v_mul_f32_e32 v85, 0xbfb8aa3b, v81
	v_exp_f32_e32 v84, v84
	v_exp_f32_e32 v85, v85
	v_add_f32_e32 v82, 1.0, v86
	v_add_f32_e32 v83, 1.0, v87
	v_rcp_f32_e32 v82, v82
	v_rcp_f32_e32 v83, v83
	v_add_f32_e32 v84, 1.0, v84
	v_add_f32_e32 v85, 1.0, v85
	v_rcp_f32_e32 v84, v84
	v_rcp_f32_e32 v85, v85
	v_pk_mul_f32 v[78:79], v[78:79], v[82:83]
	v_pk_fma_f32 v[72:73], v[72:73], v[186:187], v[140:141] op_sel_hi:[1,0,1]
	v_pk_mul_f32 v[70:71], v[70:71], v[78:79]
	v_pk_mul_f32 v[78:79], v[80:81], v[84:85]
	v_mul_f32_e32 v80, 0xbfb8aa3b, v74
	v_mul_f32_e32 v81, 0xbfb8aa3b, v75
	v_exp_f32_e32 v80, v80
	v_exp_f32_e32 v81, v81
	v_pk_fma_f32 v[76:77], v[76:77], v[186:187], v[136:137] op_sel_hi:[1,0,1]
	v_pk_mul_f32 v[72:73], v[72:73], v[78:79]
	v_add_f32_e32 v78, 1.0, v80
	v_add_f32_e32 v79, 1.0, v81
	v_mul_f32_e32 v80, 0xbfb8aa3b, v76
	v_mul_f32_e32 v81, 0xbfb8aa3b, v77
	v_exp_f32_e32 v80, v80
	v_exp_f32_e32 v81, v81
	v_rcp_f32_e32 v78, v78
	v_rcp_f32_e32 v79, v79
	v_add_f32_e32 v80, 1.0, v80
	v_add_f32_e32 v81, 1.0, v81
	v_rcp_f32_e32 v80, v80
	v_rcp_f32_e32 v81, v81
	v_pk_mul_f32 v[74:75], v[74:75], v[78:79]
	v_pk_fma_f32 v[66:67], v[66:67], v[186:187], v[130:131] op_sel_hi:[1,0,1]
	v_pk_fma_f32 v[68:69], v[68:69], v[186:187], v[132:133] op_sel_hi:[1,0,1]
	v_pk_mul_f32 v[74:75], v[66:67], v[74:75]
	v_pk_mul_f32 v[66:67], v[76:77], v[80:81]
	v_pk_fma_f32 v[62:63], v[62:63], v[182:183], v[142:143] op_sel_hi:[1,0,1]
	v_pk_mul_f32 v[76:77], v[68:69], v[66:67]
	v_mad_i64_i32 v[66:67], s[18:19], v184, s56, v[166:167]
	v_lshl_add_u64 v[66:67], v[66:67], 0, s[16:17]
	v_lshl_add_u64 v[78:79], v[66:67], 0, v[154:155]
	v_cvt_pk_bf16_f32 v66, v70, v71
	v_cvt_pk_bf16_f32 v67, v72, v73
	v_cvt_pk_bf16_f32 v68, v74, v75
	v_cvt_pk_bf16_f32 v69, v76, v77
	v_mul_f32_e32 v70, 0xbfb8aa3b, v62
	v_mul_f32_e32 v71, 0xbfb8aa3b, v63
	v_pk_fma_f32 v[64:65], v[64:65], v[182:183], v[144:145] op_sel_hi:[1,0,1]
	v_exp_f32_e32 v70, v70
	v_exp_f32_e32 v71, v71
	global_store_dwordx4 v[78:79], v[66:69], off nt
	v_pk_fma_f32 v[54:55], v[54:55], v[182:183], v[138:139] op_sel_hi:[1,0,1]
	v_pk_fma_f32 v[58:59], v[58:59], v[182:183], v[134:135] op_sel_hi:[1,0,1]
	v_mul_f32_e32 v68, 0xbfb8aa3b, v64
	v_mul_f32_e32 v69, 0xbfb8aa3b, v65
	v_exp_f32_e32 v68, v68
	v_exp_f32_e32 v69, v69
	v_add_f32_e32 v66, 1.0, v70
	v_add_f32_e32 v67, 1.0, v71
	v_rcp_f32_e32 v66, v66
	v_rcp_f32_e32 v67, v67
	v_add_f32_e32 v68, 1.0, v68
	v_add_f32_e32 v69, 1.0, v69
	v_rcp_f32_e32 v68, v68
	v_rcp_f32_e32 v69, v69
	v_pk_mul_f32 v[62:63], v[62:63], v[66:67]
	v_pk_fma_f32 v[56:57], v[56:57], v[182:183], v[140:141] op_sel_hi:[1,0,1]
	v_pk_mul_f32 v[54:55], v[54:55], v[62:63]
	v_pk_mul_f32 v[62:63], v[64:65], v[68:69]
	v_mul_f32_e32 v64, 0xbfb8aa3b, v58
	v_mul_f32_e32 v65, 0xbfb8aa3b, v59
	v_exp_f32_e32 v64, v64
	v_exp_f32_e32 v65, v65
	v_pk_fma_f32 v[60:61], v[60:61], v[182:183], v[136:137] op_sel_hi:[1,0,1]
	v_pk_mul_f32 v[56:57], v[56:57], v[62:63]
	v_add_f32_e32 v62, 1.0, v64
	v_add_f32_e32 v63, 1.0, v65
	v_mul_f32_e32 v64, 0xbfb8aa3b, v60
	v_mul_f32_e32 v65, 0xbfb8aa3b, v61
	v_exp_f32_e32 v64, v64
	v_exp_f32_e32 v65, v65
	v_rcp_f32_e32 v62, v62
	v_rcp_f32_e32 v63, v63
	v_add_f32_e32 v64, 1.0, v64
	v_add_f32_e32 v65, 1.0, v65
	v_rcp_f32_e32 v64, v64
	v_rcp_f32_e32 v65, v65
	v_pk_mul_f32 v[58:59], v[58:59], v[62:63]
	v_pk_fma_f32 v[50:51], v[50:51], v[182:183], v[130:131] op_sel_hi:[1,0,1]
	v_pk_fma_f32 v[52:53], v[52:53], v[182:183], v[132:133] op_sel_hi:[1,0,1]
	v_pk_mul_f32 v[58:59], v[50:51], v[58:59]
	v_pk_mul_f32 v[50:51], v[60:61], v[64:65]
	v_pk_fma_f32 v[46:47], v[46:47], v[180:181], v[142:143] op_sel_hi:[1,0,1]
	v_pk_mul_f32 v[60:61], v[52:53], v[50:51]
	v_mad_i64_i32 v[50:51], s[18:19], v193, s56, v[166:167]
	v_lshl_add_u64 v[50:51], v[50:51], 0, s[16:17]
	v_lshl_add_u64 v[62:63], v[50:51], 0, v[154:155]
	v_cvt_pk_bf16_f32 v50, v54, v55
	v_cvt_pk_bf16_f32 v51, v56, v57
	v_cvt_pk_bf16_f32 v52, v58, v59
	v_cvt_pk_bf16_f32 v53, v60, v61
	v_mul_f32_e32 v54, 0xbfb8aa3b, v46
	v_mul_f32_e32 v55, 0xbfb8aa3b, v47
	v_pk_fma_f32 v[48:49], v[48:49], v[180:181], v[144:145] op_sel_hi:[1,0,1]
	v_exp_f32_e32 v54, v54
	v_exp_f32_e32 v55, v55
	global_store_dwordx4 v[62:63], v[50:53], off nt
	v_pk_fma_f32 v[38:39], v[38:39], v[180:181], v[138:139] op_sel_hi:[1,0,1]
	v_pk_fma_f32 v[42:43], v[42:43], v[180:181], v[134:135] op_sel_hi:[1,0,1]
	v_mul_f32_e32 v52, 0xbfb8aa3b, v48
	v_mul_f32_e32 v53, 0xbfb8aa3b, v49
	v_exp_f32_e32 v52, v52
	v_exp_f32_e32 v53, v53
	v_add_f32_e32 v50, 1.0, v54
	v_add_f32_e32 v51, 1.0, v55
	v_rcp_f32_e32 v50, v50
	v_rcp_f32_e32 v51, v51
	v_add_f32_e32 v52, 1.0, v52
	v_add_f32_e32 v53, 1.0, v53
	v_rcp_f32_e32 v52, v52
	v_rcp_f32_e32 v53, v53
	v_pk_mul_f32 v[46:47], v[46:47], v[50:51]
	v_pk_fma_f32 v[40:41], v[40:41], v[180:181], v[140:141] op_sel_hi:[1,0,1]
	v_pk_mul_f32 v[38:39], v[38:39], v[46:47]
	v_pk_mul_f32 v[46:47], v[48:49], v[52:53]
	v_mul_f32_e32 v48, 0xbfb8aa3b, v42
	v_mul_f32_e32 v49, 0xbfb8aa3b, v43
	v_exp_f32_e32 v48, v48
	v_exp_f32_e32 v49, v49
	v_pk_fma_f32 v[44:45], v[44:45], v[180:181], v[136:137] op_sel_hi:[1,0,1]
	v_pk_mul_f32 v[40:41], v[40:41], v[46:47]
	v_add_f32_e32 v46, 1.0, v48
	v_add_f32_e32 v47, 1.0, v49
	v_mul_f32_e32 v48, 0xbfb8aa3b, v44
	v_mul_f32_e32 v49, 0xbfb8aa3b, v45
	v_exp_f32_e32 v48, v48
	v_exp_f32_e32 v49, v49
	v_rcp_f32_e32 v46, v46
	v_rcp_f32_e32 v47, v47
	v_add_f32_e32 v48, 1.0, v48
	v_add_f32_e32 v49, 1.0, v49
	v_rcp_f32_e32 v48, v48
	v_rcp_f32_e32 v49, v49
	v_pk_mul_f32 v[42:43], v[42:43], v[46:47]
	v_pk_fma_f32 v[34:35], v[34:35], v[180:181], v[130:131] op_sel_hi:[1,0,1]
	v_pk_fma_f32 v[36:37], v[36:37], v[180:181], v[132:133] op_sel_hi:[1,0,1]
	v_pk_mul_f32 v[42:43], v[34:35], v[42:43]
	v_pk_mul_f32 v[34:35], v[44:45], v[48:49]
	v_pk_fma_f32 v[30:31], v[30:31], v[176:177], v[142:143] op_sel_hi:[1,0,1]
	v_pk_mul_f32 v[44:45], v[36:37], v[34:35]
	v_mad_i64_i32 v[34:35], s[18:19], v178, s56, v[166:167]
	v_lshl_add_u64 v[34:35], v[34:35], 0, s[16:17]
	v_lshl_add_u64 v[46:47], v[34:35], 0, v[154:155]
	v_cvt_pk_bf16_f32 v34, v38, v39
	v_cvt_pk_bf16_f32 v35, v40, v41
	v_cvt_pk_bf16_f32 v36, v42, v43
	v_cvt_pk_bf16_f32 v37, v44, v45
	v_mul_f32_e32 v38, 0xbfb8aa3b, v30
	v_mul_f32_e32 v39, 0xbfb8aa3b, v31
	v_pk_fma_f32 v[32:33], v[32:33], v[176:177], v[144:145] op_sel_hi:[1,0,1]
	v_exp_f32_e32 v38, v38
	v_exp_f32_e32 v39, v39
	global_store_dwordx4 v[46:47], v[34:37], off nt
	v_pk_fma_f32 v[22:23], v[22:23], v[176:177], v[138:139] op_sel_hi:[1,0,1]
	v_pk_fma_f32 v[26:27], v[26:27], v[176:177], v[134:135] op_sel_hi:[1,0,1]
	v_mul_f32_e32 v36, 0xbfb8aa3b, v32
	v_mul_f32_e32 v37, 0xbfb8aa3b, v33
	v_exp_f32_e32 v36, v36
	v_exp_f32_e32 v37, v37
	v_add_f32_e32 v34, 1.0, v38
	v_add_f32_e32 v35, 1.0, v39
	v_rcp_f32_e32 v34, v34
	v_rcp_f32_e32 v35, v35
	v_add_f32_e32 v36, 1.0, v36
	v_add_f32_e32 v37, 1.0, v37
	v_rcp_f32_e32 v36, v36
	v_rcp_f32_e32 v37, v37
	v_pk_mul_f32 v[30:31], v[30:31], v[34:35]
	v_pk_fma_f32 v[24:25], v[24:25], v[176:177], v[140:141] op_sel_hi:[1,0,1]
	v_pk_mul_f32 v[22:23], v[22:23], v[30:31]
	v_pk_mul_f32 v[30:31], v[32:33], v[36:37]
	v_mul_f32_e32 v32, 0xbfb8aa3b, v26
	v_mul_f32_e32 v33, 0xbfb8aa3b, v27
	v_exp_f32_e32 v32, v32
	v_exp_f32_e32 v33, v33
	v_pk_fma_f32 v[28:29], v[28:29], v[176:177], v[136:137] op_sel_hi:[1,0,1]
	v_pk_mul_f32 v[24:25], v[24:25], v[30:31]
	v_add_f32_e32 v30, 1.0, v32
	v_add_f32_e32 v31, 1.0, v33
	v_mul_f32_e32 v32, 0xbfb8aa3b, v28
	v_mul_f32_e32 v33, 0xbfb8aa3b, v29
	v_exp_f32_e32 v32, v32
	v_exp_f32_e32 v33, v33
	v_rcp_f32_e32 v30, v30
	v_rcp_f32_e32 v31, v31
	v_add_f32_e32 v32, 1.0, v32
	v_add_f32_e32 v33, 1.0, v33
	v_rcp_f32_e32 v32, v32
	v_rcp_f32_e32 v33, v33
	v_pk_mul_f32 v[26:27], v[26:27], v[30:31]
	v_pk_fma_f32 v[18:19], v[18:19], v[176:177], v[130:131] op_sel_hi:[1,0,1]
	v_pk_fma_f32 v[20:21], v[20:21], v[176:177], v[132:133] op_sel_hi:[1,0,1]
	v_pk_mul_f32 v[26:27], v[18:19], v[26:27]
	v_pk_mul_f32 v[18:19], v[28:29], v[32:33]
	v_pk_fma_f32 v[14:15], v[14:15], v[172:173], v[142:143] op_sel_hi:[1,0,1]
	v_pk_mul_f32 v[28:29], v[20:21], v[18:19]
	v_mad_i64_i32 v[18:19], s[18:19], v174, s56, v[166:167]
	v_lshl_add_u64 v[18:19], v[18:19], 0, s[16:17]
	v_lshl_add_u64 v[30:31], v[18:19], 0, v[154:155]
	v_cvt_pk_bf16_f32 v18, v22, v23
	v_cvt_pk_bf16_f32 v19, v24, v25
	v_cvt_pk_bf16_f32 v20, v26, v27
	v_cvt_pk_bf16_f32 v21, v28, v29
	v_mul_f32_e32 v22, 0xbfb8aa3b, v14
	v_mul_f32_e32 v23, 0xbfb8aa3b, v15
	v_pk_fma_f32 v[16:17], v[16:17], v[172:173], v[144:145] op_sel_hi:[1,0,1]
	v_exp_f32_e32 v22, v22
	v_exp_f32_e32 v23, v23
	global_store_dwordx4 v[30:31], v[18:21], off nt
	v_pk_fma_f32 v[6:7], v[6:7], v[172:173], v[138:139] op_sel_hi:[1,0,1]
	v_pk_fma_f32 v[10:11], v[10:11], v[172:173], v[134:135] op_sel_hi:[1,0,1]
	v_mul_f32_e32 v20, 0xbfb8aa3b, v16
	v_mul_f32_e32 v21, 0xbfb8aa3b, v17
	v_exp_f32_e32 v20, v20
	v_exp_f32_e32 v21, v21
	v_add_f32_e32 v18, 1.0, v22
	v_add_f32_e32 v19, 1.0, v23
	v_rcp_f32_e32 v18, v18
	v_rcp_f32_e32 v19, v19
	v_add_f32_e32 v20, 1.0, v20
	v_add_f32_e32 v21, 1.0, v21
	v_rcp_f32_e32 v20, v20
	v_rcp_f32_e32 v21, v21
	v_pk_mul_f32 v[14:15], v[14:15], v[18:19]
	v_pk_fma_f32 v[8:9], v[8:9], v[172:173], v[140:141] op_sel_hi:[1,0,1]
	v_pk_mul_f32 v[6:7], v[6:7], v[14:15]
	v_pk_mul_f32 v[14:15], v[16:17], v[20:21]
	v_mul_f32_e32 v16, 0xbfb8aa3b, v10
	v_mul_f32_e32 v17, 0xbfb8aa3b, v11
	v_exp_f32_e32 v16, v16
	v_exp_f32_e32 v17, v17
	v_pk_fma_f32 v[12:13], v[12:13], v[172:173], v[136:137] op_sel_hi:[1,0,1]
	v_pk_mul_f32 v[8:9], v[8:9], v[14:15]
	v_add_f32_e32 v14, 1.0, v16
	v_add_f32_e32 v15, 1.0, v17
	v_mul_f32_e32 v16, 0xbfb8aa3b, v12
	v_mul_f32_e32 v17, 0xbfb8aa3b, v13
	v_exp_f32_e32 v16, v16
	v_exp_f32_e32 v17, v17
	v_rcp_f32_e32 v14, v14
	v_rcp_f32_e32 v15, v15
	v_add_f32_e32 v16, 1.0, v16
	v_add_f32_e32 v17, 1.0, v17
	v_rcp_f32_e32 v16, v16
	v_rcp_f32_e32 v17, v17
	v_pk_mul_f32 v[10:11], v[10:11], v[14:15]
	v_pk_fma_f32 v[2:3], v[2:3], v[172:173], v[130:131] op_sel_hi:[1,0,1]
	v_pk_fma_f32 v[4:5], v[4:5], v[172:173], v[132:133] op_sel_hi:[1,0,1]
	v_pk_mul_f32 v[10:11], v[2:3], v[10:11]
	v_pk_mul_f32 v[2:3], v[12:13], v[16:17]
	s_nop 0
	v_pk_mul_f32 v[12:13], v[4:5], v[2:3]
	v_mad_i64_i32 v[2:3], s[18:19], v168, s56, v[166:167]
	v_lshl_add_u64 v[2:3], v[2:3], 0, s[16:17]
	v_lshl_add_u64 v[14:15], v[2:3], 0, v[154:155]
	v_cvt_pk_bf16_f32 v2, v6, v7
	v_cvt_pk_bf16_f32 v3, v8, v9
	v_cvt_pk_bf16_f32 v4, v10, v11
	v_cvt_pk_bf16_f32 v5, v12, v13
	s_mov_b32 s17, s8
	s_mov_b32 s16, s10
	global_store_dwordx4 v[14:15], v[2:5], off nt
	s_cmpk_gt_u32 s33, 0xff
	s_cbranch_scc0 .Ldfr_p12_c
	s_barrier

.Ldfr_p13_c:
	s_and_b64 vcc, exec, s[4:5]
	s_mov_b32 s8, s55
	s_mov_b32 s57, s56
	s_mov_b64 s[34:35], s[0:1]
	s_mov_b64 s[24:25], s[6:7]
	s_cbranch_vccnz .LBB0_3500

.LBB0_3482:
	s_add_u32 s24, s24, 0xb0080
	s_addc_u32 s25, s25, 0
	s_add_u32 s60, s34, 0x100
	s_addc_u32 s61, s35, 0
	s_mov_b32 s62, -2
	s_waitcnt lgkmcnt(0)
	s_waitcnt vmcnt(0)
	ds_read_b128 v[130:133], v171
	ds_read_b128 v[134:137], v171 offset:1024
	ds_read_b128 v[138:141], v171 offset:2048
	ds_read_b128 v[142:145], v171 offset:3072
	s_add_u32 s18, s24, 0xfff50080
	s_addc_u32 s19, s25, -1
	s_cmp_eq_u32 s62, 40
	s_cselect_b32 s19, s7, s19
	s_cselect_b32 s18, s6, s18
	s_cselect_b32 s35, s1, s61
	s_cselect_b32 s34, s0, s60
	v_lshl_add_u64 v[202:203], s[24:25], 0, v[168:169]
	s_add_i32 m0, s41, 0xc000
	ds_read_b128 v[146:149], v210
	ds_read_b128 v[150:153], v210 offset:1024
	ds_read_b128 v[178:181], v210 offset:2048
	ds_read_b128 v[182:185], v210 offset:3072
	ds_read_b128 v[186:189], v210 offset:4096
	ds_read_b128 v[190:193], v210 offset:5120
	ds_read_b128 v[194:197], v210 offset:6144
	ds_read_b128 v[198:201], v210 offset:7168
	global_load_lds_dwordx4 v[202:203], off
	v_lshl_add_u64 v[202:203], s[24:25], 0, v[172:173]
	s_add_i32 m0, s41, 0xe000
	s_nop 0
	global_load_lds_dwordx4 v[202:203], off
	s_waitcnt lgkmcnt(8)
	s_setprio 1
	s_barrier
	s_waitcnt lgkmcnt(0)
	v_mfma_f32_16x16x32_bf16 v[126:129], v[130:133], v[146:149], 0
	v_mfma_f32_16x16x32_bf16 v[122:125], v[138:141], v[146:149], 0
	v_mfma_f32_16x16x32_bf16 v[110:113], v[130:133], v[178:181], 0
	v_mfma_f32_16x16x32_bf16 v[106:109], v[138:141], v[178:181], 0
	v_mfma_f32_16x16x32_bf16 v[94:97], v[130:133], v[186:189], 0
	v_mfma_f32_16x16x32_bf16 v[90:93], v[138:141], v[186:189], 0
	v_mfma_f32_16x16x32_bf16 v[78:81], v[130:133], v[194:197], 0
	v_mfma_f32_16x16x32_bf16 v[74:77], v[138:141], v[194:197], 0
	v_mfma_f32_16x16x32_bf16 v[126:129], v[134:137], v[150:153], v[126:129]
	v_mfma_f32_16x16x32_bf16 v[122:125], v[142:145], v[150:153], v[122:125]
	v_mfma_f32_16x16x32_bf16 v[110:113], v[134:137], v[182:185], v[110:113]
	v_mfma_f32_16x16x32_bf16 v[106:109], v[142:145], v[182:185], v[106:109]
	v_mfma_f32_16x16x32_bf16 v[94:97], v[134:137], v[190:193], v[94:97]
	v_mfma_f32_16x16x32_bf16 v[90:93], v[142:145], v[190:193], v[90:93]
	v_mfma_f32_16x16x32_bf16 v[78:81], v[134:137], v[198:201], v[78:81]
	v_mfma_f32_16x16x32_bf16 v[74:77], v[142:145], v[198:201], v[74:77]
	s_barrier
	s_setprio 0
	s_add_i32 s20, s52, s40
	v_lshl_add_u64 v[222:223], s[34:35], 0, v[156:157]
	s_mov_b32 m0, s20
	ds_read_b128 v[202:205], v211
	ds_read_b128 v[206:209], v211 offset:1024
	ds_read_b128 v[214:217], v211 offset:2048
	ds_read_b128 v[218:221], v211 offset:3072
	global_load_lds_dwordx4 v[222:223], off
	v_lshl_add_u64 v[224:225], s[34:35], 0, v[160:161]
	s_add_i32 m0, s20, 0x2000
	s_nop 0
	global_load_lds_dwordx4 v[224:225], off
	s_setprio 1
	s_barrier
	s_waitcnt lgkmcnt(0)
	v_mfma_f32_16x16x32_bf16 v[118:121], v[202:205], v[146:149], 0
	v_mfma_f32_16x16x32_bf16 v[114:117], v[214:217], v[146:149], 0
	v_mfma_f32_16x16x32_bf16 v[102:105], v[202:205], v[178:181], 0
	v_mfma_f32_16x16x32_bf16 v[98:101], v[214:217], v[178:181], 0
	v_mfma_f32_16x16x32_bf16 v[86:89], v[202:205], v[186:189], 0
	v_mfma_f32_16x16x32_bf16 v[82:85], v[214:217], v[186:189], 0
	v_mfma_f32_16x16x32_bf16 v[70:73], v[202:205], v[194:197], 0
	v_mfma_f32_16x16x32_bf16 v[66:69], v[214:217], v[194:197], 0
	v_mfma_f32_16x16x32_bf16 v[118:121], v[206:209], v[150:153], v[118:121]
	v_mfma_f32_16x16x32_bf16 v[114:117], v[218:221], v[150:153], v[114:117]
	v_mfma_f32_16x16x32_bf16 v[102:105], v[206:209], v[182:185], v[102:105]
	v_mfma_f32_16x16x32_bf16 v[98:101], v[218:221], v[182:185], v[98:101]
	v_mfma_f32_16x16x32_bf16 v[86:89], v[206:209], v[190:193], v[86:89]
	v_mfma_f32_16x16x32_bf16 v[82:85], v[218:221], v[190:193], v[82:85]
	v_mfma_f32_16x16x32_bf16 v[70:73], v[206:209], v[198:201], v[70:73]
	v_mfma_f32_16x16x32_bf16 v[66:69], v[218:221], v[198:201], v[66:69]
	s_barrier
	s_setprio 0
	s_mov_b32 m0, s41
	v_lshl_add_u64 v[226:227], s[18:19], 0, v[154:155]
	ds_read_b128 v[146:149], v210 offset:16384
	ds_read_b128 v[150:153], v210 offset:17408
	ds_read_b128 v[178:181], v210 offset:18432
	ds_read_b128 v[182:185], v210 offset:19456
	ds_read_b128 v[186:189], v210 offset:20480
	ds_read_b128 v[190:193], v210 offset:21504
	ds_read_b128 v[194:197], v210 offset:22528
	ds_read_b128 v[198:201], v210 offset:23552
	global_load_lds_dwordx4 v[226:227], off
	v_lshl_add_u64 v[228:229], s[18:19], 0, v[158:159]
	s_mov_b32 m0, s42
	s_nop 0
	global_load_lds_dwordx4 v[228:229], off
	s_setprio 1
	s_barrier
	s_waitcnt lgkmcnt(0)
	v_mfma_f32_16x16x32_bf16 v[62:65], v[130:133], v[146:149], 0
	v_mfma_f32_16x16x32_bf16 v[58:61], v[138:141], v[146:149], 0
	v_mfma_f32_16x16x32_bf16 v[46:49], v[130:133], v[178:181], 0
	v_mfma_f32_16x16x32_bf16 v[42:45], v[138:141], v[178:181], 0
	v_mfma_f32_16x16x32_bf16 v[30:33], v[130:133], v[186:189], 0
	v_mfma_f32_16x16x32_bf16 v[26:29], v[138:141], v[186:189], 0
	v_mfma_f32_16x16x32_bf16 v[14:17], v[130:133], v[194:197], 0
	v_mfma_f32_16x16x32_bf16 v[10:13], v[138:141], v[194:197], 0
	v_mfma_f32_16x16x32_bf16 v[62:65], v[134:137], v[150:153], v[62:65]
	v_mfma_f32_16x16x32_bf16 v[58:61], v[142:145], v[150:153], v[58:61]
	v_mfma_f32_16x16x32_bf16 v[46:49], v[134:137], v[182:185], v[46:49]
	v_mfma_f32_16x16x32_bf16 v[42:45], v[142:145], v[182:185], v[42:45]
	v_mfma_f32_16x16x32_bf16 v[30:33], v[134:137], v[190:193], v[30:33]
	v_mfma_f32_16x16x32_bf16 v[26:29], v[142:145], v[190:193], v[26:29]
	v_mfma_f32_16x16x32_bf16 v[14:17], v[134:137], v[198:201], v[14:17]
	v_mfma_f32_16x16x32_bf16 v[10:13], v[142:145], v[198:201], v[10:13]
	s_barrier
	s_setprio 0
	s_add_u32 s20, s34, 0xb0000
	s_addc_u32 s21, s35, 0
	s_add_i32 s63, s53, s40
	v_lshl_add_u64 v[130:131], s[20:21], 0, v[156:157]
	s_mov_b32 m0, s63
	s_nop 0
	global_load_lds_dwordx4 v[130:131], off
	v_lshl_add_u64 v[130:131], s[20:21], 0, v[160:161]
	s_add_i32 m0, s63, 0x2000
	s_nop 0
	global_load_lds_dwordx4 v[130:131], off
	s_waitcnt vmcnt(6)
	s_setprio 1
	s_barrier
	v_mfma_f32_16x16x32_bf16 v[54:57], v[202:205], v[146:149], 0
	v_mfma_f32_16x16x32_bf16 v[50:53], v[214:217], v[146:149], 0
	v_mfma_f32_16x16x32_bf16 v[38:41], v[202:205], v[178:181], 0
	v_mfma_f32_16x16x32_bf16 v[34:37], v[214:217], v[178:181], 0
	v_mfma_f32_16x16x32_bf16 v[22:25], v[202:205], v[186:189], 0
	v_mfma_f32_16x16x32_bf16 v[18:21], v[214:217], v[186:189], 0
	v_mfma_f32_16x16x32_bf16 v[6:9], v[202:205], v[194:197], 0
	v_mfma_f32_16x16x32_bf16 v[2:5], v[214:217], v[194:197], 0
	v_mfma_f32_16x16x32_bf16 v[54:57], v[206:209], v[150:153], v[54:57]
	v_mfma_f32_16x16x32_bf16 v[50:53], v[218:221], v[150:153], v[50:53]
	v_mfma_f32_16x16x32_bf16 v[38:41], v[206:209], v[182:185], v[38:41]
	v_mfma_f32_16x16x32_bf16 v[34:37], v[218:221], v[182:185], v[34:37]
	v_mfma_f32_16x16x32_bf16 v[22:25], v[206:209], v[190:193], v[22:25]
	v_mfma_f32_16x16x32_bf16 v[18:21], v[218:221], v[190:193], v[18:21]
	v_mfma_f32_16x16x32_bf16 v[6:9], v[206:209], v[198:201], v[6:9]
	v_mfma_f32_16x16x32_bf16 v[2:5], v[218:221], v[198:201], v[2:5]
	s_barrier
	s_setprio 0
	s_add_i32 s20, 0, 0x18000
	v_add_u32_e32 v142, s20, v165
	ds_read_b128 v[130:133], v142
	ds_read_b128 v[134:137], v142 offset:1024
	ds_read_b128 v[138:141], v142 offset:2048
	ds_read_b128 v[142:145], v142 offset:3072
	s_add_u32 s18, s18, 0xb0000
	s_addc_u32 s19, s19, 0
	s_mov_b32 m0, s43
	v_lshl_add_u64 v[202:203], s[18:19], 0, v[154:155]
	ds_read_b128 v[146:149], v210 offset:32768
	ds_read_b128 v[150:153], v210 offset:33792
	ds_read_b128 v[178:181], v210 offset:34816
	ds_read_b128 v[182:185], v210 offset:35840
	ds_read_b128 v[186:189], v210 offset:36864
	ds_read_b128 v[190:193], v210 offset:37888
	ds_read_b128 v[194:197], v210 offset:38912
	ds_read_b128 v[198:201], v210 offset:39936
	global_load_lds_dwordx4 v[202:203], off
	v_lshl_add_u64 v[202:203], s[18:19], 0, v[158:159]
	s_mov_b32 m0, s44
	s_nop 0
	global_load_lds_dwordx4 v[202:203], off
	s_waitcnt lgkmcnt(8)
	s_setprio 1
	s_barrier
	s_waitcnt lgkmcnt(0)
	v_mfma_f32_16x16x32_bf16 v[126:129], v[130:133], v[146:149], v[126:129]
	v_mfma_f32_16x16x32_bf16 v[122:125], v[138:141], v[146:149], v[122:125]
	v_mfma_f32_16x16x32_bf16 v[110:113], v[130:133], v[178:181], v[110:113]
	v_mfma_f32_16x16x32_bf16 v[106:109], v[138:141], v[178:181], v[106:109]
	v_mfma_f32_16x16x32_bf16 v[94:97], v[130:133], v[186:189], v[94:97]
	v_mfma_f32_16x16x32_bf16 v[90:93], v[138:141], v[186:189], v[90:93]
	v_mfma_f32_16x16x32_bf16 v[78:81], v[130:133], v[194:197], v[78:81]
	v_mfma_f32_16x16x32_bf16 v[74:77], v[138:141], v[194:197], v[74:77]
	v_mfma_f32_16x16x32_bf16 v[126:129], v[134:137], v[150:153], v[126:129]
	v_mfma_f32_16x16x32_bf16 v[122:125], v[142:145], v[150:153], v[122:125]
	v_mfma_f32_16x16x32_bf16 v[110:113], v[134:137], v[182:185], v[110:113]
	v_mfma_f32_16x16x32_bf16 v[106:109], v[142:145], v[182:185], v[106:109]
	v_mfma_f32_16x16x32_bf16 v[94:97], v[134:137], v[190:193], v[94:97]
	v_mfma_f32_16x16x32_bf16 v[90:93], v[142:145], v[190:193], v[90:93]
	v_mfma_f32_16x16x32_bf16 v[78:81], v[134:137], v[198:201], v[78:81]
	v_mfma_f32_16x16x32_bf16 v[74:77], v[142:145], v[198:201], v[74:77]
	s_barrier
	s_setprio 0
	s_add_i32 s21, 0, 0x1c000
	s_add_i32 s18, s20, s40
	v_add_u32_e32 v162, s21, v165
	v_lshl_add_u64 v[222:223], v[222:223], 0, s[14:15]
	s_mov_b32 m0, s18
	ds_read_b128 v[202:205], v162
	ds_read_b128 v[206:209], v162 offset:1024
	ds_read_b128 v[214:217], v162 offset:2048
	ds_read_b128 v[218:221], v162 offset:3072
	global_load_lds_dwordx4 v[222:223], off
	v_lshl_add_u64 v[222:223], v[224:225], 0, s[14:15]
	s_add_i32 m0, s18, 0x2000
	s_nop 0
	global_load_lds_dwordx4 v[222:223], off
	s_setprio 1
	s_barrier
	s_waitcnt lgkmcnt(0)
	v_mfma_f32_16x16x32_bf16 v[118:121], v[202:205], v[146:149], v[118:121]
	v_mfma_f32_16x16x32_bf16 v[114:117], v[214:217], v[146:149], v[114:117]
	v_mfma_f32_16x16x32_bf16 v[102:105], v[202:205], v[178:181], v[102:105]
	v_mfma_f32_16x16x32_bf16 v[98:101], v[214:217], v[178:181], v[98:101]
	v_mfma_f32_16x16x32_bf16 v[86:89], v[202:205], v[186:189], v[86:89]
	v_mfma_f32_16x16x32_bf16 v[82:85], v[214:217], v[186:189], v[82:85]
	v_mfma_f32_16x16x32_bf16 v[70:73], v[202:205], v[194:197], v[70:73]
	v_mfma_f32_16x16x32_bf16 v[66:69], v[214:217], v[194:197], v[66:69]
	v_mfma_f32_16x16x32_bf16 v[118:121], v[206:209], v[150:153], v[118:121]
	v_mfma_f32_16x16x32_bf16 v[114:117], v[218:221], v[150:153], v[114:117]
	v_mfma_f32_16x16x32_bf16 v[102:105], v[206:209], v[182:185], v[102:105]
	v_mfma_f32_16x16x32_bf16 v[98:101], v[218:221], v[182:185], v[98:101]
	v_mfma_f32_16x16x32_bf16 v[86:89], v[206:209], v[190:193], v[86:89]
	v_mfma_f32_16x16x32_bf16 v[82:85], v[218:221], v[190:193], v[82:85]
	v_mfma_f32_16x16x32_bf16 v[70:73], v[206:209], v[198:201], v[70:73]
	v_mfma_f32_16x16x32_bf16 v[66:69], v[218:221], v[198:201], v[66:69]
	s_barrier
	s_setprio 0
	s_mov_b32 m0, s48
	v_lshl_add_u64 v[222:223], v[226:227], 0, s[14:15]
	ds_read_b128 v[146:149], v210 offset:49152
	ds_read_b128 v[150:153], v210 offset:50176
	ds_read_b128 v[178:181], v210 offset:51200
	ds_read_b128 v[182:185], v210 offset:52224
	ds_read_b128 v[186:189], v210 offset:53248
	ds_read_b128 v[190:193], v210 offset:54272
	ds_read_b128 v[194:197], v210 offset:55296
	ds_read_b128 v[198:201], v210 offset:56320
	global_load_lds_dwordx4 v[222:223], off
	v_lshl_add_u64 v[222:223], v[228:229], 0, s[14:15]
	s_mov_b32 m0, s49
	s_nop 0
	global_load_lds_dwordx4 v[222:223], off
	s_setprio 1
	s_barrier
	s_waitcnt lgkmcnt(0)
	v_mfma_f32_16x16x32_bf16 v[62:65], v[130:133], v[146:149], v[62:65]
	v_mfma_f32_16x16x32_bf16 v[58:61], v[138:141], v[146:149], v[58:61]
	v_mfma_f32_16x16x32_bf16 v[46:49], v[130:133], v[178:181], v[46:49]
	v_mfma_f32_16x16x32_bf16 v[42:45], v[138:141], v[178:181], v[42:45]
	v_mfma_f32_16x16x32_bf16 v[30:33], v[130:133], v[186:189], v[30:33]
	v_mfma_f32_16x16x32_bf16 v[26:29], v[138:141], v[186:189], v[26:29]
	v_mfma_f32_16x16x32_bf16 v[14:17], v[130:133], v[194:197], v[14:17]
	v_mfma_f32_16x16x32_bf16 v[10:13], v[138:141], v[194:197], v[10:13]
	v_mfma_f32_16x16x32_bf16 v[62:65], v[134:137], v[150:153], v[62:65]
	v_mfma_f32_16x16x32_bf16 v[58:61], v[142:145], v[150:153], v[58:61]
	v_mfma_f32_16x16x32_bf16 v[46:49], v[134:137], v[182:185], v[46:49]
	v_mfma_f32_16x16x32_bf16 v[42:45], v[142:145], v[182:185], v[42:45]
	v_mfma_f32_16x16x32_bf16 v[30:33], v[134:137], v[190:193], v[30:33]
	v_mfma_f32_16x16x32_bf16 v[26:29], v[142:145], v[190:193], v[26:29]
	v_mfma_f32_16x16x32_bf16 v[14:17], v[134:137], v[198:201], v[14:17]
	v_mfma_f32_16x16x32_bf16 v[10:13], v[142:145], v[198:201], v[10:13]
	s_barrier
	s_setprio 0
	s_add_u32 s18, s34, 0xb0080
	s_addc_u32 s19, s35, 0
	s_add_i32 s20, s21, s40
	v_lshl_add_u64 v[130:131], s[18:19], 0, v[156:157]
	s_mov_b32 m0, s20
	s_nop 0
	global_load_lds_dwordx4 v[130:131], off
	v_lshl_add_u64 v[130:131], s[18:19], 0, v[160:161]
	s_add_i32 m0, s20, 0x2000
	s_nop 0
	global_load_lds_dwordx4 v[130:131], off
	s_waitcnt vmcnt(6)
	s_setprio 1
	s_barrier
	v_mfma_f32_16x16x32_bf16 v[54:57], v[202:205], v[146:149], v[54:57]
	v_mfma_f32_16x16x32_bf16 v[50:53], v[214:217], v[146:149], v[50:53]
	v_mfma_f32_16x16x32_bf16 v[38:41], v[202:205], v[178:181], v[38:41]
	v_mfma_f32_16x16x32_bf16 v[34:37], v[214:217], v[178:181], v[34:37]
	v_mfma_f32_16x16x32_bf16 v[22:25], v[202:205], v[186:189], v[22:25]
	v_mfma_f32_16x16x32_bf16 v[18:21], v[214:217], v[186:189], v[18:21]
	v_mfma_f32_16x16x32_bf16 v[6:9], v[202:205], v[194:197], v[6:9]
	v_mfma_f32_16x16x32_bf16 v[2:5], v[214:217], v[194:197], v[2:5]
	v_mfma_f32_16x16x32_bf16 v[54:57], v[206:209], v[150:153], v[54:57]
	v_mfma_f32_16x16x32_bf16 v[50:53], v[218:221], v[150:153], v[50:53]
	v_mfma_f32_16x16x32_bf16 v[38:41], v[206:209], v[182:185], v[38:41]
	v_mfma_f32_16x16x32_bf16 v[34:37], v[218:221], v[182:185], v[34:37]
	v_mfma_f32_16x16x32_bf16 v[22:25], v[206:209], v[190:193], v[22:25]
	v_mfma_f32_16x16x32_bf16 v[18:21], v[218:221], v[190:193], v[18:21]
	v_mfma_f32_16x16x32_bf16 v[6:9], v[206:209], v[198:201], v[6:9]
	v_mfma_f32_16x16x32_bf16 v[2:5], v[218:221], v[198:201], v[2:5]
	s_add_i32 s62, s62, 2
	s_add_u32 s24, s24, 0x100
	s_addc_u32 s25, s25, 0
	s_add_u32 s60, s60, 0x100
	s_addc_u32 s61, s61, 0
	s_cmp_gt_u32 s62, 41

.LBB0_3483:
	ds_read_b128 v[130:133], v171
	ds_read_b128 v[134:137], v171 offset:1024
	ds_read_b128 v[138:141], v171 offset:2048
	ds_read_b128 v[142:145], v171 offset:3072
	s_add_u32 s18, s24, 0xfff50080
	s_addc_u32 s19, s25, -1
	s_cmp_eq_u32 s62, 40
	s_cselect_b32 s19, s7, s19
	s_cselect_b32 s18, s6, s18
	s_cselect_b32 s35, s1, s61
	s_cselect_b32 s34, s0, s60
	v_lshl_add_u64 v[202:203], s[24:25], 0, v[168:169]
	s_add_i32 m0, s41, 0xc000
	ds_read_b128 v[146:149], v210
	ds_read_b128 v[150:153], v210 offset:1024
	ds_read_b128 v[178:181], v210 offset:2048
	ds_read_b128 v[182:185], v210 offset:3072
	ds_read_b128 v[186:189], v210 offset:4096
	ds_read_b128 v[190:193], v210 offset:5120
	ds_read_b128 v[194:197], v210 offset:6144
	ds_read_b128 v[198:201], v210 offset:7168
	global_load_lds_dwordx4 v[202:203], off
	v_lshl_add_u64 v[202:203], s[24:25], 0, v[172:173]
	s_add_i32 m0, s41, 0xe000
	s_nop 0
	global_load_lds_dwordx4 v[202:203], off
	s_waitcnt lgkmcnt(8)
	s_setprio 1
	s_barrier
	s_waitcnt lgkmcnt(0)
	v_mfma_f32_16x16x32_bf16 v[126:129], v[130:133], v[146:149], v[126:129]
	v_mfma_f32_16x16x32_bf16 v[122:125], v[138:141], v[146:149], v[122:125]
	v_mfma_f32_16x16x32_bf16 v[110:113], v[130:133], v[178:181], v[110:113]
	v_mfma_f32_16x16x32_bf16 v[106:109], v[138:141], v[178:181], v[106:109]
	v_mfma_f32_16x16x32_bf16 v[94:97], v[130:133], v[186:189], v[94:97]
	v_mfma_f32_16x16x32_bf16 v[90:93], v[138:141], v[186:189], v[90:93]
	v_mfma_f32_16x16x32_bf16 v[78:81], v[130:133], v[194:197], v[78:81]
	v_mfma_f32_16x16x32_bf16 v[74:77], v[138:141], v[194:197], v[74:77]
	v_mfma_f32_16x16x32_bf16 v[126:129], v[134:137], v[150:153], v[126:129]
	v_mfma_f32_16x16x32_bf16 v[122:125], v[142:145], v[150:153], v[122:125]
	v_mfma_f32_16x16x32_bf16 v[110:113], v[134:137], v[182:185], v[110:113]
	v_mfma_f32_16x16x32_bf16 v[106:109], v[142:145], v[182:185], v[106:109]
	v_mfma_f32_16x16x32_bf16 v[94:97], v[134:137], v[190:193], v[94:97]
	v_mfma_f32_16x16x32_bf16 v[90:93], v[142:145], v[190:193], v[90:93]
	v_mfma_f32_16x16x32_bf16 v[78:81], v[134:137], v[198:201], v[78:81]
	v_mfma_f32_16x16x32_bf16 v[74:77], v[142:145], v[198:201], v[74:77]
	s_barrier
	s_setprio 0
	s_add_i32 s20, s52, s40
	v_lshl_add_u64 v[222:223], s[34:35], 0, v[156:157]
	s_mov_b32 m0, s20
	ds_read_b128 v[202:205], v211
	ds_read_b128 v[206:209], v211 offset:1024
	ds_read_b128 v[214:217], v211 offset:2048
	ds_read_b128 v[218:221], v211 offset:3072
	global_load_lds_dwordx4 v[222:223], off
	v_lshl_add_u64 v[224:225], s[34:35], 0, v[160:161]
	s_add_i32 m0, s20, 0x2000
	s_nop 0
	global_load_lds_dwordx4 v[224:225], off
	s_setprio 1
	s_barrier
	s_waitcnt lgkmcnt(0)
	v_mfma_f32_16x16x32_bf16 v[118:121], v[202:205], v[146:149], v[118:121]
	v_mfma_f32_16x16x32_bf16 v[114:117], v[214:217], v[146:149], v[114:117]
	v_mfma_f32_16x16x32_bf16 v[102:105], v[202:205], v[178:181], v[102:105]
	v_mfma_f32_16x16x32_bf16 v[98:101], v[214:217], v[178:181], v[98:101]
	v_mfma_f32_16x16x32_bf16 v[86:89], v[202:205], v[186:189], v[86:89]
	v_mfma_f32_16x16x32_bf16 v[82:85], v[214:217], v[186:189], v[82:85]
	v_mfma_f32_16x16x32_bf16 v[70:73], v[202:205], v[194:197], v[70:73]
	v_mfma_f32_16x16x32_bf16 v[66:69], v[214:217], v[194:197], v[66:69]
	v_mfma_f32_16x16x32_bf16 v[118:121], v[206:209], v[150:153], v[118:121]
	v_mfma_f32_16x16x32_bf16 v[114:117], v[218:221], v[150:153], v[114:117]
	v_mfma_f32_16x16x32_bf16 v[102:105], v[206:209], v[182:185], v[102:105]
	v_mfma_f32_16x16x32_bf16 v[98:101], v[218:221], v[182:185], v[98:101]
	v_mfma_f32_16x16x32_bf16 v[86:89], v[206:209], v[190:193], v[86:89]
	v_mfma_f32_16x16x32_bf16 v[82:85], v[218:221], v[190:193], v[82:85]
	v_mfma_f32_16x16x32_bf16 v[70:73], v[206:209], v[198:201], v[70:73]
	v_mfma_f32_16x16x32_bf16 v[66:69], v[218:221], v[198:201], v[66:69]
	s_barrier
	s_setprio 0
	s_mov_b32 m0, s41
	v_lshl_add_u64 v[226:227], s[18:19], 0, v[154:155]
	ds_read_b128 v[146:149], v210 offset:16384
	ds_read_b128 v[150:153], v210 offset:17408
	ds_read_b128 v[178:181], v210 offset:18432
	ds_read_b128 v[182:185], v210 offset:19456
	ds_read_b128 v[186:189], v210 offset:20480
	ds_read_b128 v[190:193], v210 offset:21504
	ds_read_b128 v[194:197], v210 offset:22528
	ds_read_b128 v[198:201], v210 offset:23552
	global_load_lds_dwordx4 v[226:227], off
	v_lshl_add_u64 v[228:229], s[18:19], 0, v[158:159]
	s_mov_b32 m0, s42
	s_nop 0
	global_load_lds_dwordx4 v[228:229], off
	s_setprio 1
	s_barrier
	s_waitcnt lgkmcnt(0)
	v_mfma_f32_16x16x32_bf16 v[62:65], v[130:133], v[146:149], v[62:65]
	v_mfma_f32_16x16x32_bf16 v[58:61], v[138:141], v[146:149], v[58:61]
	v_mfma_f32_16x16x32_bf16 v[46:49], v[130:133], v[178:181], v[46:49]
	v_mfma_f32_16x16x32_bf16 v[42:45], v[138:141], v[178:181], v[42:45]
	v_mfma_f32_16x16x32_bf16 v[30:33], v[130:133], v[186:189], v[30:33]
	v_mfma_f32_16x16x32_bf16 v[26:29], v[138:141], v[186:189], v[26:29]
	v_mfma_f32_16x16x32_bf16 v[14:17], v[130:133], v[194:197], v[14:17]
	v_mfma_f32_16x16x32_bf16 v[10:13], v[138:141], v[194:197], v[10:13]
	v_mfma_f32_16x16x32_bf16 v[62:65], v[134:137], v[150:153], v[62:65]
	v_mfma_f32_16x16x32_bf16 v[58:61], v[142:145], v[150:153], v[58:61]
	v_mfma_f32_16x16x32_bf16 v[46:49], v[134:137], v[182:185], v[46:49]
	v_mfma_f32_16x16x32_bf16 v[42:45], v[142:145], v[182:185], v[42:45]
	v_mfma_f32_16x16x32_bf16 v[30:33], v[134:137], v[190:193], v[30:33]
	v_mfma_f32_16x16x32_bf16 v[26:29], v[142:145], v[190:193], v[26:29]
	v_mfma_f32_16x16x32_bf16 v[14:17], v[134:137], v[198:201], v[14:17]
	v_mfma_f32_16x16x32_bf16 v[10:13], v[142:145], v[198:201], v[10:13]
	s_barrier
	s_setprio 0
	s_add_u32 s20, s34, 0xb0000
	s_addc_u32 s21, s35, 0
	s_add_i32 s63, s53, s40
	v_lshl_add_u64 v[130:131], s[20:21], 0, v[156:157]
	s_mov_b32 m0, s63
	s_nop 0
	global_load_lds_dwordx4 v[130:131], off
	v_lshl_add_u64 v[130:131], s[20:21], 0, v[160:161]
	s_add_i32 m0, s63, 0x2000
	s_nop 0
	global_load_lds_dwordx4 v[130:131], off
	s_waitcnt vmcnt(6)
	s_setprio 1
	s_barrier
	v_mfma_f32_16x16x32_bf16 v[54:57], v[202:205], v[146:149], v[54:57]
	v_mfma_f32_16x16x32_bf16 v[50:53], v[214:217], v[146:149], v[50:53]
	v_mfma_f32_16x16x32_bf16 v[38:41], v[202:205], v[178:181], v[38:41]
	v_mfma_f32_16x16x32_bf16 v[34:37], v[214:217], v[178:181], v[34:37]
	v_mfma_f32_16x16x32_bf16 v[22:25], v[202:205], v[186:189], v[22:25]
	v_mfma_f32_16x16x32_bf16 v[18:21], v[214:217], v[186:189], v[18:21]
	v_mfma_f32_16x16x32_bf16 v[6:9], v[202:205], v[194:197], v[6:9]
	v_mfma_f32_16x16x32_bf16 v[2:5], v[214:217], v[194:197], v[2:5]
	v_mfma_f32_16x16x32_bf16 v[54:57], v[206:209], v[150:153], v[54:57]
	v_mfma_f32_16x16x32_bf16 v[50:53], v[218:221], v[150:153], v[50:53]
	v_mfma_f32_16x16x32_bf16 v[38:41], v[206:209], v[182:185], v[38:41]
	v_mfma_f32_16x16x32_bf16 v[34:37], v[218:221], v[182:185], v[34:37]
	v_mfma_f32_16x16x32_bf16 v[22:25], v[206:209], v[190:193], v[22:25]
	v_mfma_f32_16x16x32_bf16 v[18:21], v[218:221], v[190:193], v[18:21]
	v_mfma_f32_16x16x32_bf16 v[6:9], v[206:209], v[198:201], v[6:9]
	v_mfma_f32_16x16x32_bf16 v[2:5], v[218:221], v[198:201], v[2:5]
	s_barrier
	s_setprio 0
	s_add_i32 s20, 0, 0x18000
	v_add_u32_e32 v142, s20, v165
	ds_read_b128 v[130:133], v142
	ds_read_b128 v[134:137], v142 offset:1024
	ds_read_b128 v[138:141], v142 offset:2048
	ds_read_b128 v[142:145], v142 offset:3072
	s_add_u32 s18, s18, 0xb0000
	s_addc_u32 s19, s19, 0
	s_mov_b32 m0, s43
	v_lshl_add_u64 v[202:203], s[18:19], 0, v[154:155]
	ds_read_b128 v[146:149], v210 offset:32768
	ds_read_b128 v[150:153], v210 offset:33792
	ds_read_b128 v[178:181], v210 offset:34816
	ds_read_b128 v[182:185], v210 offset:35840
	ds_read_b128 v[186:189], v210 offset:36864
	ds_read_b128 v[190:193], v210 offset:37888
	ds_read_b128 v[194:197], v210 offset:38912
	ds_read_b128 v[198:201], v210 offset:39936
	global_load_lds_dwordx4 v[202:203], off
	v_lshl_add_u64 v[202:203], s[18:19], 0, v[158:159]
	s_mov_b32 m0, s44
	s_nop 0
	global_load_lds_dwordx4 v[202:203], off
	s_waitcnt lgkmcnt(8)
	s_setprio 1
	s_barrier
	s_waitcnt lgkmcnt(0)
	v_mfma_f32_16x16x32_bf16 v[126:129], v[130:133], v[146:149], v[126:129]
	v_mfma_f32_16x16x32_bf16 v[122:125], v[138:141], v[146:149], v[122:125]
	v_mfma_f32_16x16x32_bf16 v[110:113], v[130:133], v[178:181], v[110:113]
	v_mfma_f32_16x16x32_bf16 v[106:109], v[138:141], v[178:181], v[106:109]
	v_mfma_f32_16x16x32_bf16 v[94:97], v[130:133], v[186:189], v[94:97]
	v_mfma_f32_16x16x32_bf16 v[90:93], v[138:141], v[186:189], v[90:93]
	v_mfma_f32_16x16x32_bf16 v[78:81], v[130:133], v[194:197], v[78:81]
	v_mfma_f32_16x16x32_bf16 v[74:77], v[138:141], v[194:197], v[74:77]
	v_mfma_f32_16x16x32_bf16 v[126:129], v[134:137], v[150:153], v[126:129]
	v_mfma_f32_16x16x32_bf16 v[122:125], v[142:145], v[150:153], v[122:125]
	v_mfma_f32_16x16x32_bf16 v[110:113], v[134:137], v[182:185], v[110:113]
	v_mfma_f32_16x16x32_bf16 v[106:109], v[142:145], v[182:185], v[106:109]
	v_mfma_f32_16x16x32_bf16 v[94:97], v[134:137], v[190:193], v[94:97]
	v_mfma_f32_16x16x32_bf16 v[90:93], v[142:145], v[190:193], v[90:93]
	v_mfma_f32_16x16x32_bf16 v[78:81], v[134:137], v[198:201], v[78:81]
	v_mfma_f32_16x16x32_bf16 v[74:77], v[142:145], v[198:201], v[74:77]
	s_barrier
	s_setprio 0
	s_add_i32 s21, 0, 0x1c000
	s_add_i32 s18, s20, s40
	v_add_u32_e32 v162, s21, v165
	v_lshl_add_u64 v[222:223], v[222:223], 0, s[14:15]
	s_mov_b32 m0, s18
	ds_read_b128 v[202:205], v162
	ds_read_b128 v[206:209], v162 offset:1024
	ds_read_b128 v[214:217], v162 offset:2048
	ds_read_b128 v[218:221], v162 offset:3072
	global_load_lds_dwordx4 v[222:223], off
	v_lshl_add_u64 v[222:223], v[224:225], 0, s[14:15]
	s_add_i32 m0, s18, 0x2000
	s_nop 0
	global_load_lds_dwordx4 v[222:223], off
	s_setprio 1
	s_barrier
	s_waitcnt lgkmcnt(0)
	v_mfma_f32_16x16x32_bf16 v[118:121], v[202:205], v[146:149], v[118:121]
	v_mfma_f32_16x16x32_bf16 v[114:117], v[214:217], v[146:149], v[114:117]
	v_mfma_f32_16x16x32_bf16 v[102:105], v[202:205], v[178:181], v[102:105]
	v_mfma_f32_16x16x32_bf16 v[98:101], v[214:217], v[178:181], v[98:101]
	v_mfma_f32_16x16x32_bf16 v[86:89], v[202:205], v[186:189], v[86:89]
	v_mfma_f32_16x16x32_bf16 v[82:85], v[214:217], v[186:189], v[82:85]
	v_mfma_f32_16x16x32_bf16 v[70:73], v[202:205], v[194:197], v[70:73]
	v_mfma_f32_16x16x32_bf16 v[66:69], v[214:217], v[194:197], v[66:69]
	v_mfma_f32_16x16x32_bf16 v[118:121], v[206:209], v[150:153], v[118:121]
	v_mfma_f32_16x16x32_bf16 v[114:117], v[218:221], v[150:153], v[114:117]
	v_mfma_f32_16x16x32_bf16 v[102:105], v[206:209], v[182:185], v[102:105]
	v_mfma_f32_16x16x32_bf16 v[98:101], v[218:221], v[182:185], v[98:101]
	v_mfma_f32_16x16x32_bf16 v[86:89], v[206:209], v[190:193], v[86:89]
	v_mfma_f32_16x16x32_bf16 v[82:85], v[218:221], v[190:193], v[82:85]
	v_mfma_f32_16x16x32_bf16 v[70:73], v[206:209], v[198:201], v[70:73]
	v_mfma_f32_16x16x32_bf16 v[66:69], v[218:221], v[198:201], v[66:69]
	s_barrier
	s_setprio 0
	s_mov_b32 m0, s48
	v_lshl_add_u64 v[222:223], v[226:227], 0, s[14:15]
	ds_read_b128 v[146:149], v210 offset:49152
	ds_read_b128 v[150:153], v210 offset:50176
	ds_read_b128 v[178:181], v210 offset:51200
	ds_read_b128 v[182:185], v210 offset:52224
	ds_read_b128 v[186:189], v210 offset:53248
	ds_read_b128 v[190:193], v210 offset:54272
	ds_read_b128 v[194:197], v210 offset:55296
	ds_read_b128 v[198:201], v210 offset:56320
	global_load_lds_dwordx4 v[222:223], off
	v_lshl_add_u64 v[222:223], v[228:229], 0, s[14:15]
	s_mov_b32 m0, s49
	s_nop 0
	global_load_lds_dwordx4 v[222:223], off
	s_setprio 1
	s_barrier
	s_waitcnt lgkmcnt(0)
	v_mfma_f32_16x16x32_bf16 v[62:65], v[130:133], v[146:149], v[62:65]
	v_mfma_f32_16x16x32_bf16 v[58:61], v[138:141], v[146:149], v[58:61]
	v_mfma_f32_16x16x32_bf16 v[46:49], v[130:133], v[178:181], v[46:49]
	v_mfma_f32_16x16x32_bf16 v[42:45], v[138:141], v[178:181], v[42:45]
	v_mfma_f32_16x16x32_bf16 v[30:33], v[130:133], v[186:189], v[30:33]
	v_mfma_f32_16x16x32_bf16 v[26:29], v[138:141], v[186:189], v[26:29]
	v_mfma_f32_16x16x32_bf16 v[14:17], v[130:133], v[194:197], v[14:17]
	v_mfma_f32_16x16x32_bf16 v[10:13], v[138:141], v[194:197], v[10:13]
	v_mfma_f32_16x16x32_bf16 v[62:65], v[134:137], v[150:153], v[62:65]
	v_mfma_f32_16x16x32_bf16 v[58:61], v[142:145], v[150:153], v[58:61]
	v_mfma_f32_16x16x32_bf16 v[46:49], v[134:137], v[182:185], v[46:49]
	v_mfma_f32_16x16x32_bf16 v[42:45], v[142:145], v[182:185], v[42:45]
	v_mfma_f32_16x16x32_bf16 v[30:33], v[134:137], v[190:193], v[30:33]
	v_mfma_f32_16x16x32_bf16 v[26:29], v[142:145], v[190:193], v[26:29]
	v_mfma_f32_16x16x32_bf16 v[14:17], v[134:137], v[198:201], v[14:17]
	v_mfma_f32_16x16x32_bf16 v[10:13], v[142:145], v[198:201], v[10:13]
	s_barrier
	s_setprio 0
	s_add_u32 s18, s34, 0xb0080
	s_addc_u32 s19, s35, 0
	s_add_i32 s20, s21, s40
	v_lshl_add_u64 v[130:131], s[18:19], 0, v[156:157]
	s_mov_b32 m0, s20
	s_nop 0
	global_load_lds_dwordx4 v[130:131], off
	v_lshl_add_u64 v[130:131], s[18:19], 0, v[160:161]
	s_add_i32 m0, s20, 0x2000
	s_nop 0
	global_load_lds_dwordx4 v[130:131], off
	s_waitcnt vmcnt(6)
	s_setprio 1
	s_barrier
	v_mfma_f32_16x16x32_bf16 v[54:57], v[202:205], v[146:149], v[54:57]
	v_mfma_f32_16x16x32_bf16 v[50:53], v[214:217], v[146:149], v[50:53]
	v_mfma_f32_16x16x32_bf16 v[38:41], v[202:205], v[178:181], v[38:41]
	v_mfma_f32_16x16x32_bf16 v[34:37], v[214:217], v[178:181], v[34:37]
	v_mfma_f32_16x16x32_bf16 v[22:25], v[202:205], v[186:189], v[22:25]
	v_mfma_f32_16x16x32_bf16 v[18:21], v[214:217], v[186:189], v[18:21]
	v_mfma_f32_16x16x32_bf16 v[6:9], v[202:205], v[194:197], v[6:9]
	v_mfma_f32_16x16x32_bf16 v[2:5], v[214:217], v[194:197], v[2:5]
	v_mfma_f32_16x16x32_bf16 v[54:57], v[206:209], v[150:153], v[54:57]
	v_mfma_f32_16x16x32_bf16 v[50:53], v[218:221], v[150:153], v[50:53]
	v_mfma_f32_16x16x32_bf16 v[38:41], v[206:209], v[182:185], v[38:41]
	v_mfma_f32_16x16x32_bf16 v[34:37], v[218:221], v[182:185], v[34:37]
	v_mfma_f32_16x16x32_bf16 v[22:25], v[206:209], v[190:193], v[22:25]
	v_mfma_f32_16x16x32_bf16 v[18:21], v[218:221], v[190:193], v[18:21]
	v_mfma_f32_16x16x32_bf16 v[6:9], v[206:209], v[198:201], v[6:9]
	v_mfma_f32_16x16x32_bf16 v[2:5], v[218:221], v[198:201], v[2:5]
	s_add_i32 s62, s62, 2
	s_add_u32 s24, s24, 0x100
	s_addc_u32 s25, s25, 0
	s_add_u32 s60, s60, 0x100
	s_addc_u32 s61, s61, 0
	s_cmp_gt_u32 s62, 41
	s_cbranch_scc0 .Ldfr_p13_r
	s_cmpk_gt_u32 s33, 0xff
	s_cbranch_scc1 .Ldfr_p13_b
	s_barrier
.Ldfr_p13_b:
	s_setprio 0
	s_ashr_i32 s18, s57, 3
	s_mul_hi_i32 s19, s18, 0x9000
	s_mul_i32 s18, s18, 0x9000
	s_add_u32 s20, s58, s18
	s_addc_u32 s21, s59, s19
	s_lshl_b32 s34, s8, 8
	v_lshl_add_u32 v206, s57, 8, v1
	s_ashr_i32 s35, s34, 31
	v_ashrrev_i32_e32 v207, 31, v206
	s_lshl_b64 s[18:19], s[34:35], 2
	v_lshl_add_u64 v[130:131], s[34:35], 1, v[166:167]
	v_lshlrev_b64 v[178:179], 11, v[206:207]
	s_add_u32 s18, s20, s18
	v_lshl_add_u64 v[132:133], v[130:131], 0, v[178:179]
	s_addc_u32 s19, s21, s19
	v_lshlrev_b32_e32 v162, 2, v164
	global_load_dwordx4 v[180:183], v[132:133], off
	global_load_dwordx4 v[184:187], v[132:133], off offset:256
	v_lshl_add_u64 v[132:133], s[18:19], 0, v[162:163]
	v_lshl_add_u64 v[134:135], v[132:133], 0, s[16:17]
	v_add_co_u32_e32 v132, vcc, s51, v132
	v_or_b32_e32 v204, 16, v206
	s_nop 0
	v_addc_co_u32_e32 v133, vcc, 0, v133, vcc
	global_load_dwordx4 v[188:191], v[132:133], off
	global_load_dwordx4 v[214:217], v[134:135], off offset:512
	global_load_dwordx4 v[218:221], v[134:135], off offset:16
	global_load_dwordx4 v[222:225], v[134:135], off offset:528
	v_or_b32_e32 v200, 32, v206
	v_or_b32_e32 v196, 48, v206
	v_ashrrev_i32_e32 v205, 31, v204
	v_ashrrev_i32_e32 v201, 31, v200
	v_ashrrev_i32_e32 v197, 31, v196
	v_lshlrev_b64 v[208:209], 11, v[204:205]
	v_lshlrev_b64 v[202:203], 11, v[200:201]
	v_lshlrev_b64 v[198:199], 11, v[196:197]
	v_lshl_add_u64 v[132:133], v[130:131], 0, v[208:209]
	v_lshl_add_u64 v[134:135], v[130:131], 0, v[202:203]
	v_lshl_add_u64 v[130:131], v[130:131], 0, v[198:199]
	global_load_dwordx4 v[150:153], v[132:133], off
	global_load_dwordx4 v[146:149], v[132:133], off offset:256
	global_load_dwordx4 v[142:145], v[134:135], off
	global_load_dwordx4 v[138:141], v[134:135], off offset:256
	s_nop 0
	global_load_dwordx4 v[134:137], v[130:131], off
	s_nop 0
	global_load_dwordx4 v[130:133], v[130:131], off offset:256
	v_lshl_add_u64 v[192:193], s[10:11], 0, v[178:179]
	v_or_b32_e32 v178, s34, v164
	v_mov_b32_e32 v179, s35
	v_lshl_add_u64 v[226:227], v[178:179], 1, v[192:193]
	s_lshl_b32 s24, s8, 2
	s_ashr_i32 s25, s24, 31
	s_waitcnt vmcnt(0)
	v_lshlrev_b32_e32 v228, 16, v180
	v_lshlrev_b32_e32 v232, 16, v184
	v_and_b32_e32 v233, 0xffff0000, v184
	v_and_b32_e32 v229, 0xffff0000, v180
	v_lshlrev_b32_e32 v234, 16, v181
	v_and_b32_e32 v235, 0xffff0000, v181
	v_lshlrev_b32_e32 v236, 16, v185
	v_pk_mul_f32 v[192:193], v[214:215], 0.5 op_sel_hi:[1,0]
	v_and_b32_e32 v237, 0xffff0000, v185
	v_lshlrev_b32_e32 v244, 16, v187
	v_and_b32_e32 v245, 0xffff0000, v187
	v_pk_mul_f32 v[194:195], v[188:189], 0.5 op_sel_hi:[1,0]
	v_pk_mul_f32 v[188:189], v[216:217], 0.5 op_sel_hi:[1,0]
	v_pk_mul_f32 v[180:181], v[224:225], 0.5 op_sel_hi:[1,0]
	v_pk_fma_f32 v[118:119], v[118:119], v[192:193], v[232:233]
	v_pk_mul_f32 v[190:191], v[190:191], 0.5 op_sel_hi:[1,0]
	v_pk_fma_f32 v[126:127], v[126:127], v[194:195], v[228:229]
	v_pk_fma_f32 v[120:121], v[120:121], v[188:189], v[236:237]
	v_pk_fma_f32 v[216:217], v[116:117], v[180:181], v[244:245]
	v_pk_mul_f32 v[116:117], v[118:119], v[118:119]
	v_lshlrev_b32_e32 v240, 16, v186
	v_and_b32_e32 v241, 0xffff0000, v186
	v_pk_mul_f32 v[186:187], v[218:219], 0.5 op_sel_hi:[1,0]
	v_pk_mul_f32 v[184:185], v[222:223], 0.5 op_sel_hi:[1,0]
	v_pk_fma_f32 v[128:129], v[128:129], v[190:191], v[234:235]
	v_pk_mul_f32 v[218:219], v[120:121], v[120:121]
	v_pk_fma_f32 v[116:117], v[126:127], v[126:127], v[116:117]
	v_lshlrev_b32_e32 v238, 16, v182
	v_and_b32_e32 v239, 0xffff0000, v182
	v_pk_fma_f32 v[214:215], v[114:115], v[184:185], v[240:241]
	v_cvt_pk_bf16_f32 v114, v126, v127
	v_pk_fma_f32 v[126:127], v[128:129], v[128:129], v[218:219]
	v_add_f32_e32 v116, v116, v117
	v_lshlrev_b32_e32 v242, 16, v183
	v_and_b32_e32 v243, 0xffff0000, v183
	v_pk_mul_f32 v[182:183], v[220:221], 0.5 op_sel_hi:[1,0]
	v_pk_fma_f32 v[122:123], v[122:123], v[186:187], v[238:239]
	v_pk_mul_f32 v[220:221], v[214:215], v[214:215]
	v_add_f32_e32 v116, v126, v116
	v_cvt_pk_bf16_f32 v115, v128, v129
	v_pk_fma_f32 v[128:129], v[122:123], v[122:123], v[220:221]
	v_add_f32_e32 v116, v127, v116
	v_pk_fma_f32 v[124:125], v[124:125], v[182:183], v[242:243]
	v_pk_mul_f32 v[222:223], v[216:217], v[216:217]
	v_add_f32_e32 v116, v128, v116
	v_pk_fma_f32 v[218:219], v[124:125], v[124:125], v[222:223]
	v_add_f32_e32 v116, v129, v116
	v_add_f32_e32 v116, v218, v116
	v_and_b32_e32 v117, 64, v212
	v_add_f32_e32 v127, v219, v116
	v_xor_b32_e32 v116, 16, v212
	v_add_u32_e32 v128, 64, v117
	v_cmp_lt_i32_e32 vcc, v116, v128
	v_cvt_pk_bf16_f32 v117, v124, v125
	s_nop 0
	v_cndmask_b32_e32 v116, v212, v116, vcc
	v_lshlrev_b32_e32 v126, 2, v116
	ds_bpermute_b32 v129, v126, v127
	v_cvt_pk_bf16_f32 v116, v122, v123
	global_store_dwordx4 v[226:227], v[114:117], off nt
	s_nop 1
	v_xor_b32_e32 v115, 32, v212
	v_cmp_lt_i32_e32 vcc, v115, v128
	s_waitcnt lgkmcnt(0)
	v_add_f32_e32 v114, v127, v129
	v_cvt_pk_bf16_f32 v116, v118, v119
	v_cndmask_b32_e32 v115, v212, v115, vcc
	v_lshlrev_b32_e32 v127, 2, v115
	ds_bpermute_b32 v115, v127, v114
	v_cvt_pk_bf16_f32 v117, v120, v121
	v_cvt_pk_bf16_f32 v118, v214, v215
	v_cvt_pk_bf16_f32 v119, v216, v217
	global_store_dwordx4 v[226:227], v[116:119], off offset:256 nt
	s_and_saveexec_b64 s[18:19], s[2:3]
	s_cbranch_execz .LBB0_3486
	s_waitcnt lgkmcnt(0)
	v_add_f32_e32 v116, v114, v115
	v_lshlrev_b64 v[114:115], 6, v[206:207]
	v_lshl_add_u64 v[114:115], s[12:13], 0, v[114:115]
	v_lshl_add_u64 v[114:115], s[24:25], 2, v[114:115]
	s_lshl_b32 s8, s47, 2
	v_lshl_add_u64 v[114:115], v[114:115], 0, s[8:9]
	global_store_dword v[114:115], v116, off
